# peel + ALIGN barrier of the leading half moved ~80-125 instructions into the epilogue (all 9 GEMM phases)
# speedup vs baseline: 1.0021x; 1.0021x over previous
; #define PG8_STAGE(bufoff, gbase, voff) do { _Pragma("unroll") for (int _i = 0; _i < 2; ++_i) \
;         __builtin_amdgcn_global_load_lds((const unsigned*)((const char*)(gbase) + (voff)[_i]), (PG8_LAS unsigned*)(lds + (bufoff) + ldsw + _i * 8192), 16, 0, PG8_LOAD_AUX); } while (0)
; #define PG8_LDA(dst, b, h) do { _Pragma("unroll") for (int m = 0; m < 4; ++m) _Pragma("unroll") for (int k = 0; k < 2; ++k) dst[m][k] = *(const PG8_LAS bf16x8*)(lds + PG8_SA(b, h) + aoff + m * 2048 + k * 1024); } while (0)
; #define PG8_LDB(dst, b, h) do { _Pragma("unroll") for (int n = 0; n < 2; ++n) _Pragma("unroll") for (int k = 0; k < 2; ++k) dst[n][k] = *(const PG8_LAS bf16x8*)(lds + PG8_SB(b, h) + boff + n * 2048 + k * 1024); } while (0)
; #define PG8_MMA(ai, bj, At, Bt) do { __builtin_amdgcn_s_setprio(1); _Pragma("unroll") for (int m = 0; m < 4; ++m) _Pragma("unroll") for (int n = 0; n < 2; ++n) _Pragma("unroll") for (int k = 0; k < 2; ++k) \
;         acc[ai][bj][m][n] = __builtin_amdgcn_mfma_f32_16x16x32_bf16(Bt[n][k], At[m][k], acc[ai][bj][m][n], 0, 0, 0); __builtin_amdgcn_s_setprio(0); } while (0)
; #define PG8_WAIT_V(n) asm volatile("s_waitcnt vmcnt(" #n ")" ::: "memory")
; #define PG8_WAIT_L(n) asm volatile("s_waitcnt lgkmcnt(" #n ")" ::: "memory")
; #define PG8_BAR __builtin_amdgcn_s_barrier()
; #define PG8_SCHED __builtin_amdgcn_sched_barrier(0)
; template <class Epi, class Sched, bool ALIGN_EPI = false, bool SP2 = false>
; __device__ __forceinline__ void gemm_phase(PG8_LAS unsigned char* lds, const Gemm g, const Sched& S, const Epi& E) {
;     ...
;             PG8_LDB(B0, 1, 0); PG8_LDB(B1, 1, 1); PG8_SCHED; PG8_LDA(At, 1, 0); PG8_STAGE(PG8_SA(0, 1), a2 + hstepA, voffA);
;             PG8_WAIT_V(8); PG8_WAIT_L(0); PG8_BAR; PG8_MMA(0, 0, At, B0); PG8_MMA(0, 1, At, B1); PG8_BAR; PG8_SCHED;
;             PG8_LDA(At, 1, 1); PG8_STAGE(PG8_SB(1, 0), b3, voffB); PG8_STAGE(PG8_SB(1, 1), b3 + hstepB, voffB); PG8_STAGE(PG8_SA(1, 0), a3, voffA);
;             PG8_WAIT_V(8); PG8_WAIT_L(0); PG8_BAR; PG8_MMA(1, 0, At, B0); PG8_MMA(1, 1, At, B1); PG8_BAR; PG8_SCHED;
.Lkmid_P1:
	s_add_i32 s29, 0, 0x18000
	v_add_u32_e32 v161, s29, v146
	s_add_i32 s38, 0, 0x1c000
	ds_read_b128 v[162:165], v161
	ds_read_b128 v[166:169], v161 offset:1024
	ds_read_b128 v[170:173], v161 offset:2048
	ds_read_b128 v[174:177], v161 offset:3072
	v_add_u32_e32 v161, s38, v146
	ds_read_b128 v[178:181], v161
	ds_read_b128 v[182:185], v161 offset:1024
	ds_read_b128 v[186:189], v161 offset:2048
	ds_read_b128 v[190:193], v161 offset:3072
	s_add_u32 s30, s34, 0x40000
	s_addc_u32 s31, s35, 0
	s_mov_b32 m0, s44
	v_lshl_add_u64 v[234:235], s[30:31], 0, v[128:129]
	ds_read_b128 v[194:197], v160 offset:32768
	ds_read_b128 v[198:201], v160 offset:33792
	ds_read_b128 v[202:205], v160 offset:34816
	ds_read_b128 v[206:209], v160 offset:35840
	ds_read_b128 v[210:213], v160 offset:36864
	ds_read_b128 v[214:217], v160 offset:37888
	ds_read_b128 v[218:221], v160 offset:38912
	ds_read_b128 v[222:225], v160 offset:39936
	global_load_lds_dwordx4 v[234:235], off
	v_lshl_add_u64 v[234:235], s[30:31], 0, v[132:133]
	s_mov_b32 m0, s45
	s_nop 0
	global_load_lds_dwordx4 v[234:235], off
	s_waitcnt vmcnt(8)
	s_waitcnt lgkmcnt(0)
	s_barrier
	s_setprio 1
	s_waitcnt lgkmcnt(0)
	v_mfma_f32_16x16x32_bf16 v[124:127], v[162:165], v[194:197], v[124:127]
	v_mfma_f32_16x16x32_bf16 v[120:123], v[170:173], v[194:197], v[120:123]
	v_mfma_f32_16x16x32_bf16 v[108:111], v[162:165], v[202:205], v[108:111]
	v_mfma_f32_16x16x32_bf16 v[104:107], v[170:173], v[202:205], v[104:107]
	v_mfma_f32_16x16x32_bf16 v[92:95], v[162:165], v[210:213], v[92:95]
	v_mfma_f32_16x16x32_bf16 v[88:91], v[170:173], v[210:213], v[88:91]
	v_mfma_f32_16x16x32_bf16 v[76:79], v[162:165], v[218:221], v[76:79]
	v_mfma_f32_16x16x32_bf16 v[72:75], v[170:173], v[218:221], v[72:75]
	v_mfma_f32_16x16x32_bf16 v[124:127], v[166:169], v[198:201], v[124:127]
	v_mfma_f32_16x16x32_bf16 v[120:123], v[174:177], v[198:201], v[120:123]
	v_mfma_f32_16x16x32_bf16 v[108:111], v[166:169], v[206:209], v[108:111]
	v_mfma_f32_16x16x32_bf16 v[104:107], v[174:177], v[206:209], v[104:107]
	v_mfma_f32_16x16x32_bf16 v[92:95], v[166:169], v[214:217], v[92:95]
	v_mfma_f32_16x16x32_bf16 v[88:91], v[174:177], v[214:217], v[88:91]
	v_mfma_f32_16x16x32_bf16 v[76:79], v[166:169], v[222:225], v[76:79]
	v_mfma_f32_16x16x32_bf16 v[72:75], v[174:177], v[222:225], v[72:75]
	s_setprio 0
	s_setprio 1
	v_mfma_f32_16x16x32_bf16 v[116:119], v[178:181], v[194:197], v[116:119]
	v_mfma_f32_16x16x32_bf16 v[112:115], v[186:189], v[194:197], v[112:115]
	v_mfma_f32_16x16x32_bf16 v[100:103], v[178:181], v[202:205], v[100:103]
	v_mfma_f32_16x16x32_bf16 v[96:99], v[186:189], v[202:205], v[96:99]
	v_mfma_f32_16x16x32_bf16 v[84:87], v[178:181], v[210:213], v[84:87]
	v_mfma_f32_16x16x32_bf16 v[80:83], v[186:189], v[210:213], v[80:83]
	v_mfma_f32_16x16x32_bf16 v[68:71], v[178:181], v[218:221], v[68:71]
	v_mfma_f32_16x16x32_bf16 v[64:67], v[186:189], v[218:221], v[64:67]
	v_mfma_f32_16x16x32_bf16 v[116:119], v[182:185], v[198:201], v[116:119]
	v_mfma_f32_16x16x32_bf16 v[112:115], v[190:193], v[198:201], v[112:115]
	v_mfma_f32_16x16x32_bf16 v[100:103], v[182:185], v[206:209], v[100:103]
	v_mfma_f32_16x16x32_bf16 v[96:99], v[190:193], v[206:209], v[96:99]
	v_mfma_f32_16x16x32_bf16 v[84:87], v[182:185], v[214:217], v[84:87]
	v_mfma_f32_16x16x32_bf16 v[80:83], v[190:193], v[214:217], v[80:83]
	v_mfma_f32_16x16x32_bf16 v[68:71], v[182:185], v[222:225], v[68:71]
	v_mfma_f32_16x16x32_bf16 v[64:67], v[190:193], v[222:225], v[64:67]
	s_setprio 0
	s_barrier
	s_add_i32 s29, s29, s33
	v_lshl_add_u64 v[226:227], v[226:227], 0, s[10:11]
	s_mov_b32 m0, s29
	ds_read_b128 v[194:197], v160 offset:49152
	ds_read_b128 v[198:201], v160 offset:50176
	ds_read_b128 v[202:205], v160 offset:51200
	ds_read_b128 v[206:209], v160 offset:52224
	ds_read_b128 v[210:213], v160 offset:53248
	ds_read_b128 v[214:217], v160 offset:54272
	ds_read_b128 v[218:221], v160 offset:55296
	ds_read_b128 v[222:225], v160 offset:56320
	global_load_lds_dwordx4 v[226:227], off
	s_add_i32 m0, s29, 0x2000
	s_add_u32 s22, s22, 0x10080
	v_lshl_add_u64 v[226:227], v[228:229], 0, s[10:11]
	s_addc_u32 s23, s23, 0
	s_add_i32 s29, s38, s33
	global_load_lds_dwordx4 v[226:227], off
	v_lshl_add_u64 v[226:227], s[22:23], 0, v[130:131]
	s_mov_b32 m0, s29
	s_nop 0
	global_load_lds_dwordx4 v[226:227], off
	v_lshl_add_u64 v[226:227], s[22:23], 0, v[134:135]
	s_add_i32 m0, s29, 0x2000
	s_nop 0
	global_load_lds_dwordx4 v[226:227], off
	v_lshl_add_u64 v[226:227], v[230:231], 0, s[10:11]
	s_mov_b32 m0, s48
	s_nop 0
	global_load_lds_dwordx4 v[226:227], off
	v_lshl_add_u64 v[226:227], v[232:233], 0, s[10:11]
	s_mov_b32 m0, s49
	s_nop 0
	global_load_lds_dwordx4 v[226:227], off
	s_waitcnt vmcnt(8)
	s_waitcnt lgkmcnt(0)
	s_barrier
; __device__ __forceinline__ unsigned cvt_pk_bf16(float lo, float hi) { const cvt_f32x2_t v = {lo, hi}; const cvt_bf16x2_t b = __builtin_convertvector(v, cvt_bf16x2_t); return __builtin_bit_cast(unsigned, b); }
; __device__ __forceinline__ unsigned swap8(unsigned v) { return (unsigned)__builtin_amdgcn_update_dpp(0, (int)v, 0x128  , 0xF, 0xF, false); }
; __device__ __forceinline__ void wide_store(bf16_t* O, int ldc, int rowg  , int col0  , int fr, u32x4 w0, u32x4 w1) {
;     const bool lo = fr < 8;
;     u32x4 snd = lo ? w1 : w0, rcv;
;     rcv.x = swap8(snd.x); rcv.y = swap8(snd.y); rcv.z = swap8(snd.z); rcv.w = swap8(snd.w);
;     const u32x4 first = lo ? w0 : rcv, second = lo ? rcv : w1;
;     bf16_t* p = O + (size_t)(rowg + (fr & 7)) * ldc + col0 + (lo ? 0 : 32);
;     __builtin_nontemporal_store(first, (u32x4*)p); __builtin_nontemporal_store(second, (u32x4*)(p + (size_t)8 * ldc));
;     __device__ __forceinline__ void operator()(const f32x4 (&acc)[2][2][4][2], const Unit& u, int wr, int wc, int fr, int fq) const {
;         const int col0 = u.pn * BM + wc * 64 + 8 * fq;
; #pragma unroll
;         for (int ai = 0; ai < 2; ++ai)
; #pragma unroll
;             for (int m = 0; m < 4; ++m) { const int rowg = u.pm * BM + ai * HALF + wr * 64 + m * 16;
;                 const float sc = slots ? rstd_from_slots(slots, rowg + fr, fq) : 1.0f;
;                 u32x4 w[2];
; #pragma unroll
;                 for (int bj = 0; bj < 2; ++bj) { const f32x4 v0 = acc[ai][bj][m][0] * sc, v1 = acc[ai][bj][m][1] * sc;
;                     w[bj].x = cvt_pk_bf16(v0[0], v0[1]); w[bj].y = cvt_pk_bf16(v0[2], v0[3]); w[bj].z = cvt_pk_bf16(v1[0], v1[1]); w[bj].w = cvt_pk_bf16(v1[2], v1[3]); }
;                 wide_store(O, ldc, rowg, col0, fr, w[0], w[1]); }
	s_setprio 1
	s_waitcnt lgkmcnt(0)
	v_mfma_f32_16x16x32_bf16 v[60:63], v[162:165], v[194:197], v[60:63]
	v_mfma_f32_16x16x32_bf16 v[56:59], v[170:173], v[194:197], v[56:59]
	v_mfma_f32_16x16x32_bf16 v[44:47], v[162:165], v[202:205], v[44:47]
	v_mfma_f32_16x16x32_bf16 v[40:43], v[170:173], v[202:205], v[40:43]
	v_mfma_f32_16x16x32_bf16 v[28:31], v[162:165], v[210:213], v[28:31]
	v_mfma_f32_16x16x32_bf16 v[24:27], v[170:173], v[210:213], v[24:27]
	v_mfma_f32_16x16x32_bf16 v[12:15], v[162:165], v[218:221], v[12:15]
	v_mfma_f32_16x16x32_bf16 v[8:11], v[170:173], v[218:221], v[8:11]
	v_mfma_f32_16x16x32_bf16 v[60:63], v[166:169], v[198:201], v[60:63]
	v_mfma_f32_16x16x32_bf16 v[56:59], v[174:177], v[198:201], v[56:59]
	v_mfma_f32_16x16x32_bf16 v[44:47], v[166:169], v[206:209], v[44:47]
	v_mfma_f32_16x16x32_bf16 v[40:43], v[174:177], v[206:209], v[40:43]
	v_mfma_f32_16x16x32_bf16 v[28:31], v[166:169], v[214:217], v[28:31]
	v_mfma_f32_16x16x32_bf16 v[24:27], v[174:177], v[214:217], v[24:27]
	v_mfma_f32_16x16x32_bf16 v[12:15], v[166:169], v[222:225], v[12:15]
	v_mfma_f32_16x16x32_bf16 v[8:11], v[174:177], v[222:225], v[8:11]
	s_setprio 0
	s_setprio 1
	v_mfma_f32_16x16x32_bf16 v[52:55], v[178:181], v[194:197], v[52:55]
	v_mfma_f32_16x16x32_bf16 v[48:51], v[186:189], v[194:197], v[48:51]
	v_mfma_f32_16x16x32_bf16 v[36:39], v[178:181], v[202:205], v[36:39]
	v_mfma_f32_16x16x32_bf16 v[32:35], v[186:189], v[202:205], v[32:35]
	v_mfma_f32_16x16x32_bf16 v[20:23], v[178:181], v[210:213], v[20:23]
	v_mfma_f32_16x16x32_bf16 v[16:19], v[186:189], v[210:213], v[16:19]
	v_mfma_f32_16x16x32_bf16 v[4:7], v[178:181], v[218:221], v[4:7]
	v_mfma_f32_16x16x32_bf16 v[0:3], v[186:189], v[218:221], v[0:3]
	v_mfma_f32_16x16x32_bf16 v[52:55], v[182:185], v[198:201], v[52:55]
	v_mfma_f32_16x16x32_bf16 v[48:51], v[190:193], v[198:201], v[48:51]
	v_mfma_f32_16x16x32_bf16 v[36:39], v[182:185], v[206:209], v[36:39]
	v_mfma_f32_16x16x32_bf16 v[32:35], v[190:193], v[206:209], v[32:35]
	v_mfma_f32_16x16x32_bf16 v[20:23], v[182:185], v[214:217], v[20:23]
	v_mfma_f32_16x16x32_bf16 v[16:19], v[190:193], v[214:217], v[16:19]
	v_mfma_f32_16x16x32_bf16 v[4:7], v[182:185], v[222:225], v[4:7]
	v_mfma_f32_16x16x32_bf16 v[0:3], v[190:193], v[222:225], v[0:3]
	s_setprio 0
	s_barrier
	s_add_i32 s28, s28, 2
	s_add_u32 s20, s20, 0x100
	s_addc_u32 s21, s21, 0
	s_add_u32 s26, s26, 0x100
	s_addc_u32 s27, s27, 0
	s_cmp_gt_u32 s28, 13
	s_cbranch_scc0 .LBB0_215
	v_cvt_pk_bf16_f32 v120, v120, v121
	v_cvt_pk_bf16_f32 v112, v112, v113
	v_cvt_pk_bf16_f32 v121, v122, v123
	v_cvt_pk_bf16_f32 v113, v114, v115
	v_cndmask_b32_e64 v115, v120, v112, s[2:3]
	v_mov_b32_e32 v122, 0
	v_cvt_pk_bf16_f32 v124, v124, v125
	v_cvt_pk_bf16_f32 v125, v126, v127
	v_cvt_pk_bf16_f32 v126, v116, v117
	v_cvt_pk_bf16_f32 v127, v118, v119
	v_cndmask_b32_e64 v114, v121, v113, s[2:3]
	v_mov_b32_dpp v122, v115 row_ror:8 row_mask:0xf bank_mask:0xf
	v_mov_b32_e32 v115, 0
	v_readlane_b32 s30, v239, 49
	v_lshl_or_b32 v162, s1, 8, v147
	s_lshl_b32 s0, s0, 8
	v_cndmask_b32_e64 v116, v125, v127, s[2:3]
	v_cndmask_b32_e64 v117, v124, v126, s[2:3]
	v_mov_b32_e32 v161, 0
	v_mov_b32_e32 v164, 0
	v_mov_b32_dpp v115, v114 row_ror:8 row_mask:0xf bank_mask:0xf
	v_readlane_b32 s31, v239, 50
	v_cvt_pk_bf16_f32 v104, v104, v105
	v_cvt_pk_bf16_f32 v100, v100, v101
	v_cvt_pk_bf16_f32 v101, v102, v103
	v_cvt_pk_bf16_f32 v102, v96, v97
	v_ashrrev_i32_e32 v163, 31, v162
	v_mov_b32_dpp v161, v117 row_ror:8 row_mask:0xf bank_mask:0xf
	v_mov_b32_dpp v164, v116 row_ror:8 row_mask:0xf bank_mask:0xf
	v_cndmask_b32_e64 v118, v122, v120, s[2:3]
	v_cndmask_b32_e64 v123, v113, v115, s[2:3]
	v_cndmask_b32_e64 v122, v112, v122, s[2:3]
	v_add_u32_e32 v114, s0, v148
	v_mov_b64_e32 v[112:113], s[30:31]
	v_cvt_pk_bf16_f32 v108, v108, v109
	v_cvt_pk_bf16_f32 v109, v110, v111
	v_cvt_pk_bf16_f32 v105, v106, v107
	v_cvt_pk_bf16_f32 v103, v98, v99
	v_cndmask_b32_e64 v97, v104, v102, s[2:3]
	v_mov_b32_e32 v110, v137
	v_cndmask_b32_e64 v119, v115, v121, s[2:3]
	v_cndmask_b32_e64 v117, v164, v125, s[2:3]
	v_cndmask_b32_e64 v116, v161, v124, s[2:3]
	v_mad_i64_i32 v[124:125], s[20:21], v114, s53, v[112:113]
	v_lshlrev_b64 v[114:115], 1, v[162:163]
	v_cndmask_b32_e64 v96, v105, v103, s[2:3]
	v_cndmask_b32_e64 v98, v109, v101, s[2:3]
	v_mov_b32_e32 v107, v137
	v_mov_b32_dpp v110, v97 row_ror:8 row_mask:0xf bank_mask:0xf
	v_mov_b32_e32 v111, v137
	v_cvt_pk_bf16_f32 v88, v88, v89
	v_cvt_pk_bf16_f32 v84, v84, v85
	v_cvt_pk_bf16_f32 v85, v86, v87
	v_cvt_pk_bf16_f32 v86, v80, v81
	v_lshl_add_u64 v[124:125], v[124:125], 0, v[114:115]
	v_cndmask_b32_e64 v99, v108, v100, s[2:3]
	v_mov_b32_e32 v106, v137
	v_mov_b32_dpp v107, v98 row_ror:8 row_mask:0xf bank_mask:0xf
	v_mov_b32_dpp v111, v96 row_ror:8 row_mask:0xf bank_mask:0xf
	v_cndmask_b32_e64 v98, v110, v104, s[2:3]
	v_add_u32_e32 v104, s0, v149
	v_cvt_pk_bf16_f32 v92, v92, v93
	v_cvt_pk_bf16_f32 v93, v94, v95
	v_cvt_pk_bf16_f32 v89, v90, v91
	v_cvt_pk_bf16_f32 v87, v82, v83
	v_cndmask_b32_e64 v81, v88, v86, s[2:3]
	v_mov_b32_e32 v94, v137
	v_lshl_add_u64 v[124:125], v[124:125], 0, v[136:137]
	v_mov_b32_dpp v106, v99 row_ror:8 row_mask:0xf bank_mask:0xf
	v_cndmask_b32_e64 v99, v111, v105, s[2:3]
	v_mad_i64_i32 v[104:105], s[20:21], v104, s53, v[112:113]
	v_cndmask_b32_e64 v80, v89, v87, s[2:3]
	v_cndmask_b32_e64 v82, v93, v85, s[2:3]
	v_mov_b32_e32 v91, v137
	v_mov_b32_dpp v94, v81 row_ror:8 row_mask:0xf bank_mask:0xf
	v_mov_b32_e32 v95, v137
	v_cvt_pk_bf16_f32 v72, v72, v73
	v_cvt_pk_bf16_f32 v68, v68, v69
	v_cvt_pk_bf16_f32 v69, v70, v71
	v_cvt_pk_bf16_f32 v70, v64, v65
	s_cmp_lg_u64 s[12:13], 0
	s_cbranch_scc0 .LBB0_218
	s_barrier
; __device__ __forceinline__ unsigned cvt_pk_bf16(float lo, float hi) { const cvt_f32x2_t v = {lo, hi}; const cvt_bf16x2_t b = __builtin_convertvector(v, cvt_bf16x2_t); return __builtin_bit_cast(unsigned, b); }
; __device__ __forceinline__ unsigned swap8(unsigned v) { return (unsigned)__builtin_amdgcn_update_dpp(0, (int)v, 0x128  , 0xF, 0xF, false); }
; __device__ __forceinline__ void wide_store(bf16_t* O, int ldc, int rowg  , int col0  , int fr, u32x4 w0, u32x4 w1) {
;     const bool lo = fr < 8;
;     u32x4 snd = lo ? w1 : w0, rcv;
;     rcv.x = swap8(snd.x); rcv.y = swap8(snd.y); rcv.z = swap8(snd.z); rcv.w = swap8(snd.w);
;     const u32x4 first = lo ? w0 : rcv, second = lo ? rcv : w1;
;     bf16_t* p = O + (size_t)(rowg + (fr & 7)) * ldc + col0 + (lo ? 0 : 32);
;     __builtin_nontemporal_store(first, (u32x4*)p); __builtin_nontemporal_store(second, (u32x4*)(p + (size_t)8 * ldc));
; }
;     __device__ __forceinline__ void operator()(const f32x4 (&acc)[2][2][4][2], const Unit& u, int wr, int wc, int fr, int fq) const {
;         const int col0 = u.pn * BM + wc * 64 + 8 * fq;
; #pragma unroll
;         for (int ai = 0; ai < 2; ++ai)
; #pragma unroll
;             for (int m = 0; m < 4; ++m) { const int rowg = u.pm * BM + ai * HALF + wr * 64 + m * 16;
;                 const float sc = slots ? rstd_from_slots(slots, rowg + fr, fq) : 1.0f;
;                 u32x4 w[2];
; #pragma unroll
;                 for (int bj = 0; bj < 2; ++bj) { const f32x4 v0 = acc[ai][bj][m][0] * sc, v1 = acc[ai][bj][m][1] * sc;
;                     w[bj].x = cvt_pk_bf16(v0[0], v0[1]); w[bj].y = cvt_pk_bf16(v0[2], v0[3]); w[bj].z = cvt_pk_bf16(v1[0], v1[1]); w[bj].w = cvt_pk_bf16(v1[2], v1[3]); }
;                 wide_store(O, ldc, rowg, col0, fr, w[0], w[1]); }
;     }
.LBB0_218:
	global_store_dwordx4 v[124:125], v[116:119], off nt
	v_lshl_add_u64 v[104:105], v[104:105], 0, v[114:115]
	v_cndmask_b32_e64 v83, v92, v84, s[2:3]
	v_add_co_u32_e32 v116, vcc, s54, v124
	v_mov_b32_e32 v90, v137
	v_mov_b32_dpp v91, v82 row_ror:8 row_mask:0xf bank_mask:0xf
	v_mov_b32_dpp v95, v80 row_ror:8 row_mask:0xf bank_mask:0xf
	v_cndmask_b32_e64 v82, v94, v88, s[2:3]
	v_add_u32_e32 v88, s0, v150
	v_cvt_pk_bf16_f32 v76, v76, v77
	v_cvt_pk_bf16_f32 v77, v78, v79
	v_cvt_pk_bf16_f32 v73, v74, v75
	v_cvt_pk_bf16_f32 v71, v66, v67
	v_cndmask_b32_e64 v65, v72, v70, s[2:3]
	v_mov_b32_e32 v78, v137
	v_cndmask_b32_e64 v121, v127, v164, s[2:3]
	v_cndmask_b32_e64 v120, v126, v161, s[2:3]
	v_addc_co_u32_e32 v117, vcc, 0, v125, vcc
	v_cndmask_b32_e64 v97, v107, v109, s[2:3]
	v_cndmask_b32_e64 v96, v106, v108, s[2:3]
	v_lshl_add_u64 v[104:105], v[104:105], 0, v[136:137]
	v_mov_b32_dpp v90, v83 row_ror:8 row_mask:0xf bank_mask:0xf
	v_cndmask_b32_e64 v83, v95, v89, s[2:3]
	v_mad_i64_i32 v[88:89], s[20:21], v88, s53, v[112:113]
	v_cndmask_b32_e64 v64, v73, v71, s[2:3]
	v_cndmask_b32_e64 v66, v77, v69, s[2:3]
	v_mov_b32_e32 v75, v137
	v_mov_b32_dpp v78, v65 row_ror:8 row_mask:0xf bank_mask:0xf
	v_mov_b32_e32 v79, v137
	v_cvt_pk_bf16_f32 v56, v56, v57
	v_cvt_pk_bf16_f32 v52, v52, v53
	v_cvt_pk_bf16_f32 v53, v54, v55
	v_cvt_pk_bf16_f32 v54, v48, v49
	global_store_dwordx4 v[116:117], v[120:123], off nt
	global_store_dwordx4 v[104:105], v[96:99], off nt
	v_lshl_add_u64 v[88:89], v[88:89], 0, v[114:115]
	v_cndmask_b32_e64 v67, v76, v68, s[2:3]
	v_add_co_u32_e32 v96, vcc, s54, v104
	v_mov_b32_e32 v74, v137
	v_mov_b32_dpp v75, v66 row_ror:8 row_mask:0xf bank_mask:0xf
	v_mov_b32_dpp v79, v64 row_ror:8 row_mask:0xf bank_mask:0xf
	v_cndmask_b32_e64 v66, v78, v72, s[2:3]
	v_add_u32_e32 v72, s0, v151
	v_cvt_pk_bf16_f32 v60, v60, v61
	v_cvt_pk_bf16_f32 v61, v62, v63
	v_cvt_pk_bf16_f32 v57, v58, v59
	v_cvt_pk_bf16_f32 v55, v50, v51
	v_cndmask_b32_e64 v49, v56, v54, s[2:3]
	v_mov_b32_e32 v62, v137
	v_cndmask_b32_e64 v103, v103, v111, s[2:3]
	v_cndmask_b32_e64 v102, v102, v110, s[2:3]
	v_cndmask_b32_e64 v101, v101, v107, s[2:3]
	v_cndmask_b32_e64 v100, v100, v106, s[2:3]
	v_addc_co_u32_e32 v97, vcc, 0, v105, vcc
	v_cndmask_b32_e64 v81, v91, v93, s[2:3]
	v_cndmask_b32_e64 v80, v90, v92, s[2:3]
	v_lshl_add_u64 v[88:89], v[88:89], 0, v[136:137]
	v_mov_b32_dpp v74, v67 row_ror:8 row_mask:0xf bank_mask:0xf
	v_cndmask_b32_e64 v67, v79, v73, s[2:3]
	v_mad_i64_i32 v[72:73], s[20:21], v72, s53, v[112:113]
	v_cndmask_b32_e64 v48, v57, v55, s[2:3]
	v_cndmask_b32_e64 v50, v61, v53, s[2:3]
	v_mov_b32_e32 v59, v137
	v_mov_b32_dpp v62, v49 row_ror:8 row_mask:0xf bank_mask:0xf
	v_mov_b32_e32 v63, v137
	v_cvt_pk_bf16_f32 v40, v40, v41
	v_cvt_pk_bf16_f32 v36, v36, v37
	v_cvt_pk_bf16_f32 v37, v38, v39
	v_cvt_pk_bf16_f32 v38, v32, v33
	global_store_dwordx4 v[96:97], v[100:103], off nt
	global_store_dwordx4 v[88:89], v[80:83], off nt
	v_lshl_add_u64 v[72:73], v[72:73], 0, v[114:115]
	v_cndmask_b32_e64 v51, v60, v52, s[2:3]
	v_add_co_u32_e32 v80, vcc, s54, v88
	v_mov_b32_e32 v58, v137
	v_mov_b32_dpp v59, v50 row_ror:8 row_mask:0xf bank_mask:0xf
	v_mov_b32_dpp v63, v48 row_ror:8 row_mask:0xf bank_mask:0xf
	v_cndmask_b32_e64 v50, v62, v56, s[2:3]
	v_add_u32_e32 v56, s0, v152
	v_cvt_pk_bf16_f32 v44, v44, v45
	v_cvt_pk_bf16_f32 v45, v46, v47
	v_cvt_pk_bf16_f32 v41, v42, v43
	v_cvt_pk_bf16_f32 v39, v34, v35
	v_cndmask_b32_e64 v33, v40, v38, s[2:3]
	v_mov_b32_e32 v46, v137
	v_cndmask_b32_e64 v87, v87, v95, s[2:3]
	v_cndmask_b32_e64 v86, v86, v94, s[2:3]
	v_cndmask_b32_e64 v85, v85, v91, s[2:3]
	v_cndmask_b32_e64 v84, v84, v90, s[2:3]
	v_addc_co_u32_e32 v81, vcc, 0, v89, vcc
	v_cndmask_b32_e64 v65, v75, v77, s[2:3]
	v_cndmask_b32_e64 v64, v74, v76, s[2:3]
	v_lshl_add_u64 v[72:73], v[72:73], 0, v[136:137]
	v_mov_b32_dpp v58, v51 row_ror:8 row_mask:0xf bank_mask:0xf
	v_cndmask_b32_e64 v51, v63, v57, s[2:3]
	v_mad_i64_i32 v[56:57], s[20:21], v56, s53, v[112:113]
	v_cndmask_b32_e64 v32, v41, v39, s[2:3]
	v_cndmask_b32_e64 v34, v45, v37, s[2:3]
	v_mov_b32_e32 v43, v137
	v_mov_b32_dpp v46, v33 row_ror:8 row_mask:0xf bank_mask:0xf
	v_mov_b32_e32 v47, v137
	v_cvt_pk_bf16_f32 v24, v24, v25
	v_cvt_pk_bf16_f32 v20, v20, v21
	v_cvt_pk_bf16_f32 v21, v22, v23
	v_cvt_pk_bf16_f32 v22, v16, v17
	global_store_dwordx4 v[80:81], v[84:87], off nt
	global_store_dwordx4 v[72:73], v[64:67], off nt
	v_lshl_add_u64 v[56:57], v[56:57], 0, v[114:115]
	v_cndmask_b32_e64 v35, v44, v36, s[2:3]
	v_add_co_u32_e32 v64, vcc, s54, v72
; __device__ __forceinline__ unsigned cvt_pk_bf16(float lo, float hi) { const cvt_f32x2_t v = {lo, hi}; const cvt_bf16x2_t b = __builtin_convertvector(v, cvt_bf16x2_t); return __builtin_bit_cast(unsigned, b); }
; __device__ __forceinline__ unsigned swap8(unsigned v) { return (unsigned)__builtin_amdgcn_update_dpp(0, (int)v, 0x128  , 0xF, 0xF, false); }
; __device__ __forceinline__ void wide_store(bf16_t* O, int ldc, int rowg  , int col0  , int fr, u32x4 w0, u32x4 w1) {
;     const bool lo = fr < 8;
;     u32x4 snd = lo ? w1 : w0, rcv;
;     rcv.x = swap8(snd.x); rcv.y = swap8(snd.y); rcv.z = swap8(snd.z); rcv.w = swap8(snd.w);
;     const u32x4 first = lo ? w0 : rcv, second = lo ? rcv : w1;
;     bf16_t* p = O + (size_t)(rowg + (fr & 7)) * ldc + col0 + (lo ? 0 : 32);
;     __builtin_nontemporal_store(first, (u32x4*)p); __builtin_nontemporal_store(second, (u32x4*)(p + (size_t)8 * ldc));
; }
;     __device__ __forceinline__ void operator()(const f32x4 (&acc)[2][2][4][2], const Unit& u, int wr, int wc, int fr, int fq) const {
;         const int col0 = u.pn * BM + wc * 64 + 8 * fq;
; #pragma unroll
;         for (int ai = 0; ai < 2; ++ai)
; #pragma unroll
;             for (int m = 0; m < 4; ++m) { const int rowg = u.pm * BM + ai * HALF + wr * 64 + m * 16;
;                 const float sc = slots ? rstd_from_slots(slots, rowg + fr, fq) : 1.0f;
;                 u32x4 w[2];
; #pragma unroll
;                 for (int bj = 0; bj < 2; ++bj) { const f32x4 v0 = acc[ai][bj][m][0] * sc, v1 = acc[ai][bj][m][1] * sc;
;                     w[bj].x = cvt_pk_bf16(v0[0], v0[1]); w[bj].y = cvt_pk_bf16(v0[2], v0[3]); w[bj].z = cvt_pk_bf16(v1[0], v1[1]); w[bj].w = cvt_pk_bf16(v1[2], v1[3]); }
;                 wide_store(O, ldc, rowg, col0, fr, w[0], w[1]); }
;     }
	v_mov_b32_e32 v42, v137
	v_mov_b32_dpp v43, v34 row_ror:8 row_mask:0xf bank_mask:0xf
	v_mov_b32_dpp v47, v32 row_ror:8 row_mask:0xf bank_mask:0xf
	v_cndmask_b32_e64 v34, v46, v40, s[2:3]
	v_add_u32_e32 v40, s0, v155
	v_cvt_pk_bf16_f32 v28, v28, v29
	v_cvt_pk_bf16_f32 v29, v30, v31
	v_cvt_pk_bf16_f32 v25, v26, v27
	v_cvt_pk_bf16_f32 v23, v18, v19
	v_cndmask_b32_e64 v17, v24, v22, s[2:3]
	v_mov_b32_e32 v30, v137
	v_cndmask_b32_e64 v71, v71, v79, s[2:3]
	v_cndmask_b32_e64 v70, v70, v78, s[2:3]
	v_cndmask_b32_e64 v69, v69, v75, s[2:3]
	v_cndmask_b32_e64 v68, v68, v74, s[2:3]
	v_addc_co_u32_e32 v65, vcc, 0, v73, vcc
	v_cndmask_b32_e64 v49, v59, v61, s[2:3]
	v_cndmask_b32_e64 v48, v58, v60, s[2:3]
	v_lshl_add_u64 v[56:57], v[56:57], 0, v[136:137]
	v_mov_b32_dpp v42, v35 row_ror:8 row_mask:0xf bank_mask:0xf
	v_cndmask_b32_e64 v35, v47, v41, s[2:3]
	v_mad_i64_i32 v[40:41], s[20:21], v40, s53, v[112:113]
	v_cndmask_b32_e64 v16, v25, v23, s[2:3]
	v_cndmask_b32_e64 v18, v29, v21, s[2:3]
	v_mov_b32_e32 v27, v137
	v_mov_b32_dpp v30, v17 row_ror:8 row_mask:0xf bank_mask:0xf
	v_mov_b32_e32 v31, v137
	v_cvt_pk_bf16_f32 v8, v8, v9
	v_cvt_pk_bf16_f32 v4, v4, v5
	v_cvt_pk_bf16_f32 v5, v6, v7
	v_cvt_pk_bf16_f32 v6, v0, v1
	global_store_dwordx4 v[64:65], v[68:71], off nt
	global_store_dwordx4 v[56:57], v[48:51], off nt
	v_lshl_add_u64 v[40:41], v[40:41], 0, v[114:115]
	v_cndmask_b32_e64 v19, v28, v20, s[2:3]
	v_add_co_u32_e32 v48, vcc, s54, v56
	v_mov_b32_e32 v26, v137
	v_mov_b32_dpp v27, v18 row_ror:8 row_mask:0xf bank_mask:0xf
	v_mov_b32_dpp v31, v16 row_ror:8 row_mask:0xf bank_mask:0xf
	v_cndmask_b32_e64 v18, v30, v24, s[2:3]
	v_add_u32_e32 v24, s0, v156
	v_cvt_pk_bf16_f32 v12, v12, v13
	v_cvt_pk_bf16_f32 v13, v14, v15
	v_cvt_pk_bf16_f32 v9, v10, v11
	v_cvt_pk_bf16_f32 v7, v2, v3
	v_cndmask_b32_e64 v1, v8, v6, s[2:3]
	v_mov_b32_e32 v14, v137
	v_cndmask_b32_e64 v55, v55, v63, s[2:3]
	v_cndmask_b32_e64 v54, v54, v62, s[2:3]
	v_cndmask_b32_e64 v53, v53, v59, s[2:3]
	v_cndmask_b32_e64 v52, v52, v58, s[2:3]
	v_addc_co_u32_e32 v49, vcc, 0, v57, vcc
	v_cndmask_b32_e64 v33, v43, v45, s[2:3]
	v_cndmask_b32_e64 v32, v42, v44, s[2:3]
	v_lshl_add_u64 v[40:41], v[40:41], 0, v[136:137]
	v_mov_b32_dpp v26, v19 row_ror:8 row_mask:0xf bank_mask:0xf
	v_cndmask_b32_e64 v19, v31, v25, s[2:3]
	v_mad_i64_i32 v[24:25], s[20:21], v24, s53, v[112:113]
	v_cndmask_b32_e64 v0, v9, v7, s[2:3]
	v_cndmask_b32_e64 v2, v13, v5, s[2:3]
	v_mov_b32_e32 v11, v137
	v_mov_b32_dpp v14, v1 row_ror:8 row_mask:0xf bank_mask:0xf
	v_mov_b32_e32 v15, v137
	global_store_dwordx4 v[48:49], v[52:55], off nt
	global_store_dwordx4 v[40:41], v[32:35], off nt
	v_lshl_add_u64 v[24:25], v[24:25], 0, v[114:115]
	v_cndmask_b32_e64 v3, v12, v4, s[2:3]
	v_add_co_u32_e32 v32, vcc, s54, v40
	v_mov_b32_e32 v10, v137
	v_mov_b32_dpp v11, v2 row_ror:8 row_mask:0xf bank_mask:0xf
	v_mov_b32_dpp v15, v0 row_ror:8 row_mask:0xf bank_mask:0xf
	v_cndmask_b32_e64 v2, v14, v8, s[2:3]
	v_add_u32_e32 v8, s0, v157
	v_cndmask_b32_e64 v39, v39, v47, s[2:3]
	v_cndmask_b32_e64 v38, v38, v46, s[2:3]
	v_cndmask_b32_e64 v37, v37, v43, s[2:3]
	v_cndmask_b32_e64 v36, v36, v42, s[2:3]
	v_addc_co_u32_e32 v33, vcc, 0, v41, vcc
	v_cndmask_b32_e64 v17, v27, v29, s[2:3]
	v_cndmask_b32_e64 v16, v26, v28, s[2:3]
	v_lshl_add_u64 v[24:25], v[24:25], 0, v[136:137]
	v_mov_b32_dpp v10, v3 row_ror:8 row_mask:0xf bank_mask:0xf
	v_cndmask_b32_e64 v3, v15, v9, s[2:3]
	v_mad_i64_i32 v[8:9], s[0:1], v8, s53, v[112:113]
	global_store_dwordx4 v[32:33], v[36:39], off nt
	global_store_dwordx4 v[24:25], v[16:19], off nt
	v_lshl_add_u64 v[8:9], v[8:9], 0, v[114:115]
	v_cndmask_b32_e64 v23, v23, v31, s[2:3]
	v_add_co_u32_e32 v16, vcc, s54, v24
	v_cndmask_b32_e64 v22, v22, v30, s[2:3]
	v_cndmask_b32_e64 v21, v21, v27, s[2:3]
	v_cndmask_b32_e64 v20, v20, v26, s[2:3]
	v_addc_co_u32_e32 v17, vcc, 0, v25, vcc
	v_cndmask_b32_e64 v1, v11, v13, s[2:3]
	v_cndmask_b32_e64 v0, v10, v12, s[2:3]
	v_lshl_add_u64 v[8:9], v[8:9], 0, v[136:137]
	global_store_dwordx4 v[16:17], v[20:23], off nt
	global_store_dwordx4 v[8:9], v[0:3], off nt
	v_cndmask_b32_e64 v7, v7, v15, s[2:3]
	v_cndmask_b32_e64 v6, v6, v14, s[2:3]
	v_add_co_u32_e32 v0, vcc, 0x24000, v8
	v_cndmask_b32_e64 v5, v5, v11, s[2:3]
	s_nop 0
	v_addc_co_u32_e32 v1, vcc, 0, v9, vcc
	v_cndmask_b32_e64 v4, v4, v10, s[2:3]
	s_andn2_b64 vcc, exec, s[4:5]
	s_mov_b64 s[0:1], -1
	global_store_dwordx4 v[0:1], v[4:7], off nt
	s_cbranch_vccnz .LBB0_211
	s_andn2_b64 vcc, exec, s[8:9]
	s_cbranch_vccnz .LBB0_210
	s_barrier
	s_branch .LBB0_210

; #define PG8_STAGE(bufoff, gbase, voff) do { _Pragma("unroll") for (int _i = 0; _i < 2; ++_i) \
;         __builtin_amdgcn_global_load_lds((const unsigned*)((const char*)(gbase) + (voff)[_i]), (PG8_LAS unsigned*)(lds + (bufoff) + ldsw + _i * 8192), 16, 0, PG8_LOAD_AUX); } while (0)
; #define PG8_LDA(dst, b, h) do { _Pragma("unroll") for (int m = 0; m < 4; ++m) _Pragma("unroll") for (int k = 0; k < 2; ++k) dst[m][k] = *(const PG8_LAS bf16x8*)(lds + PG8_SA(b, h) + aoff + m * 2048 + k * 1024); } while (0)
; #define PG8_LDB(dst, b, h) do { _Pragma("unroll") for (int n = 0; n < 2; ++n) _Pragma("unroll") for (int k = 0; k < 2; ++k) dst[n][k] = *(const PG8_LAS bf16x8*)(lds + PG8_SB(b, h) + boff + n * 2048 + k * 1024); } while (0)
; #define PG8_MMA(ai, bj, At, Bt) do { __builtin_amdgcn_s_setprio(1); _Pragma("unroll") for (int m = 0; m < 4; ++m) _Pragma("unroll") for (int n = 0; n < 2; ++n) _Pragma("unroll") for (int k = 0; k < 2; ++k) \
;         acc[ai][bj][m][n] = __builtin_amdgcn_mfma_f32_16x16x32_bf16(Bt[n][k], At[m][k], acc[ai][bj][m][n], 0, 0, 0); __builtin_amdgcn_s_setprio(0); } while (0)
; #define PG8_WAIT_V(n) asm volatile("s_waitcnt vmcnt(" #n ")" ::: "memory")
; #define PG8_WAIT_L(n) asm volatile("s_waitcnt lgkmcnt(" #n ")" ::: "memory")
; #define PG8_BAR __builtin_amdgcn_s_barrier()
; #define PG8_SCHED __builtin_amdgcn_sched_barrier(0)
; template <class Epi, class Sched, bool ALIGN_EPI = false, bool SP2 = false>
; __device__ __forceinline__ void gemm_phase(PG8_LAS unsigned char* lds, const Gemm g, const Sched& S, const Epi& E) {
;     ...
;             PG8_LDB(B0, 1, 0); PG8_LDB(B1, 1, 1); PG8_SCHED; PG8_LDA(At, 1, 0); PG8_STAGE(PG8_SA(0, 1), a2 + hstepA, voffA);
;             PG8_WAIT_V(8); PG8_WAIT_L(0); PG8_BAR; PG8_MMA(0, 0, At, B0); PG8_MMA(0, 1, At, B1); PG8_BAR; PG8_SCHED;
;             PG8_LDA(At, 1, 1); PG8_STAGE(PG8_SB(1, 0), b3, voffB); PG8_STAGE(PG8_SB(1, 1), b3 + hstepB, voffB); PG8_STAGE(PG8_SA(1, 0), a3, voffA);
;             PG8_WAIT_V(8); PG8_WAIT_L(0); PG8_BAR; PG8_MMA(1, 0, At, B0); PG8_MMA(1, 1, At, B1); PG8_BAR; PG8_SCHED;
.Lkmid_P3:
	s_add_i32 s29, 0, 0x18000
	s_add_i32 s38, 0, 0x1c000
	v_add_u32_e32 v174, s29, v146
	v_add_u32_e32 v190, s38, v146
	ds_read_b128 v[162:165], v174
	ds_read_b128 v[166:169], v174 offset:1024
	ds_read_b128 v[170:173], v174 offset:2048
	ds_read_b128 v[174:177], v174 offset:3072
	ds_read_b128 v[178:181], v190
	ds_read_b128 v[182:185], v190 offset:1024
	ds_read_b128 v[186:189], v190 offset:2048
	ds_read_b128 v[190:193], v190 offset:3072
	s_add_u32 s30, s34, 0x40000
	s_addc_u32 s31, s35, 0
	s_mov_b32 m0, s46
	v_lshl_add_u64 v[234:235], s[30:31], 0, v[134:135]
	ds_read_b128 v[194:197], v161 offset:32768
	ds_read_b128 v[198:201], v161 offset:33792
	ds_read_b128 v[202:205], v161 offset:34816
	ds_read_b128 v[206:209], v161 offset:35840
	ds_read_b128 v[210:213], v161 offset:36864
	ds_read_b128 v[214:217], v161 offset:37888
	ds_read_b128 v[218:221], v161 offset:38912
	ds_read_b128 v[222:225], v161 offset:39936
	global_load_lds_dwordx4 v[234:235], off
	v_lshl_add_u64 v[234:235], s[30:31], 0, v[130:131]
	s_mov_b32 m0, s47
	s_nop 0
	global_load_lds_dwordx4 v[234:235], off
	s_waitcnt vmcnt(8)
	s_waitcnt lgkmcnt(0)
	s_barrier
	s_setprio 1
	s_waitcnt lgkmcnt(0)
	v_mfma_f32_16x16x32_bf16 v[124:127], v[162:165], v[194:197], v[124:127]
	v_mfma_f32_16x16x32_bf16 v[120:123], v[170:173], v[194:197], v[120:123]
	v_mfma_f32_16x16x32_bf16 v[108:111], v[162:165], v[202:205], v[108:111]
	v_mfma_f32_16x16x32_bf16 v[104:107], v[170:173], v[202:205], v[104:107]
	v_mfma_f32_16x16x32_bf16 v[92:95], v[162:165], v[210:213], v[92:95]
	v_mfma_f32_16x16x32_bf16 v[88:91], v[170:173], v[210:213], v[88:91]
	v_mfma_f32_16x16x32_bf16 v[76:79], v[162:165], v[218:221], v[76:79]
	v_mfma_f32_16x16x32_bf16 v[72:75], v[170:173], v[218:221], v[72:75]
	v_mfma_f32_16x16x32_bf16 v[124:127], v[166:169], v[198:201], v[124:127]
	v_mfma_f32_16x16x32_bf16 v[120:123], v[174:177], v[198:201], v[120:123]
	v_mfma_f32_16x16x32_bf16 v[108:111], v[166:169], v[206:209], v[108:111]
	v_mfma_f32_16x16x32_bf16 v[104:107], v[174:177], v[206:209], v[104:107]
	v_mfma_f32_16x16x32_bf16 v[92:95], v[166:169], v[214:217], v[92:95]
	v_mfma_f32_16x16x32_bf16 v[88:91], v[174:177], v[214:217], v[88:91]
	v_mfma_f32_16x16x32_bf16 v[76:79], v[166:169], v[222:225], v[76:79]
	v_mfma_f32_16x16x32_bf16 v[72:75], v[174:177], v[222:225], v[72:75]
	s_setprio 0
	s_setprio 1
	v_mfma_f32_16x16x32_bf16 v[116:119], v[178:181], v[194:197], v[116:119]
	v_mfma_f32_16x16x32_bf16 v[112:115], v[186:189], v[194:197], v[112:115]
	v_mfma_f32_16x16x32_bf16 v[100:103], v[178:181], v[202:205], v[100:103]
	v_mfma_f32_16x16x32_bf16 v[96:99], v[186:189], v[202:205], v[96:99]
	v_mfma_f32_16x16x32_bf16 v[84:87], v[178:181], v[210:213], v[84:87]
	v_mfma_f32_16x16x32_bf16 v[80:83], v[186:189], v[210:213], v[80:83]
	v_mfma_f32_16x16x32_bf16 v[68:71], v[178:181], v[218:221], v[68:71]
	v_mfma_f32_16x16x32_bf16 v[64:67], v[186:189], v[218:221], v[64:67]
	v_mfma_f32_16x16x32_bf16 v[116:119], v[182:185], v[198:201], v[116:119]
	v_mfma_f32_16x16x32_bf16 v[112:115], v[190:193], v[198:201], v[112:115]
	v_mfma_f32_16x16x32_bf16 v[100:103], v[182:185], v[206:209], v[100:103]
	v_mfma_f32_16x16x32_bf16 v[96:99], v[190:193], v[206:209], v[96:99]
	v_mfma_f32_16x16x32_bf16 v[84:87], v[182:185], v[214:217], v[84:87]
	v_mfma_f32_16x16x32_bf16 v[80:83], v[190:193], v[214:217], v[80:83]
	v_mfma_f32_16x16x32_bf16 v[68:71], v[182:185], v[222:225], v[68:71]
	v_mfma_f32_16x16x32_bf16 v[64:67], v[190:193], v[222:225], v[64:67]
	s_setprio 0
	s_barrier
	s_add_i32 s29, s29, s37
	v_lshl_add_u64 v[226:227], v[226:227], 0, s[10:11]
	s_mov_b32 m0, s29
	ds_read_b128 v[194:197], v161 offset:49152
	ds_read_b128 v[198:201], v161 offset:50176
	ds_read_b128 v[202:205], v161 offset:51200
	ds_read_b128 v[206:209], v161 offset:52224
	ds_read_b128 v[210:213], v161 offset:53248
	ds_read_b128 v[214:217], v161 offset:54272
	ds_read_b128 v[218:221], v161 offset:55296
	ds_read_b128 v[222:225], v161 offset:56320
	global_load_lds_dwordx4 v[226:227], off
	s_add_i32 m0, s29, 0x2000
	s_add_u32 s22, s22, 0x10080
	v_lshl_add_u64 v[226:227], v[228:229], 0, s[10:11]
	s_addc_u32 s23, s23, 0
	s_add_i32 s29, s38, s37
	global_load_lds_dwordx4 v[226:227], off
	v_lshl_add_u64 v[226:227], s[22:23], 0, v[132:133]
	s_mov_b32 m0, s29
	s_nop 0
	global_load_lds_dwordx4 v[226:227], off
	v_lshl_add_u64 v[226:227], s[22:23], 0, v[128:129]
	s_add_i32 m0, s29, 0x2000
	s_nop 0
	global_load_lds_dwordx4 v[226:227], off
	v_lshl_add_u64 v[226:227], v[230:231], 0, s[10:11]
	s_mov_b32 m0, s49
	s_nop 0
	global_load_lds_dwordx4 v[226:227], off
	v_lshl_add_u64 v[226:227], v[232:233], 0, s[10:11]
	s_mov_b32 m0, s50
	s_nop 0
	global_load_lds_dwordx4 v[226:227], off
	s_waitcnt vmcnt(8)
	s_waitcnt lgkmcnt(0)
	s_barrier
; __device__ __forceinline__ unsigned cvt_pk_bf16(float lo, float hi) { const cvt_f32x2_t v = {lo, hi}; const cvt_bf16x2_t b = __builtin_convertvector(v, cvt_bf16x2_t); return __builtin_bit_cast(unsigned, b); }
; #define PG8_STAGE(bufoff, gbase, voff) do { _Pragma("unroll") for (int _i = 0; _i < 2; ++_i) \
;         __builtin_amdgcn_global_load_lds((const unsigned*)((const char*)(gbase) + (voff)[_i]), (PG8_LAS unsigned*)(lds + (bufoff) + ldsw + _i * 8192), 16, 0, PG8_LOAD_AUX); } while (0)
; #define PG8_LDA(dst, b, h) do { _Pragma("unroll") for (int m = 0; m < 4; ++m) _Pragma("unroll") for (int k = 0; k < 2; ++k) dst[m][k] = *(const PG8_LAS bf16x8*)(lds + PG8_SA(b, h) + aoff + m * 2048 + k * 1024); } while (0)
; #define PG8_WAIT_V(n) asm volatile("s_waitcnt vmcnt(" #n ")" ::: "memory")
; #define PG8_WAIT_L(n) asm volatile("s_waitcnt lgkmcnt(" #n ")" ::: "memory")
; #define PG8_BAR __builtin_amdgcn_s_barrier()
;     __device__ __forceinline__ void operator()(const f32x4 (&acc)[2][2][4][2], const Unit& u, int wr, int wc, int fr, int fq) const {
;         const int col0 = u.pn * BM + wc * 64 + 8 * fq;
; #pragma unroll
;         for (int ai = 0; ai < 2; ++ai)
; #pragma unroll
;             for (int m = 0; m < 4; ++m) { const int rowg = u.pm * BM + ai * HALF + wr * 64 + m * 16;
;                 const float sc = slots ? rstd_from_slots(slots, rowg + fr, fq) : 1.0f;
;                 u32x4 w[2];
; #pragma unroll
;                 for (int bj = 0; bj < 2; ++bj) { const f32x4 v0 = acc[ai][bj][m][0] * sc, v1 = acc[ai][bj][m][1] * sc;
;                     w[bj].x = cvt_pk_bf16(v0[0], v0[1]); w[bj].y = cvt_pk_bf16(v0[2], v0[3]); w[bj].z = cvt_pk_bf16(v1[0], v1[1]); w[bj].w = cvt_pk_bf16(v1[2], v1[3]); }
;                 wide_store(O, ldc, rowg, col0, fr, w[0], w[1]); }
; template <class Epi, class Sched, bool ALIGN_EPI = false, bool SP2 = false>
; __device__ __forceinline__ void gemm_phase(PG8_LAS unsigned char* lds, const Gemm g, const Sched& S, const Epi& E) {
;     ...
;             PG8_WAIT_V(8); PG8_WAIT_L(0); PG8_BAR; PG8_MMA(0, 0, At, B0); PG8_MMA(0, 1, At, B1); PG8_BAR; PG8_SCHED;
;             PG8_LDA(At, 1, 1); PG8_STAGE(PG8_SB(1, 0), b3, voffB); PG8_STAGE(PG8_SB(1, 1), b3 + hstepB, voffB); PG8_STAGE(PG8_SA(1, 0), a3, voffA);
;             PG8_WAIT_V(8); PG8_WAIT_L(0); PG8_BAR; PG8_MMA(1, 0, At, B0); PG8_MMA(1, 1, At, B1); PG8_BAR; PG8_SCHED;
	s_setprio 1
	s_waitcnt lgkmcnt(0)
	v_mfma_f32_16x16x32_bf16 v[60:63], v[162:165], v[194:197], v[60:63]
	v_mfma_f32_16x16x32_bf16 v[56:59], v[170:173], v[194:197], v[56:59]
	v_mfma_f32_16x16x32_bf16 v[44:47], v[162:165], v[202:205], v[44:47]
	v_mfma_f32_16x16x32_bf16 v[40:43], v[170:173], v[202:205], v[40:43]
	v_mfma_f32_16x16x32_bf16 v[28:31], v[162:165], v[210:213], v[28:31]
	v_mfma_f32_16x16x32_bf16 v[24:27], v[170:173], v[210:213], v[24:27]
	v_mfma_f32_16x16x32_bf16 v[12:15], v[162:165], v[218:221], v[12:15]
	v_mfma_f32_16x16x32_bf16 v[8:11], v[170:173], v[218:221], v[8:11]
	v_mfma_f32_16x16x32_bf16 v[60:63], v[166:169], v[198:201], v[60:63]
	v_mfma_f32_16x16x32_bf16 v[56:59], v[174:177], v[198:201], v[56:59]
	v_mfma_f32_16x16x32_bf16 v[44:47], v[166:169], v[206:209], v[44:47]
	v_mfma_f32_16x16x32_bf16 v[40:43], v[174:177], v[206:209], v[40:43]
	v_mfma_f32_16x16x32_bf16 v[28:31], v[166:169], v[214:217], v[28:31]
	v_mfma_f32_16x16x32_bf16 v[24:27], v[174:177], v[214:217], v[24:27]
	v_mfma_f32_16x16x32_bf16 v[12:15], v[166:169], v[222:225], v[12:15]
	v_mfma_f32_16x16x32_bf16 v[8:11], v[174:177], v[222:225], v[8:11]
	s_setprio 0
	s_setprio 1
	v_mfma_f32_16x16x32_bf16 v[52:55], v[178:181], v[194:197], v[52:55]
	v_mfma_f32_16x16x32_bf16 v[48:51], v[186:189], v[194:197], v[48:51]
	v_mfma_f32_16x16x32_bf16 v[36:39], v[178:181], v[202:205], v[36:39]
	v_mfma_f32_16x16x32_bf16 v[32:35], v[186:189], v[202:205], v[32:35]
	v_mfma_f32_16x16x32_bf16 v[20:23], v[178:181], v[210:213], v[20:23]
	v_mfma_f32_16x16x32_bf16 v[16:19], v[186:189], v[210:213], v[16:19]
	v_mfma_f32_16x16x32_bf16 v[4:7], v[178:181], v[218:221], v[4:7]
	v_mfma_f32_16x16x32_bf16 v[0:3], v[186:189], v[218:221], v[0:3]
	v_mfma_f32_16x16x32_bf16 v[52:55], v[182:185], v[198:201], v[52:55]
	v_mfma_f32_16x16x32_bf16 v[48:51], v[190:193], v[198:201], v[48:51]
	v_mfma_f32_16x16x32_bf16 v[36:39], v[182:185], v[206:209], v[36:39]
	v_mfma_f32_16x16x32_bf16 v[32:35], v[190:193], v[206:209], v[32:35]
	v_mfma_f32_16x16x32_bf16 v[20:23], v[182:185], v[214:217], v[20:23]
	v_mfma_f32_16x16x32_bf16 v[16:19], v[190:193], v[214:217], v[16:19]
	v_mfma_f32_16x16x32_bf16 v[4:7], v[182:185], v[222:225], v[4:7]
	v_mfma_f32_16x16x32_bf16 v[0:3], v[190:193], v[222:225], v[0:3]
	s_setprio 0
	s_barrier
	s_add_i32 s28, s28, 2
	s_add_u32 s20, s20, 0x100
	s_addc_u32 s21, s21, 0
	s_add_u32 s26, s26, 0x100
	s_addc_u32 s27, s27, 0
	s_cmp_gt_u32 s28, 13
	s_cbranch_scc0 .LBB0_369
	v_cvt_pk_bf16_f32 v120, v120, v121
	v_cvt_pk_bf16_f32 v112, v112, v113
	v_cvt_pk_bf16_f32 v121, v122, v123
	v_cvt_pk_bf16_f32 v113, v114, v115
	v_cndmask_b32_e64 v115, v120, v112, s[2:3]
	v_mov_b32_e32 v122, 0
	v_cvt_pk_bf16_f32 v124, v124, v125
	v_cvt_pk_bf16_f32 v125, v126, v127
	v_cvt_pk_bf16_f32 v126, v116, v117
	v_cvt_pk_bf16_f32 v127, v118, v119
	v_cndmask_b32_e64 v114, v121, v113, s[2:3]
	v_mov_b32_dpp v122, v115 row_ror:8 row_mask:0xf bank_mask:0xf
	v_mov_b32_e32 v115, 0
	v_readlane_b32 s30, v239, 49
	v_lshl_or_b32 v162, s1, 8, v147
	s_lshl_b32 s0, s0, 8
	v_cndmask_b32_e64 v116, v125, v127, s[2:3]
	v_cndmask_b32_e64 v117, v124, v126, s[2:3]
	v_mov_b32_e32 v164, 0
	v_mov_b32_e32 v165, 0
	v_mov_b32_dpp v115, v114 row_ror:8 row_mask:0xf bank_mask:0xf
	v_readlane_b32 s31, v239, 50
	v_cvt_pk_bf16_f32 v104, v104, v105
	v_cvt_pk_bf16_f32 v100, v100, v101
	v_cvt_pk_bf16_f32 v101, v102, v103
	v_cvt_pk_bf16_f32 v102, v96, v97
	v_ashrrev_i32_e32 v163, 31, v162
	v_mov_b32_dpp v164, v117 row_ror:8 row_mask:0xf bank_mask:0xf
	v_mov_b32_dpp v165, v116 row_ror:8 row_mask:0xf bank_mask:0xf
	v_cndmask_b32_e64 v118, v122, v120, s[2:3]
	v_cndmask_b32_e64 v123, v113, v115, s[2:3]
	v_cndmask_b32_e64 v122, v112, v122, s[2:3]
	v_add_u32_e32 v114, s0, v148
	v_mov_b64_e32 v[112:113], s[30:31]
	v_cvt_pk_bf16_f32 v108, v108, v109
	v_cvt_pk_bf16_f32 v109, v110, v111
	v_cvt_pk_bf16_f32 v105, v106, v107
	v_cvt_pk_bf16_f32 v103, v98, v99
	v_cndmask_b32_e64 v97, v104, v102, s[2:3]
	v_mov_b32_e32 v110, v137
	v_cndmask_b32_e64 v119, v115, v121, s[2:3]
	v_cndmask_b32_e64 v117, v165, v125, s[2:3]
	v_cndmask_b32_e64 v116, v164, v124, s[2:3]
	v_mad_i64_i32 v[124:125], s[20:21], v114, s55, v[112:113]
	v_lshlrev_b64 v[114:115], 1, v[162:163]
	v_cndmask_b32_e64 v96, v105, v103, s[2:3]
	v_cndmask_b32_e64 v98, v109, v101, s[2:3]
	v_mov_b32_e32 v107, v137
	v_mov_b32_dpp v110, v97 row_ror:8 row_mask:0xf bank_mask:0xf
	v_mov_b32_e32 v111, v137
	v_cvt_pk_bf16_f32 v88, v88, v89
	v_cvt_pk_bf16_f32 v84, v84, v85
	v_cvt_pk_bf16_f32 v85, v86, v87
	v_cvt_pk_bf16_f32 v86, v80, v81
	v_lshl_add_u64 v[124:125], v[124:125], 0, v[114:115]
	v_cndmask_b32_e64 v99, v108, v100, s[2:3]
	v_mov_b32_e32 v106, v137
	v_mov_b32_dpp v107, v98 row_ror:8 row_mask:0xf bank_mask:0xf
	v_mov_b32_dpp v111, v96 row_ror:8 row_mask:0xf bank_mask:0xf
	v_cndmask_b32_e64 v98, v110, v104, s[2:3]
	v_add_u32_e32 v104, s0, v149
	v_cvt_pk_bf16_f32 v92, v92, v93
	v_cvt_pk_bf16_f32 v93, v94, v95
	v_cvt_pk_bf16_f32 v89, v90, v91
	v_cvt_pk_bf16_f32 v87, v82, v83
	v_cndmask_b32_e64 v81, v88, v86, s[2:3]
	v_mov_b32_e32 v94, v137
	v_lshl_add_u64 v[124:125], v[124:125], 0, v[136:137]
	v_mov_b32_dpp v106, v99 row_ror:8 row_mask:0xf bank_mask:0xf
	v_cndmask_b32_e64 v99, v111, v105, s[2:3]
	v_mad_i64_i32 v[104:105], s[20:21], v104, s55, v[112:113]
	v_cndmask_b32_e64 v80, v89, v87, s[2:3]
	v_cndmask_b32_e64 v82, v93, v85, s[2:3]
	v_mov_b32_e32 v91, v137
	v_mov_b32_dpp v94, v81 row_ror:8 row_mask:0xf bank_mask:0xf
	v_mov_b32_e32 v95, v137
	v_cvt_pk_bf16_f32 v72, v72, v73
	v_cvt_pk_bf16_f32 v68, v68, v69
	v_cvt_pk_bf16_f32 v69, v70, v71
	v_cvt_pk_bf16_f32 v70, v64, v65
	s_cmp_lg_u64 s[12:13], 0
	s_cbranch_scc0 .LBB0_372
	s_barrier
; __device__ __forceinline__ unsigned cvt_pk_bf16(float lo, float hi) { const cvt_f32x2_t v = {lo, hi}; const cvt_bf16x2_t b = __builtin_convertvector(v, cvt_bf16x2_t); return __builtin_bit_cast(unsigned, b); }
; __device__ __forceinline__ unsigned swap8(unsigned v) { return (unsigned)__builtin_amdgcn_update_dpp(0, (int)v, 0x128  , 0xF, 0xF, false); }
; __device__ __forceinline__ void wide_store(bf16_t* O, int ldc, int rowg  , int col0  , int fr, u32x4 w0, u32x4 w1) {
;     const bool lo = fr < 8;
;     u32x4 snd = lo ? w1 : w0, rcv;
;     rcv.x = swap8(snd.x); rcv.y = swap8(snd.y); rcv.z = swap8(snd.z); rcv.w = swap8(snd.w);
;     const u32x4 first = lo ? w0 : rcv, second = lo ? rcv : w1;
;     bf16_t* p = O + (size_t)(rowg + (fr & 7)) * ldc + col0 + (lo ? 0 : 32);
;     __builtin_nontemporal_store(first, (u32x4*)p); __builtin_nontemporal_store(second, (u32x4*)(p + (size_t)8 * ldc));
; }
;     __device__ __forceinline__ void operator()(const f32x4 (&acc)[2][2][4][2], const Unit& u, int wr, int wc, int fr, int fq) const {
;         const int col0 = u.pn * BM + wc * 64 + 8 * fq;
; #pragma unroll
;         for (int ai = 0; ai < 2; ++ai)
; #pragma unroll
;             for (int m = 0; m < 4; ++m) { const int rowg = u.pm * BM + ai * HALF + wr * 64 + m * 16;
;                 const float sc = slots ? rstd_from_slots(slots, rowg + fr, fq) : 1.0f;
;                 u32x4 w[2];
; #pragma unroll
;                 for (int bj = 0; bj < 2; ++bj) { const f32x4 v0 = acc[ai][bj][m][0] * sc, v1 = acc[ai][bj][m][1] * sc;
;                     w[bj].x = cvt_pk_bf16(v0[0], v0[1]); w[bj].y = cvt_pk_bf16(v0[2], v0[3]); w[bj].z = cvt_pk_bf16(v1[0], v1[1]); w[bj].w = cvt_pk_bf16(v1[2], v1[3]); }
;                 wide_store(O, ldc, rowg, col0, fr, w[0], w[1]); }
;     }
.LBB0_372:
	global_store_dwordx4 v[124:125], v[116:119], off nt
	v_lshl_add_u64 v[104:105], v[104:105], 0, v[114:115]
	v_cndmask_b32_e64 v83, v92, v84, s[2:3]
	v_add_co_u32_e32 v116, vcc, s56, v124
	v_mov_b32_e32 v90, v137
	v_mov_b32_dpp v91, v82 row_ror:8 row_mask:0xf bank_mask:0xf
	v_mov_b32_dpp v95, v80 row_ror:8 row_mask:0xf bank_mask:0xf
	v_cndmask_b32_e64 v82, v94, v88, s[2:3]
	v_add_u32_e32 v88, s0, v150
	v_cvt_pk_bf16_f32 v76, v76, v77
	v_cvt_pk_bf16_f32 v77, v78, v79
	v_cvt_pk_bf16_f32 v73, v74, v75
	v_cvt_pk_bf16_f32 v71, v66, v67
	v_cndmask_b32_e64 v65, v72, v70, s[2:3]
	v_mov_b32_e32 v78, v137
	v_cndmask_b32_e64 v121, v127, v165, s[2:3]
	v_cndmask_b32_e64 v120, v126, v164, s[2:3]
	v_addc_co_u32_e32 v117, vcc, 0, v125, vcc
	v_cndmask_b32_e64 v97, v107, v109, s[2:3]
	v_cndmask_b32_e64 v96, v106, v108, s[2:3]
	v_lshl_add_u64 v[104:105], v[104:105], 0, v[136:137]
	v_mov_b32_dpp v90, v83 row_ror:8 row_mask:0xf bank_mask:0xf
	v_cndmask_b32_e64 v83, v95, v89, s[2:3]
	v_mad_i64_i32 v[88:89], s[20:21], v88, s55, v[112:113]
	v_cndmask_b32_e64 v64, v73, v71, s[2:3]
	v_cndmask_b32_e64 v66, v77, v69, s[2:3]
	v_mov_b32_e32 v75, v137
	v_mov_b32_dpp v78, v65 row_ror:8 row_mask:0xf bank_mask:0xf
	v_mov_b32_e32 v79, v137
	v_cvt_pk_bf16_f32 v56, v56, v57
	v_cvt_pk_bf16_f32 v52, v52, v53
	v_cvt_pk_bf16_f32 v53, v54, v55
	v_cvt_pk_bf16_f32 v54, v48, v49
	global_store_dwordx4 v[116:117], v[120:123], off nt
	global_store_dwordx4 v[104:105], v[96:99], off nt
	v_lshl_add_u64 v[88:89], v[88:89], 0, v[114:115]
	v_cndmask_b32_e64 v67, v76, v68, s[2:3]
	v_add_co_u32_e32 v96, vcc, s56, v104
	v_mov_b32_e32 v74, v137
	v_mov_b32_dpp v75, v66 row_ror:8 row_mask:0xf bank_mask:0xf
	v_mov_b32_dpp v79, v64 row_ror:8 row_mask:0xf bank_mask:0xf
	v_cndmask_b32_e64 v66, v78, v72, s[2:3]
	v_add_u32_e32 v72, s0, v151
	v_cvt_pk_bf16_f32 v60, v60, v61
	v_cvt_pk_bf16_f32 v61, v62, v63
	v_cvt_pk_bf16_f32 v57, v58, v59
	v_cvt_pk_bf16_f32 v55, v50, v51
	v_cndmask_b32_e64 v49, v56, v54, s[2:3]
	v_mov_b32_e32 v62, v137
	v_cndmask_b32_e64 v103, v103, v111, s[2:3]
	v_cndmask_b32_e64 v102, v102, v110, s[2:3]
	v_cndmask_b32_e64 v101, v101, v107, s[2:3]
	v_cndmask_b32_e64 v100, v100, v106, s[2:3]
	v_addc_co_u32_e32 v97, vcc, 0, v105, vcc
	v_cndmask_b32_e64 v81, v91, v93, s[2:3]
	v_cndmask_b32_e64 v80, v90, v92, s[2:3]
	v_lshl_add_u64 v[88:89], v[88:89], 0, v[136:137]
	v_mov_b32_dpp v74, v67 row_ror:8 row_mask:0xf bank_mask:0xf
	v_cndmask_b32_e64 v67, v79, v73, s[2:3]
	v_mad_i64_i32 v[72:73], s[20:21], v72, s55, v[112:113]
	v_cndmask_b32_e64 v48, v57, v55, s[2:3]
	v_cndmask_b32_e64 v50, v61, v53, s[2:3]
	v_mov_b32_e32 v59, v137
	v_mov_b32_dpp v62, v49 row_ror:8 row_mask:0xf bank_mask:0xf
	v_mov_b32_e32 v63, v137
	v_cvt_pk_bf16_f32 v40, v40, v41
	v_cvt_pk_bf16_f32 v36, v36, v37
	v_cvt_pk_bf16_f32 v37, v38, v39
	v_cvt_pk_bf16_f32 v38, v32, v33
	global_store_dwordx4 v[96:97], v[100:103], off nt
	global_store_dwordx4 v[88:89], v[80:83], off nt
	v_lshl_add_u64 v[72:73], v[72:73], 0, v[114:115]
	v_cndmask_b32_e64 v51, v60, v52, s[2:3]
	v_add_co_u32_e32 v80, vcc, s56, v88
	v_mov_b32_e32 v58, v137
	v_mov_b32_dpp v59, v50 row_ror:8 row_mask:0xf bank_mask:0xf
	v_mov_b32_dpp v63, v48 row_ror:8 row_mask:0xf bank_mask:0xf
	v_cndmask_b32_e64 v50, v62, v56, s[2:3]
	v_add_u32_e32 v56, s0, v152
	v_cvt_pk_bf16_f32 v44, v44, v45
	v_cvt_pk_bf16_f32 v45, v46, v47
	v_cvt_pk_bf16_f32 v41, v42, v43
	v_cvt_pk_bf16_f32 v39, v34, v35
	v_cndmask_b32_e64 v33, v40, v38, s[2:3]
	v_mov_b32_e32 v46, v137
	v_cndmask_b32_e64 v87, v87, v95, s[2:3]
	v_cndmask_b32_e64 v86, v86, v94, s[2:3]
	v_cndmask_b32_e64 v85, v85, v91, s[2:3]
	v_cndmask_b32_e64 v84, v84, v90, s[2:3]
	v_addc_co_u32_e32 v81, vcc, 0, v89, vcc
	v_cndmask_b32_e64 v65, v75, v77, s[2:3]
	v_cndmask_b32_e64 v64, v74, v76, s[2:3]
	v_lshl_add_u64 v[72:73], v[72:73], 0, v[136:137]
	v_mov_b32_dpp v58, v51 row_ror:8 row_mask:0xf bank_mask:0xf
	v_cndmask_b32_e64 v51, v63, v57, s[2:3]
	v_mad_i64_i32 v[56:57], s[20:21], v56, s55, v[112:113]
	v_cndmask_b32_e64 v32, v41, v39, s[2:3]
	v_cndmask_b32_e64 v34, v45, v37, s[2:3]
	v_mov_b32_e32 v43, v137
	v_mov_b32_dpp v46, v33 row_ror:8 row_mask:0xf bank_mask:0xf
	v_mov_b32_e32 v47, v137
	v_cvt_pk_bf16_f32 v24, v24, v25
	v_cvt_pk_bf16_f32 v20, v20, v21
	v_cvt_pk_bf16_f32 v21, v22, v23
	v_cvt_pk_bf16_f32 v22, v16, v17
	global_store_dwordx4 v[80:81], v[84:87], off nt
	global_store_dwordx4 v[72:73], v[64:67], off nt
	v_lshl_add_u64 v[56:57], v[56:57], 0, v[114:115]
	v_cndmask_b32_e64 v35, v44, v36, s[2:3]
	v_add_co_u32_e32 v64, vcc, s56, v72
; __device__ __forceinline__ unsigned cvt_pk_bf16(float lo, float hi) { const cvt_f32x2_t v = {lo, hi}; const cvt_bf16x2_t b = __builtin_convertvector(v, cvt_bf16x2_t); return __builtin_bit_cast(unsigned, b); }
; __device__ __forceinline__ unsigned swap8(unsigned v) { return (unsigned)__builtin_amdgcn_update_dpp(0, (int)v, 0x128  , 0xF, 0xF, false); }
; __device__ __forceinline__ void wide_store(bf16_t* O, int ldc, int rowg  , int col0  , int fr, u32x4 w0, u32x4 w1) {
;     const bool lo = fr < 8;
;     u32x4 snd = lo ? w1 : w0, rcv;
;     rcv.x = swap8(snd.x); rcv.y = swap8(snd.y); rcv.z = swap8(snd.z); rcv.w = swap8(snd.w);
;     const u32x4 first = lo ? w0 : rcv, second = lo ? rcv : w1;
;     bf16_t* p = O + (size_t)(rowg + (fr & 7)) * ldc + col0 + (lo ? 0 : 32);
;     __builtin_nontemporal_store(first, (u32x4*)p); __builtin_nontemporal_store(second, (u32x4*)(p + (size_t)8 * ldc));
; }
;     __device__ __forceinline__ void operator()(const f32x4 (&acc)[2][2][4][2], const Unit& u, int wr, int wc, int fr, int fq) const {
;         const int col0 = u.pn * BM + wc * 64 + 8 * fq;
; #pragma unroll
;         for (int ai = 0; ai < 2; ++ai)
; #pragma unroll
;             for (int m = 0; m < 4; ++m) { const int rowg = u.pm * BM + ai * HALF + wr * 64 + m * 16;
;                 const float sc = slots ? rstd_from_slots(slots, rowg + fr, fq) : 1.0f;
;                 u32x4 w[2];
; #pragma unroll
;                 for (int bj = 0; bj < 2; ++bj) { const f32x4 v0 = acc[ai][bj][m][0] * sc, v1 = acc[ai][bj][m][1] * sc;
;                     w[bj].x = cvt_pk_bf16(v0[0], v0[1]); w[bj].y = cvt_pk_bf16(v0[2], v0[3]); w[bj].z = cvt_pk_bf16(v1[0], v1[1]); w[bj].w = cvt_pk_bf16(v1[2], v1[3]); }
;                 wide_store(O, ldc, rowg, col0, fr, w[0], w[1]); }
;     }
	v_mov_b32_e32 v42, v137
	v_mov_b32_dpp v43, v34 row_ror:8 row_mask:0xf bank_mask:0xf
	v_mov_b32_dpp v47, v32 row_ror:8 row_mask:0xf bank_mask:0xf
	v_cndmask_b32_e64 v34, v46, v40, s[2:3]
	v_add_u32_e32 v40, s0, v156
	v_cvt_pk_bf16_f32 v28, v28, v29
	v_cvt_pk_bf16_f32 v29, v30, v31
	v_cvt_pk_bf16_f32 v25, v26, v27
	v_cvt_pk_bf16_f32 v23, v18, v19
	v_cndmask_b32_e64 v17, v24, v22, s[2:3]
	v_mov_b32_e32 v30, v137
	v_cndmask_b32_e64 v71, v71, v79, s[2:3]
	v_cndmask_b32_e64 v70, v70, v78, s[2:3]
	v_cndmask_b32_e64 v69, v69, v75, s[2:3]
	v_cndmask_b32_e64 v68, v68, v74, s[2:3]
	v_addc_co_u32_e32 v65, vcc, 0, v73, vcc
	v_cndmask_b32_e64 v49, v59, v61, s[2:3]
	v_cndmask_b32_e64 v48, v58, v60, s[2:3]
	v_lshl_add_u64 v[56:57], v[56:57], 0, v[136:137]
	v_mov_b32_dpp v42, v35 row_ror:8 row_mask:0xf bank_mask:0xf
	v_cndmask_b32_e64 v35, v47, v41, s[2:3]
	v_mad_i64_i32 v[40:41], s[20:21], v40, s55, v[112:113]
	v_cndmask_b32_e64 v16, v25, v23, s[2:3]
	v_cndmask_b32_e64 v18, v29, v21, s[2:3]
	v_mov_b32_e32 v27, v137
	v_mov_b32_dpp v30, v17 row_ror:8 row_mask:0xf bank_mask:0xf
	v_mov_b32_e32 v31, v137
	v_cvt_pk_bf16_f32 v8, v8, v9
	v_cvt_pk_bf16_f32 v4, v4, v5
	v_cvt_pk_bf16_f32 v5, v6, v7
	v_cvt_pk_bf16_f32 v6, v0, v1
	global_store_dwordx4 v[64:65], v[68:71], off nt
	global_store_dwordx4 v[56:57], v[48:51], off nt
	v_lshl_add_u64 v[40:41], v[40:41], 0, v[114:115]
	v_cndmask_b32_e64 v19, v28, v20, s[2:3]
	v_add_co_u32_e32 v48, vcc, s56, v56
	v_mov_b32_e32 v26, v137
	v_mov_b32_dpp v27, v18 row_ror:8 row_mask:0xf bank_mask:0xf
	v_mov_b32_dpp v31, v16 row_ror:8 row_mask:0xf bank_mask:0xf
	v_cndmask_b32_e64 v18, v30, v24, s[2:3]
	v_add_u32_e32 v24, s0, v157
	v_cvt_pk_bf16_f32 v12, v12, v13
	v_cvt_pk_bf16_f32 v13, v14, v15
	v_cvt_pk_bf16_f32 v9, v10, v11
	v_cvt_pk_bf16_f32 v7, v2, v3
	v_cndmask_b32_e64 v1, v8, v6, s[2:3]
	v_mov_b32_e32 v14, v137
	v_cndmask_b32_e64 v55, v55, v63, s[2:3]
	v_cndmask_b32_e64 v54, v54, v62, s[2:3]
	v_cndmask_b32_e64 v53, v53, v59, s[2:3]
	v_cndmask_b32_e64 v52, v52, v58, s[2:3]
	v_addc_co_u32_e32 v49, vcc, 0, v57, vcc
	v_cndmask_b32_e64 v33, v43, v45, s[2:3]
	v_cndmask_b32_e64 v32, v42, v44, s[2:3]
	v_lshl_add_u64 v[40:41], v[40:41], 0, v[136:137]
	v_mov_b32_dpp v26, v19 row_ror:8 row_mask:0xf bank_mask:0xf
	v_cndmask_b32_e64 v19, v31, v25, s[2:3]
	v_mad_i64_i32 v[24:25], s[20:21], v24, s55, v[112:113]
	v_cndmask_b32_e64 v0, v9, v7, s[2:3]
	v_cndmask_b32_e64 v2, v13, v5, s[2:3]
	v_mov_b32_e32 v11, v137
	v_mov_b32_dpp v14, v1 row_ror:8 row_mask:0xf bank_mask:0xf
	v_mov_b32_e32 v15, v137
	global_store_dwordx4 v[48:49], v[52:55], off nt
	global_store_dwordx4 v[40:41], v[32:35], off nt
	v_lshl_add_u64 v[24:25], v[24:25], 0, v[114:115]
	v_cndmask_b32_e64 v3, v12, v4, s[2:3]
	v_add_co_u32_e32 v32, vcc, s56, v40
	v_mov_b32_e32 v10, v137
	v_mov_b32_dpp v11, v2 row_ror:8 row_mask:0xf bank_mask:0xf
	v_mov_b32_dpp v15, v0 row_ror:8 row_mask:0xf bank_mask:0xf
	v_cndmask_b32_e64 v2, v14, v8, s[2:3]
	v_add_u32_e32 v8, s0, v158
	v_cndmask_b32_e64 v39, v39, v47, s[2:3]
	v_cndmask_b32_e64 v38, v38, v46, s[2:3]
	v_cndmask_b32_e64 v37, v37, v43, s[2:3]
	v_cndmask_b32_e64 v36, v36, v42, s[2:3]
	v_addc_co_u32_e32 v33, vcc, 0, v41, vcc
	v_cndmask_b32_e64 v17, v27, v29, s[2:3]
	v_cndmask_b32_e64 v16, v26, v28, s[2:3]
	v_lshl_add_u64 v[24:25], v[24:25], 0, v[136:137]
	v_mov_b32_dpp v10, v3 row_ror:8 row_mask:0xf bank_mask:0xf
	v_cndmask_b32_e64 v3, v15, v9, s[2:3]
	v_mad_i64_i32 v[8:9], s[0:1], v8, s55, v[112:113]
	global_store_dwordx4 v[32:33], v[36:39], off nt
	global_store_dwordx4 v[24:25], v[16:19], off nt
	v_lshl_add_u64 v[8:9], v[8:9], 0, v[114:115]
	v_cndmask_b32_e64 v23, v23, v31, s[2:3]
	v_add_co_u32_e32 v16, vcc, s56, v24
	v_cndmask_b32_e64 v22, v22, v30, s[2:3]
	v_cndmask_b32_e64 v21, v21, v27, s[2:3]
	v_cndmask_b32_e64 v20, v20, v26, s[2:3]
	v_addc_co_u32_e32 v17, vcc, 0, v25, vcc
	v_cndmask_b32_e64 v1, v11, v13, s[2:3]
	v_cndmask_b32_e64 v0, v10, v12, s[2:3]
	v_lshl_add_u64 v[8:9], v[8:9], 0, v[136:137]
	global_store_dwordx4 v[16:17], v[20:23], off nt
	global_store_dwordx4 v[8:9], v[0:3], off nt
	v_cndmask_b32_e64 v7, v7, v15, s[2:3]
	v_cndmask_b32_e64 v6, v6, v14, s[2:3]
	v_add_co_u32_e32 v0, vcc, 0x24000, v8
	v_cndmask_b32_e64 v5, v5, v11, s[2:3]
	s_nop 0
	v_addc_co_u32_e32 v1, vcc, 0, v9, vcc
	v_cndmask_b32_e64 v4, v4, v10, s[2:3]
	s_andn2_b64 vcc, exec, s[4:5]
	s_mov_b64 s[0:1], -1
	global_store_dwordx4 v[0:1], v[4:7], off nt
	s_cbranch_vccnz .LBB0_365
	s_andn2_b64 vcc, exec, s[8:9]
	s_cbranch_vccnz .LBB0_364
	s_barrier
	s_branch .LBB0_364

; #define PG8_STAGE(bufoff, gbase, voff) do { _Pragma("unroll") for (int _i = 0; _i < 2; ++_i) \
;         __builtin_amdgcn_global_load_lds((const unsigned*)((const char*)(gbase) + (voff)[_i]), (PG8_LAS unsigned*)(lds + (bufoff) + ldsw + _i * 8192), 16, 0, PG8_LOAD_AUX); } while (0)
; #define PG8_LDA(dst, b, h) do { _Pragma("unroll") for (int m = 0; m < 4; ++m) _Pragma("unroll") for (int k = 0; k < 2; ++k) dst[m][k] = *(const PG8_LAS bf16x8*)(lds + PG8_SA(b, h) + aoff + m * 2048 + k * 1024); } while (0)
; #define PG8_LDB(dst, b, h) do { _Pragma("unroll") for (int n = 0; n < 2; ++n) _Pragma("unroll") for (int k = 0; k < 2; ++k) dst[n][k] = *(const PG8_LAS bf16x8*)(lds + PG8_SB(b, h) + boff + n * 2048 + k * 1024); } while (0)
; #define PG8_MMA(ai, bj, At, Bt) do { __builtin_amdgcn_s_setprio(1); _Pragma("unroll") for (int m = 0; m < 4; ++m) _Pragma("unroll") for (int n = 0; n < 2; ++n) _Pragma("unroll") for (int k = 0; k < 2; ++k) \
;         acc[ai][bj][m][n] = __builtin_amdgcn_mfma_f32_16x16x32_bf16(Bt[n][k], At[m][k], acc[ai][bj][m][n], 0, 0, 0); __builtin_amdgcn_s_setprio(0); } while (0)
; #define PG8_WAIT_V(n) asm volatile("s_waitcnt vmcnt(" #n ")" ::: "memory")
; #define PG8_WAIT_L(n) asm volatile("s_waitcnt lgkmcnt(" #n ")" ::: "memory")
; #define PG8_BAR __builtin_amdgcn_s_barrier()
; #define PG8_SCHED __builtin_amdgcn_sched_barrier(0)
; template <class Epi, class Sched, bool ALIGN_EPI = false, bool SP2 = false>
; __device__ __forceinline__ void gemm_phase(PG8_LAS unsigned char* lds, const Gemm g, const Sched& S, const Epi& E) {
;     ...
;             PG8_LDB(B0, 1, 0); PG8_LDB(B1, 1, 1); PG8_SCHED; PG8_LDA(At, 1, 0); PG8_STAGE(PG8_SA(0, 1), a2 + hstepA, voffA);
;             PG8_WAIT_V(8); PG8_WAIT_L(0); PG8_BAR; PG8_MMA(0, 0, At, B0); PG8_MMA(0, 1, At, B1); PG8_BAR; PG8_SCHED;
;             PG8_LDA(At, 1, 1); PG8_STAGE(PG8_SB(1, 0), b3, voffB); PG8_STAGE(PG8_SB(1, 1), b3 + hstepB, voffB); PG8_STAGE(PG8_SA(1, 0), a3, voffA);
;             PG8_WAIT_V(8); PG8_WAIT_L(0); PG8_BAR; PG8_MMA(1, 0, At, B0); PG8_MMA(1, 1, At, B1); PG8_BAR; PG8_SCHED;
.Lkmid_P6:
	s_add_i32 s30, 0, 0x18000
	v_add_u32_e32 v161, s30, v152
	s_add_i32 s31, 0, 0x1c000
	ds_read_b128 v[146:149], v161
	ds_read_b128 v[162:165], v161 offset:1024
	ds_read_b128 v[166:169], v161 offset:2048
	ds_read_b128 v[170:173], v161 offset:3072
	v_add_u32_e32 v161, s31, v152
	ds_read_b128 v[174:177], v161
	ds_read_b128 v[178:181], v161 offset:1024
	ds_read_b128 v[182:185], v161 offset:2048
	ds_read_b128 v[186:189], v161 offset:3072
	s_add_u32 s22, s22, 0x40000
	s_addc_u32 s23, s23, 0
	s_mov_b32 m0, s50
	v_lshl_add_u64 v[230:231], s[22:23], 0, v[128:129]
	ds_read_b128 v[190:193], v159 offset:32768
	ds_read_b128 v[194:197], v159 offset:33792
	ds_read_b128 v[198:201], v159 offset:34816
	ds_read_b128 v[202:205], v159 offset:35840
	ds_read_b128 v[206:209], v159 offset:36864
	ds_read_b128 v[210:213], v159 offset:37888
	ds_read_b128 v[214:217], v159 offset:38912
	ds_read_b128 v[218:221], v159 offset:39936
	global_load_lds_dwordx4 v[230:231], off
	v_lshl_add_u64 v[230:231], s[22:23], 0, v[132:133]
	s_mov_b32 m0, s51
	s_nop 0
	global_load_lds_dwordx4 v[230:231], off
	s_waitcnt vmcnt(8)
	s_waitcnt lgkmcnt(0)
	s_barrier
	s_setprio 1
	s_waitcnt lgkmcnt(0)
	v_mfma_f32_16x16x32_bf16 v[124:127], v[146:149], v[190:193], v[124:127]
	v_mfma_f32_16x16x32_bf16 v[120:123], v[166:169], v[190:193], v[120:123]
	v_mfma_f32_16x16x32_bf16 v[108:111], v[146:149], v[198:201], v[108:111]
	v_mfma_f32_16x16x32_bf16 v[104:107], v[166:169], v[198:201], v[104:107]
	v_mfma_f32_16x16x32_bf16 v[92:95], v[146:149], v[206:209], v[92:95]
	v_mfma_f32_16x16x32_bf16 v[88:91], v[166:169], v[206:209], v[88:91]
	v_mfma_f32_16x16x32_bf16 v[76:79], v[146:149], v[214:217], v[76:79]
	v_mfma_f32_16x16x32_bf16 v[72:75], v[166:169], v[214:217], v[72:75]
	v_mfma_f32_16x16x32_bf16 v[124:127], v[162:165], v[194:197], v[124:127]
	v_mfma_f32_16x16x32_bf16 v[120:123], v[170:173], v[194:197], v[120:123]
	v_mfma_f32_16x16x32_bf16 v[108:111], v[162:165], v[202:205], v[108:111]
	v_mfma_f32_16x16x32_bf16 v[104:107], v[170:173], v[202:205], v[104:107]
	v_mfma_f32_16x16x32_bf16 v[92:95], v[162:165], v[210:213], v[92:95]
	v_mfma_f32_16x16x32_bf16 v[88:91], v[170:173], v[210:213], v[88:91]
	v_mfma_f32_16x16x32_bf16 v[76:79], v[162:165], v[218:221], v[76:79]
	v_mfma_f32_16x16x32_bf16 v[72:75], v[170:173], v[218:221], v[72:75]
	s_setprio 0
	s_setprio 1
	v_mfma_f32_16x16x32_bf16 v[116:119], v[174:177], v[190:193], v[116:119]
	v_mfma_f32_16x16x32_bf16 v[112:115], v[182:185], v[190:193], v[112:115]
	v_mfma_f32_16x16x32_bf16 v[100:103], v[174:177], v[198:201], v[100:103]
	v_mfma_f32_16x16x32_bf16 v[96:99], v[182:185], v[198:201], v[96:99]
	v_mfma_f32_16x16x32_bf16 v[84:87], v[174:177], v[206:209], v[84:87]
	v_mfma_f32_16x16x32_bf16 v[80:83], v[182:185], v[206:209], v[80:83]
	v_mfma_f32_16x16x32_bf16 v[68:71], v[174:177], v[214:217], v[68:71]
	v_mfma_f32_16x16x32_bf16 v[64:67], v[182:185], v[214:217], v[64:67]
	v_mfma_f32_16x16x32_bf16 v[116:119], v[178:181], v[194:197], v[116:119]
	v_mfma_f32_16x16x32_bf16 v[112:115], v[186:189], v[194:197], v[112:115]
	v_mfma_f32_16x16x32_bf16 v[100:103], v[178:181], v[202:205], v[100:103]
	v_mfma_f32_16x16x32_bf16 v[96:99], v[186:189], v[202:205], v[96:99]
	v_mfma_f32_16x16x32_bf16 v[84:87], v[178:181], v[210:213], v[84:87]
	v_mfma_f32_16x16x32_bf16 v[80:83], v[186:189], v[210:213], v[80:83]
	v_mfma_f32_16x16x32_bf16 v[68:71], v[178:181], v[218:221], v[68:71]
	v_mfma_f32_16x16x32_bf16 v[64:67], v[186:189], v[218:221], v[64:67]
	s_setprio 0
	s_barrier
	s_add_i32 s22, s30, s34
	v_lshl_add_u64 v[222:223], v[222:223], 0, s[14:15]
	s_mov_b32 m0, s22
	ds_read_b128 v[190:193], v159 offset:49152
	ds_read_b128 v[194:197], v159 offset:50176
	ds_read_b128 v[198:201], v159 offset:51200
	ds_read_b128 v[202:205], v159 offset:52224
	ds_read_b128 v[206:209], v159 offset:53248
	ds_read_b128 v[210:213], v159 offset:54272
	ds_read_b128 v[214:217], v159 offset:55296
	ds_read_b128 v[218:221], v159 offset:56320
	global_load_lds_dwordx4 v[222:223], off
	s_add_i32 m0, s22, 0x2000
	s_add_u32 s20, s20, 0x10080
	v_lshl_add_u64 v[222:223], v[224:225], 0, s[14:15]
	s_addc_u32 s21, s21, 0
	s_add_i32 s22, s31, s34
	global_load_lds_dwordx4 v[222:223], off
	v_lshl_add_u64 v[222:223], s[20:21], 0, v[130:131]
	s_mov_b32 m0, s22
	s_nop 0
	global_load_lds_dwordx4 v[222:223], off
	v_lshl_add_u64 v[222:223], s[20:21], 0, v[134:135]
	s_add_i32 m0, s22, 0x2000
	s_nop 0
	global_load_lds_dwordx4 v[222:223], off
	v_lshl_add_u64 v[222:223], v[226:227], 0, s[14:15]
	s_mov_b32 m0, s57
	s_nop 0
	global_load_lds_dwordx4 v[222:223], off
	v_lshl_add_u64 v[222:223], v[228:229], 0, s[14:15]
	s_mov_b32 m0, s58
	s_nop 0
	global_load_lds_dwordx4 v[222:223], off
	s_waitcnt vmcnt(8)
	s_waitcnt lgkmcnt(0)
	s_barrier
; __device__ __forceinline__ unsigned cvt_pk_bf16(float lo, float hi) { const cvt_f32x2_t v = {lo, hi}; const cvt_bf16x2_t b = __builtin_convertvector(v, cvt_bf16x2_t); return __builtin_bit_cast(unsigned, b); }
;     __device__ __forceinline__ void operator()(const f32x4 (&acc)[2][2][4][2], const Unit& u, int wr, int wc, int fr, int fq) const {
;     ...
;             for (int m = 0; m < 4; ++m) { const int rowg = u.pm * BM + ai * HALF + wr * 64 + m * 16, row = rowg + fr; const size_t off = (size_t)row * 1024 + col0;
;                 u32x4 w[2]; float ss = 0.f;
; #pragma unroll
;                 for (int bj = 0; bj < 2; ++bj) { f32x4 b0, b1;
;                     if (BASE_F32) { const float* bp = (const float*)base + off + 32 * bj; b0 = *(const f32x4*)bp; b1 = *(const f32x4*)(bp + 4); }
;                     else { const u32x4 bb = *(const u32x4*)((const bf16_t*)base + off + 32 * bj);
;                         b0 = (f32x4){__uint_as_float(bb.x << 16), __uint_as_float(bb.x & 0xffff0000u), __uint_as_float(bb.y << 16), __uint_as_float(bb.y & 0xffff0000u)};
;                         b1 = (f32x4){__uint_as_float(bb.z << 16), __uint_as_float(bb.z & 0xffff0000u), __uint_as_float(bb.w << 16), __uint_as_float(bb.w & 0xffff0000u)}; }
;                     const f32x4 o0 = b0 + acc[ai][bj][m][0], o1 = b1 + acc[ai][bj][m][1];
;                     ss += ((o0[0] * o0[0] + o0[1] * o0[1]) + (o0[2] * o0[2] + o0[3] * o0[3])) + ((o1[0] * o1[0] + o1[1] * o1[1]) + (o1[2] * o1[2] + o1[3] * o1[3]));
;                     w[bj].x = cvt_pk_bf16(o0[0], o0[1]); w[bj].y = cvt_pk_bf16(o0[2], o0[3]); w[bj].z = cvt_pk_bf16(o1[0], o1[1]); w[bj].w = cvt_pk_bf16(o1[2], o1[3]); }
;                 ss += __shfl_xor(ss, 16); ss += __shfl_xor(ss, 32); if (fq == 0) slots[(size_t)row * 16 + u.pn * 4 + wc] = ss;
	s_setprio 1
	s_waitcnt lgkmcnt(0)
	v_mfma_f32_16x16x32_bf16 v[60:63], v[146:149], v[190:193], v[60:63]
	v_mfma_f32_16x16x32_bf16 v[56:59], v[166:169], v[190:193], v[56:59]
	v_mfma_f32_16x16x32_bf16 v[44:47], v[146:149], v[198:201], v[44:47]
	v_mfma_f32_16x16x32_bf16 v[40:43], v[166:169], v[198:201], v[40:43]
	v_mfma_f32_16x16x32_bf16 v[28:31], v[146:149], v[206:209], v[28:31]
	v_mfma_f32_16x16x32_bf16 v[24:27], v[166:169], v[206:209], v[24:27]
	v_mfma_f32_16x16x32_bf16 v[12:15], v[146:149], v[214:217], v[12:15]
	v_mfma_f32_16x16x32_bf16 v[8:11], v[166:169], v[214:217], v[8:11]
	v_mfma_f32_16x16x32_bf16 v[60:63], v[162:165], v[194:197], v[60:63]
	v_mfma_f32_16x16x32_bf16 v[56:59], v[170:173], v[194:197], v[56:59]
	v_mfma_f32_16x16x32_bf16 v[44:47], v[162:165], v[202:205], v[44:47]
	v_mfma_f32_16x16x32_bf16 v[40:43], v[170:173], v[202:205], v[40:43]
	v_mfma_f32_16x16x32_bf16 v[28:31], v[162:165], v[210:213], v[28:31]
	v_mfma_f32_16x16x32_bf16 v[24:27], v[170:173], v[210:213], v[24:27]
	v_mfma_f32_16x16x32_bf16 v[12:15], v[162:165], v[218:221], v[12:15]
	v_mfma_f32_16x16x32_bf16 v[8:11], v[170:173], v[218:221], v[8:11]
	s_setprio 0
	s_setprio 1
	v_mfma_f32_16x16x32_bf16 v[52:55], v[174:177], v[190:193], v[52:55]
	v_mfma_f32_16x16x32_bf16 v[48:51], v[182:185], v[190:193], v[48:51]
	v_mfma_f32_16x16x32_bf16 v[36:39], v[174:177], v[198:201], v[36:39]
	v_mfma_f32_16x16x32_bf16 v[32:35], v[182:185], v[198:201], v[32:35]
	v_mfma_f32_16x16x32_bf16 v[20:23], v[174:177], v[206:209], v[20:23]
	v_mfma_f32_16x16x32_bf16 v[16:19], v[182:185], v[206:209], v[16:19]
	v_mfma_f32_16x16x32_bf16 v[4:7], v[174:177], v[214:217], v[4:7]
	v_mfma_f32_16x16x32_bf16 v[0:3], v[182:185], v[214:217], v[0:3]
	v_mfma_f32_16x16x32_bf16 v[52:55], v[178:181], v[194:197], v[52:55]
	v_mfma_f32_16x16x32_bf16 v[48:51], v[186:189], v[194:197], v[48:51]
	v_mfma_f32_16x16x32_bf16 v[36:39], v[178:181], v[202:205], v[36:39]
	v_mfma_f32_16x16x32_bf16 v[32:35], v[186:189], v[202:205], v[32:35]
	v_mfma_f32_16x16x32_bf16 v[20:23], v[178:181], v[210:213], v[20:23]
	v_mfma_f32_16x16x32_bf16 v[16:19], v[186:189], v[210:213], v[16:19]
	v_mfma_f32_16x16x32_bf16 v[4:7], v[178:181], v[218:221], v[4:7]
	v_mfma_f32_16x16x32_bf16 v[0:3], v[186:189], v[218:221], v[0:3]
	s_setprio 0
	s_barrier
	s_add_i32 s29, s29, 2
	s_add_u32 s0, s0, 0x100
	s_addc_u32 s1, s1, 0
	s_add_u32 s27, s27, 0x100
	s_addc_u32 s28, s28, 0
	s_cmp_gt_u32 s29, 13
	s_cbranch_scc0 .LBB0_585
	s_lshl_b32 s19, s48, 8
	s_add_i32 s19, s19, s56
	v_or_b32_e32 v148, s19, v150
	v_ashrrev_i32_e32 v149, 31, v148
	v_readlane_b32 s64, v239, 10
	v_lshl_or_b32 v146, s10, 8, v156
	v_lshlrev_b64 v[162:163], 12, v[148:149]
	v_readlane_b32 s65, v239, 11
	v_ashrrev_i32_e32 v147, 31, v146
	v_and_b32_e32 v178, 64, v160
	v_lshl_add_u64 v[162:163], s[64:65], 0, v[162:163]
	v_lshl_add_u64 v[174:175], v[146:147], 2, v[162:163]
	global_load_dwordx4 v[162:165], v[174:175], off
	global_load_dwordx4 v[166:169], v[174:175], off offset:16
	global_load_dwordx4 v[170:173], v[174:175], off offset:128
	s_nop 0
	global_load_dwordx4 v[174:177], v[174:175], off offset:144
	v_xor_b32_e32 v161, 16, v160
	v_add_u32_e32 v178, 64, v178
	v_cmp_lt_i32_e32 vcc, v161, v178
	s_lshl_b32 s0, s10, 2
	s_ashr_i32 s1, s0, 31
	v_cndmask_b32_e32 v161, v160, v161, vcc
	v_lshlrev_b32_e32 v161, 2, v161
	v_readlane_b32 s66, v239, 12
	v_readlane_b32 s67, v239, 13
	v_readlane_b32 s68, v239, 14
	v_readlane_b32 s69, v239, 15
	v_readlane_b32 s70, v239, 16
	v_readlane_b32 s71, v239, 17
	v_readlane_b32 s72, v239, 18
	v_readlane_b32 s73, v239, 19
	v_readlane_b32 s74, v239, 20
	v_readlane_b32 s75, v239, 21
	v_readlane_b32 s76, v239, 22
	v_readlane_b32 s77, v239, 23
	v_readlane_b32 s78, v239, 24
	v_readlane_b32 s79, v239, 25
	s_waitcnt vmcnt(0)
	v_pk_add_f32 v[126:127], v[126:127], v[164:165]
	v_pk_add_f32 v[124:125], v[124:125], v[162:163]
	v_pk_add_f32 v[122:123], v[122:123], v[168:169]
	v_pk_add_f32 v[120:121], v[120:121], v[166:167]
	v_pk_add_f32 v[118:119], v[118:119], v[172:173]
	v_pk_add_f32 v[116:117], v[116:117], v[170:171]
	v_pk_add_f32 v[114:115], v[114:115], v[176:177]
	v_pk_add_f32 v[112:113], v[112:113], v[174:175]
	v_mul_f32_e32 v162, v125, v125
	v_mul_f32_e32 v163, v127, v127
	v_mul_f32_e32 v164, v121, v121
	v_mul_f32_e32 v165, v123, v123
	v_mul_f32_e32 v166, v117, v117
	v_mul_f32_e32 v167, v119, v119
	v_mul_f32_e32 v168, v113, v113
	v_mul_f32_e32 v169, v115, v115
	v_fmac_f32_e32 v162, v124, v124
	v_fmac_f32_e32 v163, v126, v126
	v_fmac_f32_e32 v164, v120, v120
	v_fmac_f32_e32 v165, v122, v122
	v_fmac_f32_e32 v166, v116, v116
	v_fmac_f32_e32 v167, v118, v118
	v_fmac_f32_e32 v168, v112, v112
	v_fmac_f32_e32 v169, v114, v114
	v_add_f32_e32 v162, v162, v163
	v_add_f32_e32 v163, v164, v165
	v_add_f32_e32 v164, v166, v167
	v_add_f32_e32 v165, v168, v169
	v_add_f32_e32 v162, v162, v163
	v_add_f32_e32 v163, v164, v165
	v_add_f32_e32 v163, v162, v163
	ds_bpermute_b32 v164, v161, v163
	v_xor_b32_e32 v162, 32, v160
	v_cmp_lt_i32_e32 vcc, v162, v178
	s_waitcnt lgkmcnt(0)
	v_add_f32_e32 v163, v163, v164
	v_cndmask_b32_e32 v162, v160, v162, vcc
	v_lshlrev_b32_e32 v162, 2, v162
	ds_bpermute_b32 v164, v162, v163
	s_and_saveexec_b64 s[20:21], s[2:3]
	v_readlane_b32 s30, v239, 49
	v_readlane_b32 s31, v239, 50
	s_cbranch_execz .LBB0_590
	v_lshlrev_b64 v[148:149], 6, v[148:149]
	v_lshl_add_u64 v[148:149], s[82:83], 0, v[148:149]
	v_lshl_add_u64 v[148:149], s[0:1], 2, v[148:149]
	s_lshl_b32 s10, s55, 2
	v_lshl_add_u64 v[148:149], v[148:149], 0, s[10:11]
	s_waitcnt lgkmcnt(0)
	v_add_f32_e32 v163, v163, v164
	global_store_dword v[148:149], v163, off
; __device__ __forceinline__ unsigned swap8(unsigned v) { return (unsigned)__builtin_amdgcn_update_dpp(0, (int)v, 0x128  , 0xF, 0xF, false); }
; __device__ __forceinline__ void wide_store(bf16_t* O, int ldc, int rowg  , int col0  , int fr, u32x4 w0, u32x4 w1) {
;     const bool lo = fr < 8;
;     u32x4 snd = lo ? w1 : w0, rcv;
;     rcv.x = swap8(snd.x); rcv.y = swap8(snd.y); rcv.z = swap8(snd.z); rcv.w = swap8(snd.w);
;     const u32x4 first = lo ? w0 : rcv, second = lo ? rcv : w1;
;     bf16_t* p = O + (size_t)(rowg + (fr & 7)) * ldc + col0 + (lo ? 0 : 32);
;     __builtin_nontemporal_store(first, (u32x4*)p); __builtin_nontemporal_store(second, (u32x4*)(p + (size_t)8 * ldc));
; }
;     __device__ __forceinline__ void operator()(const f32x4 (&acc)[2][2][4][2], const Unit& u, int wr, int wc, int fr, int fq) const {
;         const int col0 = u.pn * BM + wc * 64 + 8 * fq;
; #pragma unroll
;         for (int ai = 0; ai < 2; ++ai)
; #pragma unroll
;             for (int m = 0; m < 4; ++m) { const int rowg = u.pm * BM + ai * HALF + wr * 64 + m * 16;
;                 const float sc = slots ? rstd_from_slots(slots, rowg + fr, fq) : 1.0f;
;                 u32x4 w[2];
; #pragma unroll
;                 for (int bj = 0; bj < 2; ++bj) { const f32x4 v0 = acc[ai][bj][m][0] * sc, v1 = acc[ai][bj][m][1] * sc;
;                     w[bj].x = cvt_pk_bf16(v0[0], v0[1]); w[bj].y = cvt_pk_bf16(v0[2], v0[3]); w[bj].z = cvt_pk_bf16(v1[0], v1[1]); w[bj].w = cvt_pk_bf16(v1[2], v1[3]); }
;                 wide_store(O, ldc, rowg, col0, fr, w[0], w[1]); }
;     }
;     __device__ __forceinline__ void operator()(const f32x4 (&acc)[2][2][4][2], const Unit& u, int wr, int wc, int fr, int fq) const {
;         const int col0 = u.pn * BM + wc * 64 + 8 * fq;
; #pragma unroll
;         for (int ai = 0; ai < 2; ++ai)
; #pragma unroll
;             for (int m = 0; m < 4; ++m) { const int rowg = u.pm * BM + ai * HALF + wr * 64 + m * 16, row = rowg + fr; const size_t off = (size_t)row * 1024 + col0;
;                 u32x4 w[2]; float ss = 0.f;
; #pragma unroll
;                 for (int bj = 0; bj < 2; ++bj) { f32x4 b0, b1;
;                     if (BASE_F32) { const float* bp = (const float*)base + off + 32 * bj; b0 = *(const f32x4*)bp; b1 = *(const f32x4*)(bp + 4); }
;                     else { const u32x4 bb = *(const u32x4*)((const bf16_t*)base + off + 32 * bj);
.LBB0_590:
	s_or_b64 exec, exec, s[20:21]
	v_cvt_pk_bf16_f32 v120, v120, v121
	v_cvt_pk_bf16_f32 v116, v116, v117
	v_cvt_pk_bf16_f32 v117, v118, v119
	v_cvt_pk_bf16_f32 v118, v112, v113
	v_cvt_pk_bf16_f32 v124, v124, v125
	v_cvt_pk_bf16_f32 v125, v126, v127
	v_cvt_pk_bf16_f32 v121, v122, v123
	v_cvt_pk_bf16_f32 v119, v114, v115
	v_cndmask_b32_e64 v113, v120, v118, s[4:5]
	v_mov_b32_e32 v126, v137
	v_cndmask_b32_e64 v112, v121, v119, s[4:5]
	v_cndmask_b32_e64 v114, v125, v117, s[4:5]
	v_mov_b32_e32 v123, v137
	v_mov_b32_dpp v126, v113 row_ror:8 row_mask:0xf bank_mask:0xf
	v_mov_b32_e32 v127, v137
	v_cndmask_b32_e64 v115, v124, v116, s[4:5]
	v_mov_b32_e32 v122, v137
	v_mov_b32_dpp v123, v114 row_ror:8 row_mask:0xf bank_mask:0xf
	v_mov_b32_dpp v127, v112 row_ror:8 row_mask:0xf bank_mask:0xf
	v_cndmask_b32_e64 v114, v126, v120, s[4:5]
	v_or_b32_e32 v120, s19, v151
	v_mov_b32_dpp v122, v115 row_ror:8 row_mask:0xf bank_mask:0xf
	v_cndmask_b32_e64 v115, v127, v121, s[4:5]
	v_ashrrev_i32_e32 v121, 31, v120
	v_lshlrev_b64 v[120:121], 11, v[120:121]
	v_lshl_add_u64 v[120:121], s[30:31], 0, v[120:121]
	v_lshl_add_u64 v[120:121], v[146:147], 1, v[120:121]
	v_cndmask_b32_e64 v113, v123, v125, s[4:5]
	v_cndmask_b32_e64 v112, v122, v124, s[4:5]
	v_lshl_add_u64 v[120:121], v[120:121], 0, v[136:137]
	s_cmp_lg_u64 s[16:17], 0
	s_cbranch_scc0 .LBB0_588
	s_barrier
.LBB0_588:
	global_store_dwordx4 v[120:121], v[112:115], off nt
	v_cndmask_b32_e64 v119, v119, v127, s[4:5]
	v_cndmask_b32_e64 v118, v118, v126, s[4:5]
	v_add_co_u32_e32 v112, vcc, s52, v120
	v_cndmask_b32_e64 v117, v117, v123, s[4:5]
	v_cndmask_b32_e64 v116, v116, v122, s[4:5]
	v_addc_co_u32_e32 v113, vcc, 0, v121, vcc
	s_or_b32 s22, s19, 16
	global_store_dwordx4 v[112:113], v[116:119], off nt
	v_or_b32_e32 v112, s22, v150
	v_ashrrev_i32_e32 v113, 31, v112
	v_readlane_b32 s64, v239, 10
	v_lshlrev_b64 v[114:115], 12, v[112:113]
	v_readlane_b32 s65, v239, 11
	v_readlane_b32 s66, v239, 12
	v_readlane_b32 s67, v239, 13
	v_lshl_add_u64 v[114:115], s[64:65], 0, v[114:115]
	v_lshl_add_u64 v[126:127], v[146:147], 2, v[114:115]
	global_load_dwordx4 v[114:117], v[126:127], off
	global_load_dwordx4 v[118:121], v[126:127], off offset:16
	global_load_dwordx4 v[122:125], v[126:127], off offset:128
	s_waitcnt lgkmcnt(0)
	global_load_dwordx4 v[164:167], v[126:127], off offset:144
	v_readlane_b32 s68, v239, 14
	v_readlane_b32 s69, v239, 15
	v_readlane_b32 s70, v239, 16
	v_readlane_b32 s71, v239, 17
	v_readlane_b32 s72, v239, 18
	v_readlane_b32 s73, v239, 19
	v_readlane_b32 s74, v239, 20
	v_readlane_b32 s75, v239, 21
	v_readlane_b32 s76, v239, 22
	v_readlane_b32 s77, v239, 23
	v_readlane_b32 s78, v239, 24
	v_readlane_b32 s79, v239, 25
	s_waitcnt vmcnt(3)
	v_pk_add_f32 v[110:111], v[110:111], v[116:117]
	v_pk_add_f32 v[108:109], v[108:109], v[114:115]
	s_waitcnt vmcnt(2)
	v_pk_add_f32 v[106:107], v[106:107], v[120:121]
	v_pk_add_f32 v[104:105], v[104:105], v[118:119]
	s_waitcnt vmcnt(1)
	v_pk_add_f32 v[102:103], v[102:103], v[124:125]
	v_pk_add_f32 v[100:101], v[100:101], v[122:123]
	s_waitcnt vmcnt(0)
	v_pk_add_f32 v[98:99], v[98:99], v[166:167]
	v_pk_add_f32 v[96:97], v[96:97], v[164:165]
	v_mul_f32_e32 v114, v109, v109
	v_mul_f32_e32 v115, v111, v111
	v_mul_f32_e32 v116, v105, v105
	v_mul_f32_e32 v117, v107, v107
	v_mul_f32_e32 v118, v101, v101
	v_mul_f32_e32 v119, v103, v103
	v_mul_f32_e32 v120, v97, v97
	v_mul_f32_e32 v121, v99, v99
	v_fmac_f32_e32 v114, v108, v108
	v_fmac_f32_e32 v115, v110, v110
	v_fmac_f32_e32 v116, v104, v104
	v_fmac_f32_e32 v117, v106, v106
	v_fmac_f32_e32 v118, v100, v100
	v_fmac_f32_e32 v119, v102, v102
	v_fmac_f32_e32 v120, v96, v96
	v_fmac_f32_e32 v121, v98, v98
	v_add_f32_e32 v114, v114, v115
	v_add_f32_e32 v115, v116, v117
	v_add_f32_e32 v116, v118, v119
	v_add_f32_e32 v117, v120, v121
	v_add_f32_e32 v114, v114, v115
	v_add_f32_e32 v115, v116, v117
	v_add_f32_e32 v114, v114, v115
	ds_bpermute_b32 v115, v161, v114
	s_waitcnt lgkmcnt(0)
	v_add_f32_e32 v114, v114, v115
	ds_bpermute_b32 v115, v162, v114
	s_and_saveexec_b64 s[20:21], s[2:3]
	s_cbranch_execz .LBB0_592
	v_lshlrev_b64 v[112:113], 6, v[112:113]
	v_lshl_add_u64 v[112:113], s[82:83], 0, v[112:113]
	v_lshl_add_u64 v[112:113], s[0:1], 2, v[112:113]
	s_lshl_b32 s10, s55, 2
	v_lshl_add_u64 v[112:113], v[112:113], 0, s[10:11]
	s_waitcnt lgkmcnt(0)
	v_add_f32_e32 v114, v114, v115
	global_store_dword v[112:113], v114, off

; #define PG8_STAGE(bufoff, gbase, voff) do { _Pragma("unroll") for (int _i = 0; _i < 2; ++_i) \
;         __builtin_amdgcn_global_load_lds((const unsigned*)((const char*)(gbase) + (voff)[_i]), (PG8_LAS unsigned*)(lds + (bufoff) + ldsw + _i * 8192), 16, 0, PG8_LOAD_AUX); } while (0)
; #define PG8_LDA(dst, b, h) do { _Pragma("unroll") for (int m = 0; m < 4; ++m) _Pragma("unroll") for (int k = 0; k < 2; ++k) dst[m][k] = *(const PG8_LAS bf16x8*)(lds + PG8_SA(b, h) + aoff + m * 2048 + k * 1024); } while (0)
; #define PG8_LDB(dst, b, h) do { _Pragma("unroll") for (int n = 0; n < 2; ++n) _Pragma("unroll") for (int k = 0; k < 2; ++k) dst[n][k] = *(const PG8_LAS bf16x8*)(lds + PG8_SB(b, h) + boff + n * 2048 + k * 1024); } while (0)
; #define PG8_MMA(ai, bj, At, Bt) do { __builtin_amdgcn_s_setprio(1); _Pragma("unroll") for (int m = 0; m < 4; ++m) _Pragma("unroll") for (int n = 0; n < 2; ++n) _Pragma("unroll") for (int k = 0; k < 2; ++k) \
;         acc[ai][bj][m][n] = __builtin_amdgcn_mfma_f32_16x16x32_bf16(Bt[n][k], At[m][k], acc[ai][bj][m][n], 0, 0, 0); __builtin_amdgcn_s_setprio(0); } while (0)
; #define PG8_WAIT_V(n) asm volatile("s_waitcnt vmcnt(" #n ")" ::: "memory")
; #define PG8_WAIT_L(n) asm volatile("s_waitcnt lgkmcnt(" #n ")" ::: "memory")
; #define PG8_BAR __builtin_amdgcn_s_barrier()
; #define PG8_SCHED __builtin_amdgcn_sched_barrier(0)
; template <class Epi, class Sched, bool ALIGN_EPI = false, bool SP2 = false>
; __device__ __forceinline__ void gemm_phase(PG8_LAS unsigned char* lds, const Gemm g, const Sched& S, const Epi& E) {
;     ...
;             PG8_LDB(B0, 1, 0); PG8_LDB(B1, 1, 1); PG8_SCHED; PG8_LDA(At, 1, 0); PG8_STAGE(PG8_SA(0, 1), a2 + hstepA, voffA);
;             PG8_WAIT_V(8); PG8_WAIT_L(0); PG8_BAR; PG8_MMA(0, 0, At, B0); PG8_MMA(0, 1, At, B1); PG8_BAR; PG8_SCHED;
;             PG8_LDA(At, 1, 1); PG8_STAGE(PG8_SB(1, 0), b3, voffB); PG8_STAGE(PG8_SB(1, 1), b3 + hstepB, voffB); PG8_STAGE(PG8_SA(1, 0), a3, voffA);
;             PG8_WAIT_V(8); PG8_WAIT_L(0); PG8_BAR; PG8_MMA(1, 0, At, B0); PG8_MMA(1, 1, At, B1); PG8_BAR; PG8_SCHED;
.Lkmid_P7:
	s_add_i32 s29, 0, 0x18000
	v_add_u32_e32 v163, s29, v156
	s_add_i32 s33, 0, 0x1c000
	ds_read_b128 v[146:149], v163
	ds_read_b128 v[164:167], v163 offset:1024
	ds_read_b128 v[168:171], v163 offset:2048
	ds_read_b128 v[172:175], v163 offset:3072
	v_add_u32_e32 v163, s33, v156
	ds_read_b128 v[176:179], v163
	ds_read_b128 v[180:183], v163 offset:1024
	ds_read_b128 v[184:187], v163 offset:2048
	ds_read_b128 v[188:191], v163 offset:3072
	s_add_u32 s30, s34, 0x40000
	s_addc_u32 s31, s35, 0
	s_mov_b32 m0, s47
	v_lshl_add_u64 v[230:231], s[30:31], 0, v[128:129]
	ds_read_b128 v[192:195], v160 offset:32768
	ds_read_b128 v[196:199], v160 offset:33792
	ds_read_b128 v[200:203], v160 offset:34816
	ds_read_b128 v[204:207], v160 offset:35840
	ds_read_b128 v[208:211], v160 offset:36864
	ds_read_b128 v[212:215], v160 offset:37888
	ds_read_b128 v[216:219], v160 offset:38912
	ds_read_b128 v[220:223], v160 offset:39936
	global_load_lds_dwordx4 v[230:231], off
	v_lshl_add_u64 v[230:231], s[30:31], 0, v[132:133]
	s_mov_b32 m0, s48
	s_nop 0
	global_load_lds_dwordx4 v[230:231], off
	s_waitcnt vmcnt(8)
	s_waitcnt lgkmcnt(0)
	s_barrier
	s_setprio 1
	s_waitcnt lgkmcnt(0)
	v_mfma_f32_16x16x32_bf16 v[124:127], v[146:149], v[192:195], v[124:127]
	v_mfma_f32_16x16x32_bf16 v[120:123], v[168:171], v[192:195], v[120:123]
	v_mfma_f32_16x16x32_bf16 v[108:111], v[146:149], v[200:203], v[108:111]
	v_mfma_f32_16x16x32_bf16 v[104:107], v[168:171], v[200:203], v[104:107]
	v_mfma_f32_16x16x32_bf16 v[92:95], v[146:149], v[208:211], v[92:95]
	v_mfma_f32_16x16x32_bf16 v[88:91], v[168:171], v[208:211], v[88:91]
	v_mfma_f32_16x16x32_bf16 v[76:79], v[146:149], v[216:219], v[76:79]
	v_mfma_f32_16x16x32_bf16 v[72:75], v[168:171], v[216:219], v[72:75]
	v_mfma_f32_16x16x32_bf16 v[124:127], v[164:167], v[196:199], v[124:127]
	v_mfma_f32_16x16x32_bf16 v[120:123], v[172:175], v[196:199], v[120:123]
	v_mfma_f32_16x16x32_bf16 v[108:111], v[164:167], v[204:207], v[108:111]
	v_mfma_f32_16x16x32_bf16 v[104:107], v[172:175], v[204:207], v[104:107]
	v_mfma_f32_16x16x32_bf16 v[92:95], v[164:167], v[212:215], v[92:95]
	v_mfma_f32_16x16x32_bf16 v[88:91], v[172:175], v[212:215], v[88:91]
	v_mfma_f32_16x16x32_bf16 v[76:79], v[164:167], v[220:223], v[76:79]
	v_mfma_f32_16x16x32_bf16 v[72:75], v[172:175], v[220:223], v[72:75]
	s_setprio 0
	s_setprio 1
	v_mfma_f32_16x16x32_bf16 v[116:119], v[176:179], v[192:195], v[116:119]
	v_mfma_f32_16x16x32_bf16 v[112:115], v[184:187], v[192:195], v[112:115]
	v_mfma_f32_16x16x32_bf16 v[100:103], v[176:179], v[200:203], v[100:103]
	v_mfma_f32_16x16x32_bf16 v[96:99], v[184:187], v[200:203], v[96:99]
	v_mfma_f32_16x16x32_bf16 v[84:87], v[176:179], v[208:211], v[84:87]
	v_mfma_f32_16x16x32_bf16 v[80:83], v[184:187], v[208:211], v[80:83]
	v_mfma_f32_16x16x32_bf16 v[68:71], v[176:179], v[216:219], v[68:71]
	v_mfma_f32_16x16x32_bf16 v[64:67], v[184:187], v[216:219], v[64:67]
	v_mfma_f32_16x16x32_bf16 v[116:119], v[180:183], v[196:199], v[116:119]
	v_mfma_f32_16x16x32_bf16 v[112:115], v[188:191], v[196:199], v[112:115]
	v_mfma_f32_16x16x32_bf16 v[100:103], v[180:183], v[204:207], v[100:103]
	v_mfma_f32_16x16x32_bf16 v[96:99], v[188:191], v[204:207], v[96:99]
	v_mfma_f32_16x16x32_bf16 v[84:87], v[180:183], v[212:215], v[84:87]
	v_mfma_f32_16x16x32_bf16 v[80:83], v[188:191], v[212:215], v[80:83]
	v_mfma_f32_16x16x32_bf16 v[68:71], v[180:183], v[220:223], v[68:71]
	v_mfma_f32_16x16x32_bf16 v[64:67], v[188:191], v[220:223], v[64:67]
	s_setprio 0
	s_barrier
	s_add_i32 s29, s29, s40
	v_lshl_add_u64 v[150:151], v[150:151], 0, s[8:9]
	s_mov_b32 m0, s29
	ds_read_b128 v[192:195], v160 offset:49152
	ds_read_b128 v[196:199], v160 offset:50176
	ds_read_b128 v[200:203], v160 offset:51200
	ds_read_b128 v[204:207], v160 offset:52224
	ds_read_b128 v[208:211], v160 offset:53248
	ds_read_b128 v[212:215], v160 offset:54272
	ds_read_b128 v[216:219], v160 offset:55296
	ds_read_b128 v[220:223], v160 offset:56320
	global_load_lds_dwordx4 v[150:151], off
	s_add_i32 m0, s29, 0x2000
	s_add_u32 s22, s22, 0x40080
	v_lshl_add_u64 v[150:151], v[224:225], 0, s[8:9]
	s_addc_u32 s23, s23, 0
	s_add_i32 s29, s33, s40
	global_load_lds_dwordx4 v[150:151], off
	v_lshl_add_u64 v[150:151], s[22:23], 0, v[130:131]
	s_mov_b32 m0, s29
	s_nop 0
	global_load_lds_dwordx4 v[150:151], off
	v_lshl_add_u64 v[150:151], s[22:23], 0, v[134:135]
	s_add_i32 m0, s29, 0x2000
	s_nop 0
	global_load_lds_dwordx4 v[150:151], off
	v_lshl_add_u64 v[150:151], v[226:227], 0, s[8:9]
	s_mov_b32 m0, s51
	s_nop 0
	global_load_lds_dwordx4 v[150:151], off
	v_lshl_add_u64 v[150:151], v[228:229], 0, s[8:9]
	s_mov_b32 m0, s52
	s_nop 0
	global_load_lds_dwordx4 v[150:151], off
	s_waitcnt vmcnt(8)
	s_waitcnt lgkmcnt(0)
	s_barrier
; __device__ __forceinline__ unsigned cvt_pk_bf16(float lo, float hi) { const cvt_f32x2_t v = {lo, hi}; const cvt_bf16x2_t b = __builtin_convertvector(v, cvt_bf16x2_t); return __builtin_bit_cast(unsigned, b); }
; __device__ __forceinline__ float rstd_from_slots(const float* slots, int row, int fq) {
;     const f32x4 s4 = *(const f32x4*)(slots + (size_t)row * 16 + 4 * fq);
;     float s = (s4[0] + s4[1]) + (s4[2] + s4[3]);
;     s += __shfl_xor(s, 16); s += __shfl_xor(s, 32);
;     return __builtin_amdgcn_rsqf(s * (1.0f / 1024.0f) + RMS_EPS_F);
; __device__ __forceinline__ float silu_mul(float g, float u) { return g * u * __builtin_amdgcn_rcpf(1.0f + __builtin_amdgcn_exp2f(g * -1.4426950408889634f)); }
;     __device__ __forceinline__ void operator()(const f32x4 (&acc)[2][2][4][2], const Unit& u, int wr, int wc, int fr, int fq) const {
;         const int row0 = u.pm * BM + wr * 64 + fr; const int col0 = u.pn * HALF + wc * 32 + 8 * fq;
; #pragma unroll
;         for (int ai = 0; ai < 2; ++ai)
; #pragma unroll
;             for (int m = 0; m < 4; ++m) { const int row = row0 + ai * HALF + m * 16;
;                 const float sc = rstd_from_slots(slots, row, fq);
;                 const f32x4 g0 = acc[ai][0][m][0] * sc, g1 = acc[ai][0][m][1] * sc, u0 = acc[ai][1][m][0] * sc, u1 = acc[ai][1][m][1] * sc;
;                 u32x4 w; w.x = cvt_pk_bf16(silu_mul(g0[0], u0[0]), silu_mul(g0[1], u0[1])); w.y = cvt_pk_bf16(silu_mul(g0[2], u0[2]), silu_mul(g0[3], u0[3]));
;                 w.z = cvt_pk_bf16(silu_mul(g1[0], u1[0]), silu_mul(g1[1], u1[1])); w.w = cvt_pk_bf16(silu_mul(g1[2], u1[2]), silu_mul(g1[3], u1[3]));
;                 __builtin_nontemporal_store(w, (u32x4*)(O + (size_t)row * ldc + col0)); }
	s_setprio 1
	s_waitcnt lgkmcnt(0)
	v_mfma_f32_16x16x32_bf16 v[60:63], v[146:149], v[192:195], v[60:63]
	v_mfma_f32_16x16x32_bf16 v[56:59], v[168:171], v[192:195], v[56:59]
	v_mfma_f32_16x16x32_bf16 v[44:47], v[146:149], v[200:203], v[44:47]
	v_mfma_f32_16x16x32_bf16 v[40:43], v[168:171], v[200:203], v[40:43]
	v_mfma_f32_16x16x32_bf16 v[28:31], v[146:149], v[208:211], v[28:31]
	v_mfma_f32_16x16x32_bf16 v[24:27], v[168:171], v[208:211], v[24:27]
	v_mfma_f32_16x16x32_bf16 v[12:15], v[146:149], v[216:219], v[12:15]
	v_mfma_f32_16x16x32_bf16 v[8:11], v[168:171], v[216:219], v[8:11]
	v_mfma_f32_16x16x32_bf16 v[60:63], v[164:167], v[196:199], v[60:63]
	v_mfma_f32_16x16x32_bf16 v[56:59], v[172:175], v[196:199], v[56:59]
	v_mfma_f32_16x16x32_bf16 v[44:47], v[164:167], v[204:207], v[44:47]
	v_mfma_f32_16x16x32_bf16 v[40:43], v[172:175], v[204:207], v[40:43]
	v_mfma_f32_16x16x32_bf16 v[28:31], v[164:167], v[212:215], v[28:31]
	v_mfma_f32_16x16x32_bf16 v[24:27], v[172:175], v[212:215], v[24:27]
	v_mfma_f32_16x16x32_bf16 v[12:15], v[164:167], v[220:223], v[12:15]
	v_mfma_f32_16x16x32_bf16 v[8:11], v[172:175], v[220:223], v[8:11]
	s_setprio 0
	s_setprio 1
	v_mfma_f32_16x16x32_bf16 v[52:55], v[176:179], v[192:195], v[52:55]
	v_mfma_f32_16x16x32_bf16 v[48:51], v[184:187], v[192:195], v[48:51]
	v_mfma_f32_16x16x32_bf16 v[36:39], v[176:179], v[200:203], v[36:39]
	v_mfma_f32_16x16x32_bf16 v[32:35], v[184:187], v[200:203], v[32:35]
	v_mfma_f32_16x16x32_bf16 v[20:23], v[176:179], v[208:211], v[20:23]
	v_mfma_f32_16x16x32_bf16 v[16:19], v[184:187], v[208:211], v[16:19]
	v_mfma_f32_16x16x32_bf16 v[4:7], v[176:179], v[216:219], v[4:7]
	v_mfma_f32_16x16x32_bf16 v[0:3], v[184:187], v[216:219], v[0:3]
	v_mfma_f32_16x16x32_bf16 v[52:55], v[180:183], v[196:199], v[52:55]
	v_mfma_f32_16x16x32_bf16 v[48:51], v[188:191], v[196:199], v[48:51]
	v_mfma_f32_16x16x32_bf16 v[36:39], v[180:183], v[204:207], v[36:39]
	v_mfma_f32_16x16x32_bf16 v[32:35], v[188:191], v[204:207], v[32:35]
	v_mfma_f32_16x16x32_bf16 v[20:23], v[180:183], v[212:215], v[20:23]
	v_mfma_f32_16x16x32_bf16 v[16:19], v[188:191], v[212:215], v[16:19]
	v_mfma_f32_16x16x32_bf16 v[4:7], v[180:183], v[220:223], v[4:7]
	v_mfma_f32_16x16x32_bf16 v[0:3], v[188:191], v[220:223], v[0:3]
	s_setprio 0
	s_barrier
	s_add_i32 s28, s28, 2
	s_add_u32 s20, s20, 0x100
	s_addc_u32 s21, s21, 0
	s_add_u32 s26, s26, 0x100
	s_addc_u32 s27, s27, 0
	s_cmp_gt_u32 s28, 13
	s_cbranch_scc0 .LBB0_672
	v_lshl_add_u32 v204, s0, 8, v152
	v_ashrrev_i32_e32 v205, 31, v204
	v_lshlrev_b64 v[204:205], 6, v[204:205]
	v_lshl_add_u64 v[204:205], v[136:137], 0, v[204:205]
	v_add_co_u32_e32 v206, vcc, 0x2000, v204
	s_nop 1
	v_addc_co_u32_e32 v207, vcc, 0, v205, vcc
	global_load_dwordx4 v[172:175], v[204:205], off
	global_load_dwordx4 v[176:179], v[204:205], off offset:1024
	global_load_dwordx4 v[180:183], v[204:205], off offset:2048
	global_load_dwordx4 v[184:187], v[204:205], off offset:3072
	global_load_dwordx4 v[188:191], v[206:207], off
	global_load_dwordx4 v[192:195], v[206:207], off offset:1024
	global_load_dwordx4 v[196:199], v[206:207], off offset:2048
	global_load_dwordx4 v[200:203], v[206:207], off offset:3072
	v_lshl_add_u32 v150, s0, 8, v152
	v_ashrrev_i32_e32 v151, 31, v150
	v_lshlrev_b64 v[146:147], 6, v[150:151]
	v_lshl_add_u64 v[146:147], v[136:137], 0, v[146:147]
	v_and_b32_e32 v151, 64, v161
	v_xor_b32_e32 v149, 16, v161
	v_add_u32_e32 v170, 64, v151
	v_cmp_lt_i32_e32 vcc, v149, v170
	v_xor_b32_e32 v163, 32, v161
	v_lshl_or_b32 v148, s1, 7, v157
	v_cndmask_b32_e32 v149, v161, v149, vcc
	v_lshlrev_b32_e32 v151, 2, v149
	v_cmp_lt_i32_e32 vcc, v163, v170
	v_mov_b64_e32 v[146:147], s[10:11]
	v_ashrrev_i32_e32 v149, 31, v148
	v_cndmask_b32_e32 v163, v161, v163, vcc
	v_lshlrev_b32_e32 v163, 2, v163
	v_lshlrev_b64 v[148:149], 1, v[148:149]
	s_andn2_b64 vcc, exec, s[2:3]
	s_waitcnt vmcnt(7)
	v_mov_b32_e32 v164, v172
	v_mov_b32_e32 v165, v173
	v_mov_b32_e32 v166, v174
	v_mov_b32_e32 v167, v175
	v_mov_b32_e32 v168, v165
	v_mov_b32_e32 v169, v166
	v_mov_b32_e32 v165, v167
	v_pk_add_f32 v[164:165], v[168:169], v[164:165]
	v_or_b32_e32 v166, 16, v150
	v_add_f32_e32 v164, v164, v165
	ds_bpermute_b32 v165, v151, v164
	v_ashrrev_i32_e32 v167, 31, v166
	v_lshlrev_b64 v[170:171], 6, v[166:167]
	v_lshl_add_u64 v[170:171], v[136:137], 0, v[170:171]
	s_waitcnt lgkmcnt(0)
	v_add_f32_e32 v168, v164, v165
	ds_bpermute_b32 v169, v163, v168
	v_mad_i64_i32 v[164:165], s[0:1], v150, s56, v[146:147]
	v_lshl_add_u64 v[164:165], v[164:165], 0, v[148:149]
	s_waitcnt lgkmcnt(0)
	v_add_f32_e32 v168, v168, v169
	v_fmamk_f32 v168, v168, 0x3a800000, v162
	v_rsq_f32_e32 v168, v168
	s_nop 0
	v_pk_mul_f32 v[126:127], v[126:127], v[168:169] op_sel_hi:[1,0]
	v_pk_mul_f32 v[124:125], v[124:125], v[168:169] op_sel_hi:[1,0]
	v_pk_mul_f32 v[122:123], v[122:123], v[168:169] op_sel_hi:[1,0]
	v_pk_mul_f32 v[120:121], v[120:121], v[168:169] op_sel_hi:[1,0]
	v_pk_mul_f32 v[116:117], v[116:117], v[168:169] op_sel_hi:[1,0]
	v_pk_mul_f32 v[118:119], v[118:119], v[168:169] op_sel_hi:[1,0]
	v_pk_mul_f32 v[112:113], v[112:113], v[168:169] op_sel_hi:[1,0]
	v_pk_mul_f32 v[114:115], v[114:115], v[168:169] op_sel_hi:[1,0]
	v_mul_f32_e32 v167, 0xbfb8aa3b, v124
	v_mul_f32_e32 v168, 0xbfb8aa3b, v125
	v_pk_mul_f32 v[118:119], v[126:127], v[118:119]
	v_pk_mul_f32 v[116:117], v[124:125], v[116:117]
	v_mul_f32_e32 v124, 0xbfb8aa3b, v126
	v_mul_f32_e32 v125, 0xbfb8aa3b, v127
	v_mul_f32_e32 v126, 0xbfb8aa3b, v120
	v_mul_f32_e32 v127, 0xbfb8aa3b, v121
	v_pk_mul_f32 v[112:113], v[120:121], v[112:113]
	v_mul_f32_e32 v120, 0xbfb8aa3b, v122
	v_mul_f32_e32 v121, 0xbfb8aa3b, v123
	v_pk_mul_f32 v[114:115], v[122:123], v[114:115]
	v_exp_f32_e32 v122, v167
	v_exp_f32_e32 v123, v168
	v_exp_f32_e32 v124, v124
	v_exp_f32_e32 v125, v125
	v_exp_f32_e32 v126, v126
	v_exp_f32_e32 v127, v127
	v_exp_f32_e32 v120, v120
	v_exp_f32_e32 v121, v121
	v_add_f32_e32 v122, 1.0, v122
	v_add_f32_e32 v123, 1.0, v123
	v_add_f32_e32 v124, 1.0, v124
	v_add_f32_e32 v125, 1.0, v125
	v_add_f32_e32 v126, 1.0, v126
	v_add_f32_e32 v127, 1.0, v127
	v_add_f32_e32 v167, 1.0, v120
	v_add_f32_e32 v168, 1.0, v121
	v_rcp_f32_e32 v120, v122
	v_rcp_f32_e32 v121, v123
	v_rcp_f32_e32 v122, v124
	v_rcp_f32_e32 v123, v125
	v_rcp_f32_e32 v124, v126
	v_rcp_f32_e32 v125, v127
	v_rcp_f32_e32 v126, v167
	v_rcp_f32_e32 v127, v168
	v_pk_mul_f32 v[116:117], v[116:117], v[120:121]
	v_pk_mul_f32 v[118:119], v[118:119], v[122:123]
	v_pk_mul_f32 v[120:121], v[112:113], v[124:125]
	v_pk_mul_f32 v[122:123], v[114:115], v[126:127]
	v_cvt_pk_bf16_f32 v112, v116, v117
	v_cvt_pk_bf16_f32 v113, v118, v119
	v_cvt_pk_bf16_f32 v114, v120, v121
	v_cvt_pk_bf16_f32 v115, v122, v123
	s_cmp_lg_u64 s[12:13], 0
	s_cbranch_scc0 .LBB0_675
	s_barrier
; __device__ __forceinline__ unsigned cvt_pk_bf16(float lo, float hi) { const cvt_f32x2_t v = {lo, hi}; const cvt_bf16x2_t b = __builtin_convertvector(v, cvt_bf16x2_t); return __builtin_bit_cast(unsigned, b); }
; __device__ __forceinline__ float rstd_from_slots(const float* slots, int row, int fq) {
;     const f32x4 s4 = *(const f32x4*)(slots + (size_t)row * 16 + 4 * fq);
;     float s = (s4[0] + s4[1]) + (s4[2] + s4[3]);
;     s += __shfl_xor(s, 16); s += __shfl_xor(s, 32);
;     return __builtin_amdgcn_rsqf(s * (1.0f / 1024.0f) + RMS_EPS_F);
; __device__ __forceinline__ float silu_mul(float g, float u) { return g * u * __builtin_amdgcn_rcpf(1.0f + __builtin_amdgcn_exp2f(g * -1.4426950408889634f)); }
;     __device__ __forceinline__ void operator()(const f32x4 (&acc)[2][2][4][2], const Unit& u, int wr, int wc, int fr, int fq) const {
;         const int row0 = u.pm * BM + wr * 64 + fr; const int col0 = u.pn * HALF + wc * 32 + 8 * fq;
; #pragma unroll
;         for (int ai = 0; ai < 2; ++ai)
; #pragma unroll
;             for (int m = 0; m < 4; ++m) { const int row = row0 + ai * HALF + m * 16;
;                 const float sc = rstd_from_slots(slots, row, fq);
;                 const f32x4 g0 = acc[ai][0][m][0] * sc, g1 = acc[ai][0][m][1] * sc, u0 = acc[ai][1][m][0] * sc, u1 = acc[ai][1][m][1] * sc;
;                 u32x4 w; w.x = cvt_pk_bf16(silu_mul(g0[0], u0[0]), silu_mul(g0[1], u0[1])); w.y = cvt_pk_bf16(silu_mul(g0[2], u0[2]), silu_mul(g0[3], u0[3]));
;                 w.z = cvt_pk_bf16(silu_mul(g1[0], u1[0]), silu_mul(g1[1], u1[1])); w.w = cvt_pk_bf16(silu_mul(g1[2], u1[2]), silu_mul(g1[3], u1[3]));
;                 __builtin_nontemporal_store(w, (u32x4*)(O + (size_t)row * ldc + col0)); }
.LBB0_675:
	global_store_dwordx4 v[164:165], v[112:115], off nt
	s_nop 1
	s_waitcnt vmcnt(7)
	v_mov_b32_e32 v112, v176
	v_mov_b32_e32 v113, v177
	v_mov_b32_e32 v114, v178
	v_mov_b32_e32 v115, v179
	v_mov_b32_e32 v116, v113
	v_mov_b32_e32 v117, v114
	v_mov_b32_e32 v113, v115
	v_pk_add_f32 v[112:113], v[116:117], v[112:113]
	v_mad_i64_i32 v[114:115], s[0:1], v166, s56, v[146:147]
	v_add_f32_e32 v112, v112, v113
	ds_bpermute_b32 v113, v151, v112
	v_lshl_add_u64 v[114:115], v[114:115], 0, v[148:149]
	s_waitcnt lgkmcnt(0)
	v_add_f32_e32 v116, v112, v113
	ds_bpermute_b32 v117, v163, v116
	v_or_b32_e32 v112, 32, v150
	v_ashrrev_i32_e32 v113, 31, v112
	v_lshlrev_b64 v[118:119], 6, v[112:113]
	v_lshl_add_u64 v[118:119], v[136:137], 0, v[118:119]
	s_waitcnt lgkmcnt(0)
	v_add_f32_e32 v116, v116, v117
	v_fmamk_f32 v116, v116, 0x3a800000, v162
	v_rsq_f32_e32 v116, v116
	s_nop 0
	v_pk_mul_f32 v[110:111], v[110:111], v[116:117] op_sel_hi:[1,0]
	v_pk_mul_f32 v[108:109], v[108:109], v[116:117] op_sel_hi:[1,0]
	v_pk_mul_f32 v[106:107], v[106:107], v[116:117] op_sel_hi:[1,0]
	v_pk_mul_f32 v[104:105], v[104:105], v[116:117] op_sel_hi:[1,0]
	v_pk_mul_f32 v[100:101], v[100:101], v[116:117] op_sel_hi:[1,0]
	v_pk_mul_f32 v[102:103], v[102:103], v[116:117] op_sel_hi:[1,0]
	v_pk_mul_f32 v[96:97], v[96:97], v[116:117] op_sel_hi:[1,0]
	v_pk_mul_f32 v[98:99], v[98:99], v[116:117] op_sel_hi:[1,0]
	v_mul_f32_e32 v113, 0xbfb8aa3b, v108
	v_mul_f32_e32 v116, 0xbfb8aa3b, v109
	v_pk_mul_f32 v[102:103], v[110:111], v[102:103]
	v_pk_mul_f32 v[100:101], v[108:109], v[100:101]
	v_mul_f32_e32 v108, 0xbfb8aa3b, v110
	v_mul_f32_e32 v109, 0xbfb8aa3b, v111
	v_mul_f32_e32 v110, 0xbfb8aa3b, v104
	v_mul_f32_e32 v111, 0xbfb8aa3b, v105
	v_pk_mul_f32 v[96:97], v[104:105], v[96:97]
	v_mul_f32_e32 v104, 0xbfb8aa3b, v106
	v_mul_f32_e32 v105, 0xbfb8aa3b, v107
	v_pk_mul_f32 v[98:99], v[106:107], v[98:99]
	v_exp_f32_e32 v106, v113
	v_exp_f32_e32 v107, v116
	v_exp_f32_e32 v108, v108
	v_exp_f32_e32 v109, v109
	v_exp_f32_e32 v110, v110
	v_exp_f32_e32 v111, v111
	v_exp_f32_e32 v104, v104
	v_exp_f32_e32 v105, v105
	v_add_f32_e32 v106, 1.0, v106
	v_add_f32_e32 v107, 1.0, v107
	v_add_f32_e32 v108, 1.0, v108
	v_add_f32_e32 v109, 1.0, v109
	v_add_f32_e32 v110, 1.0, v110
	v_add_f32_e32 v111, 1.0, v111
	v_add_f32_e32 v113, 1.0, v104
	v_add_f32_e32 v116, 1.0, v105
	v_rcp_f32_e32 v104, v106
	v_rcp_f32_e32 v105, v107
	v_rcp_f32_e32 v106, v108
	v_rcp_f32_e32 v107, v109
	v_rcp_f32_e32 v108, v110
	v_rcp_f32_e32 v109, v111
	v_rcp_f32_e32 v110, v113
	v_rcp_f32_e32 v111, v116
	v_pk_mul_f32 v[100:101], v[100:101], v[104:105]
	v_pk_mul_f32 v[102:103], v[102:103], v[106:107]
	v_pk_mul_f32 v[104:105], v[96:97], v[108:109]
	v_pk_mul_f32 v[106:107], v[98:99], v[110:111]
	v_cvt_pk_bf16_f32 v96, v100, v101
	v_cvt_pk_bf16_f32 v97, v102, v103
	v_cvt_pk_bf16_f32 v98, v104, v105
	v_cvt_pk_bf16_f32 v99, v106, v107
	global_store_dwordx4 v[114:115], v[96:99], off nt
	s_nop 1
	s_waitcnt vmcnt(7)
	v_mov_b32_e32 v96, v180
	v_mov_b32_e32 v97, v181
	v_mov_b32_e32 v98, v182
	v_mov_b32_e32 v99, v183
	v_mov_b32_e32 v100, v97
	v_mov_b32_e32 v101, v98
	v_mov_b32_e32 v97, v99
	v_pk_add_f32 v[96:97], v[100:101], v[96:97]
	v_mad_i64_i32 v[98:99], s[0:1], v112, s56, v[146:147]
	v_add_f32_e32 v96, v96, v97
	ds_bpermute_b32 v97, v151, v96
	v_lshl_add_u64 v[98:99], v[98:99], 0, v[148:149]
	s_waitcnt lgkmcnt(0)
	v_add_f32_e32 v100, v96, v97
	ds_bpermute_b32 v101, v163, v100
	v_or_b32_e32 v96, 48, v150
	v_ashrrev_i32_e32 v97, 31, v96
	v_lshlrev_b64 v[102:103], 6, v[96:97]
	v_lshl_add_u64 v[102:103], v[136:137], 0, v[102:103]
	s_waitcnt lgkmcnt(0)
	v_add_f32_e32 v100, v100, v101
	v_fmamk_f32 v100, v100, 0x3a800000, v162
	v_rsq_f32_e32 v100, v100
	s_nop 0
	v_pk_mul_f32 v[94:95], v[94:95], v[100:101] op_sel_hi:[1,0]
	v_pk_mul_f32 v[92:93], v[92:93], v[100:101] op_sel_hi:[1,0]
	v_pk_mul_f32 v[90:91], v[90:91], v[100:101] op_sel_hi:[1,0]
	v_pk_mul_f32 v[88:89], v[88:89], v[100:101] op_sel_hi:[1,0]
	v_pk_mul_f32 v[84:85], v[84:85], v[100:101] op_sel_hi:[1,0]
	v_pk_mul_f32 v[86:87], v[86:87], v[100:101] op_sel_hi:[1,0]
	v_pk_mul_f32 v[80:81], v[80:81], v[100:101] op_sel_hi:[1,0]
	v_pk_mul_f32 v[82:83], v[82:83], v[100:101] op_sel_hi:[1,0]
	v_mul_f32_e32 v97, 0xbfb8aa3b, v92
	v_mul_f32_e32 v100, 0xbfb8aa3b, v93
	v_pk_mul_f32 v[86:87], v[94:95], v[86:87]
	v_pk_mul_f32 v[84:85], v[92:93], v[84:85]
	v_mul_f32_e32 v92, 0xbfb8aa3b, v94
	v_mul_f32_e32 v93, 0xbfb8aa3b, v95
	v_mul_f32_e32 v94, 0xbfb8aa3b, v88
	v_mul_f32_e32 v95, 0xbfb8aa3b, v89
	v_pk_mul_f32 v[80:81], v[88:89], v[80:81]
	v_mul_f32_e32 v88, 0xbfb8aa3b, v90
	v_mul_f32_e32 v89, 0xbfb8aa3b, v91
	v_pk_mul_f32 v[82:83], v[90:91], v[82:83]
	v_exp_f32_e32 v90, v97
	v_exp_f32_e32 v91, v100
	v_exp_f32_e32 v92, v92
	v_exp_f32_e32 v93, v93
	v_exp_f32_e32 v94, v94
	v_exp_f32_e32 v95, v95
	v_exp_f32_e32 v88, v88
	v_exp_f32_e32 v89, v89
	v_add_f32_e32 v90, 1.0, v90
	v_add_f32_e32 v91, 1.0, v91
	v_add_f32_e32 v92, 1.0, v92
	v_add_f32_e32 v93, 1.0, v93
	v_add_f32_e32 v94, 1.0, v94
	v_add_f32_e32 v95, 1.0, v95
	v_add_f32_e32 v97, 1.0, v88
	v_add_f32_e32 v100, 1.0, v89
	v_rcp_f32_e32 v88, v90
	v_rcp_f32_e32 v89, v91
	v_rcp_f32_e32 v90, v92
	v_rcp_f32_e32 v91, v93
	v_rcp_f32_e32 v92, v94
	v_rcp_f32_e32 v93, v95
	v_rcp_f32_e32 v94, v97
	v_rcp_f32_e32 v95, v100
	v_pk_mul_f32 v[84:85], v[84:85], v[88:89]
	v_pk_mul_f32 v[86:87], v[86:87], v[90:91]
	v_pk_mul_f32 v[88:89], v[80:81], v[92:93]
	v_pk_mul_f32 v[90:91], v[82:83], v[94:95]
	v_cvt_pk_bf16_f32 v80, v84, v85
	v_cvt_pk_bf16_f32 v81, v86, v87
	v_cvt_pk_bf16_f32 v82, v88, v89
	v_cvt_pk_bf16_f32 v83, v90, v91
	global_store_dwordx4 v[98:99], v[80:83], off nt
	s_nop 1
	s_waitcnt vmcnt(7)
; __device__ __forceinline__ unsigned cvt_pk_bf16(float lo, float hi) { const cvt_f32x2_t v = {lo, hi}; const cvt_bf16x2_t b = __builtin_convertvector(v, cvt_bf16x2_t); return __builtin_bit_cast(unsigned, b); }
; __device__ __forceinline__ float rstd_from_slots(const float* slots, int row, int fq) {
;     const f32x4 s4 = *(const f32x4*)(slots + (size_t)row * 16 + 4 * fq);
;     float s = (s4[0] + s4[1]) + (s4[2] + s4[3]);
;     s += __shfl_xor(s, 16); s += __shfl_xor(s, 32);
;     return __builtin_amdgcn_rsqf(s * (1.0f / 1024.0f) + RMS_EPS_F);
; __device__ __forceinline__ float silu_mul(float g, float u) { return g * u * __builtin_amdgcn_rcpf(1.0f + __builtin_amdgcn_exp2f(g * -1.4426950408889634f)); }
;     __device__ __forceinline__ void operator()(const f32x4 (&acc)[2][2][4][2], const Unit& u, int wr, int wc, int fr, int fq) const {
;         const int row0 = u.pm * BM + wr * 64 + fr; const int col0 = u.pn * HALF + wc * 32 + 8 * fq;
; #pragma unroll
;         for (int ai = 0; ai < 2; ++ai)
; #pragma unroll
;             for (int m = 0; m < 4; ++m) { const int row = row0 + ai * HALF + m * 16;
;                 const float sc = rstd_from_slots(slots, row, fq);
;                 const f32x4 g0 = acc[ai][0][m][0] * sc, g1 = acc[ai][0][m][1] * sc, u0 = acc[ai][1][m][0] * sc, u1 = acc[ai][1][m][1] * sc;
;                 u32x4 w; w.x = cvt_pk_bf16(silu_mul(g0[0], u0[0]), silu_mul(g0[1], u0[1])); w.y = cvt_pk_bf16(silu_mul(g0[2], u0[2]), silu_mul(g0[3], u0[3]));
;                 w.z = cvt_pk_bf16(silu_mul(g1[0], u1[0]), silu_mul(g1[1], u1[1])); w.w = cvt_pk_bf16(silu_mul(g1[2], u1[2]), silu_mul(g1[3], u1[3]));
;                 __builtin_nontemporal_store(w, (u32x4*)(O + (size_t)row * ldc + col0)); }
	v_mov_b32_e32 v80, v184
	v_mov_b32_e32 v81, v185
	v_mov_b32_e32 v82, v186
	v_mov_b32_e32 v83, v187
	v_mov_b32_e32 v84, v81
	v_mov_b32_e32 v85, v82
	v_mov_b32_e32 v81, v83
	v_pk_add_f32 v[80:81], v[84:85], v[80:81]
	v_mad_i64_i32 v[82:83], s[0:1], v96, s56, v[146:147]
	v_add_f32_e32 v80, v80, v81
	ds_bpermute_b32 v81, v151, v80
	v_lshl_add_u64 v[82:83], v[82:83], 0, v[148:149]
	s_waitcnt lgkmcnt(0)
	v_add_f32_e32 v84, v80, v81
	ds_bpermute_b32 v85, v163, v84
	v_add_u32_e32 v80, 0x80, v150
	v_ashrrev_i32_e32 v81, 31, v80
	v_lshlrev_b64 v[86:87], 6, v[80:81]
	v_lshl_add_u64 v[86:87], v[136:137], 0, v[86:87]
	s_waitcnt lgkmcnt(0)
	v_add_f32_e32 v84, v84, v85
	v_fmamk_f32 v84, v84, 0x3a800000, v162
	v_rsq_f32_e32 v84, v84
	s_nop 0
	v_pk_mul_f32 v[78:79], v[78:79], v[84:85] op_sel_hi:[1,0]
	v_pk_mul_f32 v[76:77], v[76:77], v[84:85] op_sel_hi:[1,0]
	v_pk_mul_f32 v[74:75], v[74:75], v[84:85] op_sel_hi:[1,0]
	v_pk_mul_f32 v[72:73], v[72:73], v[84:85] op_sel_hi:[1,0]
	v_pk_mul_f32 v[68:69], v[68:69], v[84:85] op_sel_hi:[1,0]
	v_pk_mul_f32 v[70:71], v[70:71], v[84:85] op_sel_hi:[1,0]
	v_pk_mul_f32 v[64:65], v[64:65], v[84:85] op_sel_hi:[1,0]
	v_pk_mul_f32 v[66:67], v[66:67], v[84:85] op_sel_hi:[1,0]
	v_mul_f32_e32 v81, 0xbfb8aa3b, v76
	v_mul_f32_e32 v84, 0xbfb8aa3b, v77
	v_pk_mul_f32 v[70:71], v[78:79], v[70:71]
	v_pk_mul_f32 v[68:69], v[76:77], v[68:69]
	v_mul_f32_e32 v76, 0xbfb8aa3b, v78
	v_mul_f32_e32 v77, 0xbfb8aa3b, v79
	v_mul_f32_e32 v78, 0xbfb8aa3b, v72
	v_mul_f32_e32 v79, 0xbfb8aa3b, v73
	v_pk_mul_f32 v[64:65], v[72:73], v[64:65]
	v_mul_f32_e32 v72, 0xbfb8aa3b, v74
	v_mul_f32_e32 v73, 0xbfb8aa3b, v75
	v_pk_mul_f32 v[66:67], v[74:75], v[66:67]
	v_exp_f32_e32 v74, v81
	v_exp_f32_e32 v75, v84
	v_exp_f32_e32 v76, v76
	v_exp_f32_e32 v77, v77
	v_exp_f32_e32 v78, v78
	v_exp_f32_e32 v79, v79
	v_exp_f32_e32 v72, v72
	v_exp_f32_e32 v73, v73
	v_add_f32_e32 v74, 1.0, v74
	v_add_f32_e32 v75, 1.0, v75
	v_add_f32_e32 v76, 1.0, v76
	v_add_f32_e32 v77, 1.0, v77
	v_add_f32_e32 v78, 1.0, v78
	v_add_f32_e32 v79, 1.0, v79
	v_add_f32_e32 v81, 1.0, v72
	v_add_f32_e32 v84, 1.0, v73
	v_rcp_f32_e32 v72, v74
	v_rcp_f32_e32 v73, v75
	v_rcp_f32_e32 v74, v76
	v_rcp_f32_e32 v75, v77
	v_rcp_f32_e32 v76, v78
	v_rcp_f32_e32 v77, v79
	v_rcp_f32_e32 v78, v81
	v_rcp_f32_e32 v79, v84
	v_pk_mul_f32 v[68:69], v[68:69], v[72:73]
	v_pk_mul_f32 v[70:71], v[70:71], v[74:75]
	v_pk_mul_f32 v[72:73], v[64:65], v[76:77]
	v_pk_mul_f32 v[74:75], v[66:67], v[78:79]
	v_cvt_pk_bf16_f32 v64, v68, v69
	v_cvt_pk_bf16_f32 v65, v70, v71
	v_cvt_pk_bf16_f32 v66, v72, v73
	v_cvt_pk_bf16_f32 v67, v74, v75
	global_store_dwordx4 v[82:83], v[64:67], off nt
	s_nop 1
	s_waitcnt vmcnt(7)
	v_mov_b32_e32 v64, v188
	v_mov_b32_e32 v65, v189
	v_mov_b32_e32 v66, v190
	v_mov_b32_e32 v67, v191
	v_mov_b32_e32 v68, v65
	v_mov_b32_e32 v69, v66
	v_mov_b32_e32 v65, v67
	v_pk_add_f32 v[64:65], v[68:69], v[64:65]
	v_mad_i64_i32 v[66:67], s[0:1], v80, s56, v[146:147]
	v_add_f32_e32 v64, v64, v65
	ds_bpermute_b32 v65, v151, v64
	v_lshl_add_u64 v[66:67], v[66:67], 0, v[148:149]
	s_waitcnt lgkmcnt(0)
	v_add_f32_e32 v68, v64, v65
	ds_bpermute_b32 v69, v163, v68
	v_add_u32_e32 v64, 0x90, v150
	v_ashrrev_i32_e32 v65, 31, v64
	v_lshlrev_b64 v[70:71], 6, v[64:65]
	v_lshl_add_u64 v[70:71], v[136:137], 0, v[70:71]
	s_waitcnt lgkmcnt(0)
	v_add_f32_e32 v68, v68, v69
	v_fmamk_f32 v68, v68, 0x3a800000, v162
	v_rsq_f32_e32 v68, v68
	s_nop 0
	v_pk_mul_f32 v[62:63], v[62:63], v[68:69] op_sel_hi:[1,0]
	v_pk_mul_f32 v[60:61], v[60:61], v[68:69] op_sel_hi:[1,0]
	v_pk_mul_f32 v[58:59], v[58:59], v[68:69] op_sel_hi:[1,0]
	v_pk_mul_f32 v[56:57], v[56:57], v[68:69] op_sel_hi:[1,0]
	v_pk_mul_f32 v[52:53], v[52:53], v[68:69] op_sel_hi:[1,0]
	v_pk_mul_f32 v[54:55], v[54:55], v[68:69] op_sel_hi:[1,0]
	v_pk_mul_f32 v[48:49], v[48:49], v[68:69] op_sel_hi:[1,0]
	v_pk_mul_f32 v[50:51], v[50:51], v[68:69] op_sel_hi:[1,0]
	v_mul_f32_e32 v65, 0xbfb8aa3b, v60
	v_mul_f32_e32 v68, 0xbfb8aa3b, v61
	v_pk_mul_f32 v[54:55], v[62:63], v[54:55]
	v_pk_mul_f32 v[52:53], v[60:61], v[52:53]
	v_mul_f32_e32 v60, 0xbfb8aa3b, v62
	v_mul_f32_e32 v61, 0xbfb8aa3b, v63
	v_mul_f32_e32 v62, 0xbfb8aa3b, v56
	v_mul_f32_e32 v63, 0xbfb8aa3b, v57
	v_pk_mul_f32 v[48:49], v[56:57], v[48:49]
	v_mul_f32_e32 v56, 0xbfb8aa3b, v58
	v_mul_f32_e32 v57, 0xbfb8aa3b, v59
	v_pk_mul_f32 v[50:51], v[58:59], v[50:51]
	v_exp_f32_e32 v58, v65
	v_exp_f32_e32 v59, v68
	v_exp_f32_e32 v60, v60
	v_exp_f32_e32 v61, v61
	v_exp_f32_e32 v62, v62
	v_exp_f32_e32 v63, v63
	v_exp_f32_e32 v56, v56
	v_exp_f32_e32 v57, v57
	v_add_f32_e32 v58, 1.0, v58
	v_add_f32_e32 v59, 1.0, v59
	v_add_f32_e32 v60, 1.0, v60
	v_add_f32_e32 v61, 1.0, v61
	v_add_f32_e32 v62, 1.0, v62
	v_add_f32_e32 v63, 1.0, v63
	v_add_f32_e32 v65, 1.0, v56
	v_add_f32_e32 v68, 1.0, v57
	v_rcp_f32_e32 v56, v58
	v_rcp_f32_e32 v57, v59
	v_rcp_f32_e32 v58, v60
	v_rcp_f32_e32 v59, v61
	v_rcp_f32_e32 v60, v62
	v_rcp_f32_e32 v61, v63
	v_rcp_f32_e32 v62, v65
	v_rcp_f32_e32 v63, v68
	v_pk_mul_f32 v[52:53], v[52:53], v[56:57]
	v_pk_mul_f32 v[54:55], v[54:55], v[58:59]
	v_pk_mul_f32 v[56:57], v[48:49], v[60:61]
	v_pk_mul_f32 v[58:59], v[50:51], v[62:63]
	v_cvt_pk_bf16_f32 v48, v52, v53
	v_cvt_pk_bf16_f32 v49, v54, v55
	v_cvt_pk_bf16_f32 v50, v56, v57
	v_cvt_pk_bf16_f32 v51, v58, v59
	global_store_dwordx4 v[66:67], v[48:51], off nt
	s_nop 1
	s_waitcnt vmcnt(7)
	v_mov_b32_e32 v48, v192
	v_mov_b32_e32 v49, v193
	v_mov_b32_e32 v50, v194
	v_mov_b32_e32 v51, v195
	v_mov_b32_e32 v52, v49
	v_mov_b32_e32 v53, v50
	v_mov_b32_e32 v49, v51
	v_pk_add_f32 v[48:49], v[52:53], v[48:49]
	v_mad_i64_i32 v[50:51], s[0:1], v64, s56, v[146:147]
	v_add_f32_e32 v48, v48, v49
	ds_bpermute_b32 v49, v151, v48
	v_lshl_add_u64 v[50:51], v[50:51], 0, v[148:149]
	s_waitcnt lgkmcnt(0)
; __device__ __forceinline__ unsigned cvt_pk_bf16(float lo, float hi) { const cvt_f32x2_t v = {lo, hi}; const cvt_bf16x2_t b = __builtin_convertvector(v, cvt_bf16x2_t); return __builtin_bit_cast(unsigned, b); }
; __device__ __forceinline__ float rstd_from_slots(const float* slots, int row, int fq) {
;     const f32x4 s4 = *(const f32x4*)(slots + (size_t)row * 16 + 4 * fq);
;     float s = (s4[0] + s4[1]) + (s4[2] + s4[3]);
;     s += __shfl_xor(s, 16); s += __shfl_xor(s, 32);
;     return __builtin_amdgcn_rsqf(s * (1.0f / 1024.0f) + RMS_EPS_F);
; __device__ __forceinline__ float silu_mul(float g, float u) { return g * u * __builtin_amdgcn_rcpf(1.0f + __builtin_amdgcn_exp2f(g * -1.4426950408889634f)); }
;     __device__ __forceinline__ void operator()(const f32x4 (&acc)[2][2][4][2], const Unit& u, int wr, int wc, int fr, int fq) const {
;         const int row0 = u.pm * BM + wr * 64 + fr; const int col0 = u.pn * HALF + wc * 32 + 8 * fq;
; #pragma unroll
;         for (int ai = 0; ai < 2; ++ai)
; #pragma unroll
;             for (int m = 0; m < 4; ++m) { const int row = row0 + ai * HALF + m * 16;
;                 const float sc = rstd_from_slots(slots, row, fq);
;                 const f32x4 g0 = acc[ai][0][m][0] * sc, g1 = acc[ai][0][m][1] * sc, u0 = acc[ai][1][m][0] * sc, u1 = acc[ai][1][m][1] * sc;
;                 u32x4 w; w.x = cvt_pk_bf16(silu_mul(g0[0], u0[0]), silu_mul(g0[1], u0[1])); w.y = cvt_pk_bf16(silu_mul(g0[2], u0[2]), silu_mul(g0[3], u0[3]));
;                 w.z = cvt_pk_bf16(silu_mul(g1[0], u1[0]), silu_mul(g1[1], u1[1])); w.w = cvt_pk_bf16(silu_mul(g1[2], u1[2]), silu_mul(g1[3], u1[3]));
;                 __builtin_nontemporal_store(w, (u32x4*)(O + (size_t)row * ldc + col0)); }
	v_add_f32_e32 v52, v48, v49
	ds_bpermute_b32 v53, v163, v52
	v_add_u32_e32 v48, 0xa0, v150
	v_ashrrev_i32_e32 v49, 31, v48
	v_lshlrev_b64 v[54:55], 6, v[48:49]
	v_lshl_add_u64 v[54:55], v[136:137], 0, v[54:55]
	s_waitcnt lgkmcnt(0)
	v_add_f32_e32 v52, v52, v53
	v_fmamk_f32 v52, v52, 0x3a800000, v162
	v_rsq_f32_e32 v52, v52
	s_nop 0
	v_pk_mul_f32 v[46:47], v[46:47], v[52:53] op_sel_hi:[1,0]
	v_pk_mul_f32 v[44:45], v[44:45], v[52:53] op_sel_hi:[1,0]
	v_pk_mul_f32 v[42:43], v[42:43], v[52:53] op_sel_hi:[1,0]
	v_pk_mul_f32 v[40:41], v[40:41], v[52:53] op_sel_hi:[1,0]
	v_pk_mul_f32 v[36:37], v[36:37], v[52:53] op_sel_hi:[1,0]
	v_pk_mul_f32 v[38:39], v[38:39], v[52:53] op_sel_hi:[1,0]
	v_pk_mul_f32 v[32:33], v[32:33], v[52:53] op_sel_hi:[1,0]
	v_pk_mul_f32 v[34:35], v[34:35], v[52:53] op_sel_hi:[1,0]
	v_mul_f32_e32 v49, 0xbfb8aa3b, v44
	v_mul_f32_e32 v52, 0xbfb8aa3b, v45
	v_pk_mul_f32 v[38:39], v[46:47], v[38:39]
	v_pk_mul_f32 v[36:37], v[44:45], v[36:37]
	v_mul_f32_e32 v44, 0xbfb8aa3b, v46
	v_mul_f32_e32 v45, 0xbfb8aa3b, v47
	v_mul_f32_e32 v46, 0xbfb8aa3b, v40
	v_mul_f32_e32 v47, 0xbfb8aa3b, v41
	v_pk_mul_f32 v[32:33], v[40:41], v[32:33]
	v_mul_f32_e32 v40, 0xbfb8aa3b, v42
	v_mul_f32_e32 v41, 0xbfb8aa3b, v43
	v_pk_mul_f32 v[34:35], v[42:43], v[34:35]
	v_exp_f32_e32 v42, v49
	v_exp_f32_e32 v43, v52
	v_exp_f32_e32 v44, v44
	v_exp_f32_e32 v45, v45
	v_exp_f32_e32 v46, v46
	v_exp_f32_e32 v47, v47
	v_exp_f32_e32 v40, v40
	v_exp_f32_e32 v41, v41
	v_add_f32_e32 v42, 1.0, v42
	v_add_f32_e32 v43, 1.0, v43
	v_add_f32_e32 v44, 1.0, v44
	v_add_f32_e32 v45, 1.0, v45
	v_add_f32_e32 v46, 1.0, v46
	v_add_f32_e32 v47, 1.0, v47
	v_add_f32_e32 v49, 1.0, v40
	v_add_f32_e32 v52, 1.0, v41
	v_rcp_f32_e32 v40, v42
	v_rcp_f32_e32 v41, v43
	v_rcp_f32_e32 v42, v44
	v_rcp_f32_e32 v43, v45
	v_rcp_f32_e32 v44, v46
	v_rcp_f32_e32 v45, v47
	v_rcp_f32_e32 v46, v49
	v_rcp_f32_e32 v47, v52
	v_pk_mul_f32 v[36:37], v[36:37], v[40:41]
	v_pk_mul_f32 v[38:39], v[38:39], v[42:43]
	v_pk_mul_f32 v[40:41], v[32:33], v[44:45]
	v_pk_mul_f32 v[42:43], v[34:35], v[46:47]
	v_cvt_pk_bf16_f32 v32, v36, v37
	v_cvt_pk_bf16_f32 v33, v38, v39
	v_cvt_pk_bf16_f32 v34, v40, v41
	v_cvt_pk_bf16_f32 v35, v42, v43
	global_store_dwordx4 v[50:51], v[32:35], off nt
	s_nop 1
	s_waitcnt vmcnt(7)
	v_mov_b32_e32 v32, v196
	v_mov_b32_e32 v33, v197
	v_mov_b32_e32 v34, v198
	v_mov_b32_e32 v35, v199
	v_mov_b32_e32 v36, v33
	v_mov_b32_e32 v37, v34
	v_mov_b32_e32 v33, v35
	v_pk_add_f32 v[32:33], v[36:37], v[32:33]
	v_mad_i64_i32 v[34:35], s[0:1], v48, s56, v[146:147]
	v_add_f32_e32 v32, v32, v33
	ds_bpermute_b32 v33, v151, v32
	v_lshl_add_u64 v[34:35], v[34:35], 0, v[148:149]
	s_waitcnt lgkmcnt(0)
	v_add_f32_e32 v36, v32, v33
	ds_bpermute_b32 v37, v163, v36
	v_add_u32_e32 v32, 0xb0, v150
	v_ashrrev_i32_e32 v33, 31, v32
	v_lshlrev_b64 v[38:39], 6, v[32:33]
	v_lshl_add_u64 v[38:39], v[136:137], 0, v[38:39]
	s_waitcnt lgkmcnt(0)
; __device__ __forceinline__ unsigned cvt_pk_bf16(float lo, float hi) { const cvt_f32x2_t v = {lo, hi}; const cvt_bf16x2_t b = __builtin_convertvector(v, cvt_bf16x2_t); return __builtin_bit_cast(unsigned, b); }
; __device__ __forceinline__ float rstd_from_slots(const float* slots, int row, int fq) {
;     const f32x4 s4 = *(const f32x4*)(slots + (size_t)row * 16 + 4 * fq);
;     float s = (s4[0] + s4[1]) + (s4[2] + s4[3]);
;     s += __shfl_xor(s, 16); s += __shfl_xor(s, 32);
;     return __builtin_amdgcn_rsqf(s * (1.0f / 1024.0f) + RMS_EPS_F);
; __device__ __forceinline__ float silu_mul(float g, float u) { return g * u * __builtin_amdgcn_rcpf(1.0f + __builtin_amdgcn_exp2f(g * -1.4426950408889634f)); }
;     __device__ __forceinline__ void operator()(const f32x4 (&acc)[2][2][4][2], const Unit& u, int wr, int wc, int fr, int fq) const {
;         const int row0 = u.pm * BM + wr * 64 + fr; const int col0 = u.pn * HALF + wc * 32 + 8 * fq;
; #pragma unroll
;         for (int ai = 0; ai < 2; ++ai)
; #pragma unroll
;             for (int m = 0; m < 4; ++m) { const int row = row0 + ai * HALF + m * 16;
;                 const float sc = rstd_from_slots(slots, row, fq);
;                 const f32x4 g0 = acc[ai][0][m][0] * sc, g1 = acc[ai][0][m][1] * sc, u0 = acc[ai][1][m][0] * sc, u1 = acc[ai][1][m][1] * sc;
;                 u32x4 w; w.x = cvt_pk_bf16(silu_mul(g0[0], u0[0]), silu_mul(g0[1], u0[1])); w.y = cvt_pk_bf16(silu_mul(g0[2], u0[2]), silu_mul(g0[3], u0[3]));
;                 w.z = cvt_pk_bf16(silu_mul(g1[0], u1[0]), silu_mul(g1[1], u1[1])); w.w = cvt_pk_bf16(silu_mul(g1[2], u1[2]), silu_mul(g1[3], u1[3]));
;                 __builtin_nontemporal_store(w, (u32x4*)(O + (size_t)row * ldc + col0)); }
	v_add_f32_e32 v36, v36, v37
	v_fmamk_f32 v36, v36, 0x3a800000, v162
	v_rsq_f32_e32 v36, v36
	s_nop 0
	v_pk_mul_f32 v[30:31], v[30:31], v[36:37] op_sel_hi:[1,0]
	v_pk_mul_f32 v[28:29], v[28:29], v[36:37] op_sel_hi:[1,0]
	v_pk_mul_f32 v[26:27], v[26:27], v[36:37] op_sel_hi:[1,0]
	v_pk_mul_f32 v[24:25], v[24:25], v[36:37] op_sel_hi:[1,0]
	v_pk_mul_f32 v[20:21], v[20:21], v[36:37] op_sel_hi:[1,0]
	v_pk_mul_f32 v[22:23], v[22:23], v[36:37] op_sel_hi:[1,0]
	v_pk_mul_f32 v[16:17], v[16:17], v[36:37] op_sel_hi:[1,0]
	v_pk_mul_f32 v[18:19], v[18:19], v[36:37] op_sel_hi:[1,0]
	v_mul_f32_e32 v33, 0xbfb8aa3b, v28
	v_mul_f32_e32 v36, 0xbfb8aa3b, v29
	v_pk_mul_f32 v[22:23], v[30:31], v[22:23]
	v_pk_mul_f32 v[20:21], v[28:29], v[20:21]
	v_mul_f32_e32 v28, 0xbfb8aa3b, v30
	v_mul_f32_e32 v29, 0xbfb8aa3b, v31
	v_mul_f32_e32 v30, 0xbfb8aa3b, v24
	v_mul_f32_e32 v31, 0xbfb8aa3b, v25
	v_pk_mul_f32 v[16:17], v[24:25], v[16:17]
	v_mul_f32_e32 v24, 0xbfb8aa3b, v26
	v_mul_f32_e32 v25, 0xbfb8aa3b, v27
	v_pk_mul_f32 v[18:19], v[26:27], v[18:19]
	v_exp_f32_e32 v26, v33
	v_exp_f32_e32 v27, v36
	v_exp_f32_e32 v28, v28
	v_exp_f32_e32 v29, v29
	v_exp_f32_e32 v30, v30
	v_exp_f32_e32 v31, v31
	v_exp_f32_e32 v24, v24
	v_exp_f32_e32 v25, v25
	v_add_f32_e32 v26, 1.0, v26
	v_add_f32_e32 v27, 1.0, v27
	v_add_f32_e32 v28, 1.0, v28
	v_add_f32_e32 v29, 1.0, v29
	v_add_f32_e32 v30, 1.0, v30
	v_add_f32_e32 v31, 1.0, v31
	v_add_f32_e32 v33, 1.0, v24
	v_add_f32_e32 v36, 1.0, v25
	v_rcp_f32_e32 v24, v26
	v_rcp_f32_e32 v25, v27
	v_rcp_f32_e32 v26, v28
	v_rcp_f32_e32 v27, v29
	v_rcp_f32_e32 v28, v30
	v_rcp_f32_e32 v29, v31
	v_rcp_f32_e32 v30, v33
	v_rcp_f32_e32 v31, v36
	v_pk_mul_f32 v[20:21], v[20:21], v[24:25]
	v_pk_mul_f32 v[22:23], v[22:23], v[26:27]
	v_pk_mul_f32 v[24:25], v[16:17], v[28:29]
	v_pk_mul_f32 v[26:27], v[18:19], v[30:31]
	v_cvt_pk_bf16_f32 v16, v20, v21
	v_cvt_pk_bf16_f32 v17, v22, v23
	v_cvt_pk_bf16_f32 v18, v24, v25
	v_cvt_pk_bf16_f32 v19, v26, v27
	global_store_dwordx4 v[34:35], v[16:19], off nt
	s_nop 1
	s_waitcnt vmcnt(7)
	v_mov_b32_e32 v16, v200
	v_mov_b32_e32 v17, v201
	v_mov_b32_e32 v18, v202
	v_mov_b32_e32 v19, v203
	v_mov_b32_e32 v20, v17
	v_mov_b32_e32 v21, v18
	v_mov_b32_e32 v17, v19
	v_pk_add_f32 v[16:17], v[20:21], v[16:17]
	v_mad_i64_i32 v[18:19], s[0:1], v32, s56, v[146:147]
	v_add_f32_e32 v16, v16, v17
	ds_bpermute_b32 v17, v151, v16
	v_lshl_add_u64 v[18:19], v[18:19], 0, v[148:149]
	s_mov_b64 s[0:1], -1
	s_waitcnt lgkmcnt(0)
	v_add_f32_e32 v16, v16, v17
	ds_bpermute_b32 v17, v163, v16
	s_waitcnt lgkmcnt(0)
	v_add_f32_e32 v16, v16, v17
	v_fmamk_f32 v16, v16, 0x3a800000, v162
	v_rsq_f32_e32 v16, v16
	s_nop 0
	v_pk_mul_f32 v[14:15], v[14:15], v[16:17] op_sel_hi:[1,0]
	v_pk_mul_f32 v[12:13], v[12:13], v[16:17] op_sel_hi:[1,0]
	v_pk_mul_f32 v[10:11], v[10:11], v[16:17] op_sel_hi:[1,0]
	v_pk_mul_f32 v[8:9], v[8:9], v[16:17] op_sel_hi:[1,0]
	v_pk_mul_f32 v[4:5], v[4:5], v[16:17] op_sel_hi:[1,0]
	v_pk_mul_f32 v[6:7], v[6:7], v[16:17] op_sel_hi:[1,0]
	v_pk_mul_f32 v[0:1], v[0:1], v[16:17] op_sel_hi:[1,0]
	v_pk_mul_f32 v[2:3], v[2:3], v[16:17] op_sel_hi:[1,0]
	v_mul_f32_e32 v16, 0xbfb8aa3b, v12
	v_mul_f32_e32 v17, 0xbfb8aa3b, v13
	v_pk_mul_f32 v[6:7], v[14:15], v[6:7]
	v_pk_mul_f32 v[4:5], v[12:13], v[4:5]
	v_mul_f32_e32 v12, 0xbfb8aa3b, v14
	v_mul_f32_e32 v13, 0xbfb8aa3b, v15
	v_mul_f32_e32 v14, 0xbfb8aa3b, v8
	v_mul_f32_e32 v15, 0xbfb8aa3b, v9
	v_pk_mul_f32 v[0:1], v[8:9], v[0:1]
	v_mul_f32_e32 v8, 0xbfb8aa3b, v10
	v_mul_f32_e32 v9, 0xbfb8aa3b, v11
	v_pk_mul_f32 v[2:3], v[10:11], v[2:3]
	v_exp_f32_e32 v10, v16
	v_exp_f32_e32 v11, v17
	v_exp_f32_e32 v12, v12
	v_exp_f32_e32 v13, v13
	v_exp_f32_e32 v14, v14
	v_exp_f32_e32 v15, v15
	v_exp_f32_e32 v8, v8
	v_exp_f32_e32 v9, v9
	v_add_f32_e32 v10, 1.0, v10
	v_add_f32_e32 v11, 1.0, v11
	v_add_f32_e32 v12, 1.0, v12
	v_add_f32_e32 v13, 1.0, v13
	v_add_f32_e32 v14, 1.0, v14
	v_add_f32_e32 v15, 1.0, v15
	v_add_f32_e32 v16, 1.0, v8
	v_add_f32_e32 v17, 1.0, v9
	v_rcp_f32_e32 v8, v10
	v_rcp_f32_e32 v9, v11
	v_rcp_f32_e32 v10, v12
	v_rcp_f32_e32 v11, v13
	v_rcp_f32_e32 v12, v14
	v_rcp_f32_e32 v13, v15
	v_rcp_f32_e32 v14, v16
	v_rcp_f32_e32 v15, v17
	v_pk_mul_f32 v[4:5], v[4:5], v[8:9]
	v_pk_mul_f32 v[6:7], v[6:7], v[10:11]
	v_pk_mul_f32 v[8:9], v[0:1], v[12:13]
	v_pk_mul_f32 v[10:11], v[2:3], v[14:15]
	v_cvt_pk_bf16_f32 v0, v4, v5
	v_cvt_pk_bf16_f32 v1, v6, v7
	v_cvt_pk_bf16_f32 v2, v8, v9
	v_cvt_pk_bf16_f32 v3, v10, v11
	global_store_dwordx4 v[18:19], v[0:3], off nt
	s_cbranch_vccnz .LBB0_668
	s_andn2_b64 vcc, exec, s[6:7]
	s_cbranch_vccnz .LBB0_667
	s_barrier
	s_branch .LBB0_667

; #define PG8_STAGE(bufoff, gbase, voff) do { _Pragma("unroll") for (int _i = 0; _i < 2; ++_i) \
;         __builtin_amdgcn_global_load_lds((const unsigned*)((const char*)(gbase) + (voff)[_i]), (PG8_LAS unsigned*)(lds + (bufoff) + ldsw + _i * 8192), 16, 0, PG8_LOAD_AUX); } while (0)
; #define PG8_LDA(dst, b, h) do { _Pragma("unroll") for (int m = 0; m < 4; ++m) _Pragma("unroll") for (int k = 0; k < 2; ++k) dst[m][k] = *(const PG8_LAS bf16x8*)(lds + PG8_SA(b, h) + aoff + m * 2048 + k * 1024); } while (0)
; #define PG8_LDB(dst, b, h) do { _Pragma("unroll") for (int n = 0; n < 2; ++n) _Pragma("unroll") for (int k = 0; k < 2; ++k) dst[n][k] = *(const PG8_LAS bf16x8*)(lds + PG8_SB(b, h) + boff + n * 2048 + k * 1024); } while (0)
; #define PG8_MMA(ai, bj, At, Bt) do { __builtin_amdgcn_s_setprio(1); _Pragma("unroll") for (int m = 0; m < 4; ++m) _Pragma("unroll") for (int n = 0; n < 2; ++n) _Pragma("unroll") for (int k = 0; k < 2; ++k) \
;         acc[ai][bj][m][n] = __builtin_amdgcn_mfma_f32_16x16x32_bf16(Bt[n][k], At[m][k], acc[ai][bj][m][n], 0, 0, 0); __builtin_amdgcn_s_setprio(0); } while (0)
; #define PG8_WAIT_V(n) asm volatile("s_waitcnt vmcnt(" #n ")" ::: "memory")
; #define PG8_WAIT_L(n) asm volatile("s_waitcnt lgkmcnt(" #n ")" ::: "memory")
; #define PG8_BAR __builtin_amdgcn_s_barrier()
; #define PG8_SCHED __builtin_amdgcn_sched_barrier(0)
; template <class Epi, class Sched, bool ALIGN_EPI = false, bool SP2 = false>
; __device__ __forceinline__ void gemm_phase(PG8_LAS unsigned char* lds, const Gemm g, const Sched& S, const Epi& E) {
;     ...
;             PG8_LDB(B0, 1, 0); PG8_LDB(B1, 1, 1); PG8_SCHED; PG8_LDA(At, 1, 0); PG8_STAGE(PG8_SA(0, 1), a2 + hstepA, voffA);
;             PG8_WAIT_V(8); PG8_WAIT_L(0); PG8_BAR; PG8_MMA(0, 0, At, B0); PG8_MMA(0, 1, At, B1); PG8_BAR; PG8_SCHED;
;             PG8_LDA(At, 1, 1); PG8_STAGE(PG8_SB(1, 0), b3, voffB); PG8_STAGE(PG8_SB(1, 1), b3 + hstepB, voffB); PG8_STAGE(PG8_SA(1, 0), a3, voffA);
;             PG8_WAIT_V(8); PG8_WAIT_L(0); PG8_BAR; PG8_MMA(1, 0, At, B0); PG8_MMA(1, 1, At, B1); PG8_BAR; PG8_SCHED;
.Lkmid_P8:
	s_add_i32 s28, 0, 0x18000
	v_add_u32_e32 v161, s28, v151
	s_add_i32 s29, 0, 0x1c000
	ds_read_b128 v[146:149], v161
	ds_read_b128 v[162:165], v161 offset:1024
	ds_read_b128 v[166:169], v161 offset:2048
	ds_read_b128 v[170:173], v161 offset:3072
	v_add_u32_e32 v161, s29, v151
	ds_read_b128 v[174:177], v161
	ds_read_b128 v[178:181], v161 offset:1024
	ds_read_b128 v[182:185], v161 offset:2048
	ds_read_b128 v[186:189], v161 offset:3072
	s_add_u32 s22, s22, 0xb0000
	s_addc_u32 s23, s23, 0
	s_mov_b32 m0, s43
	v_lshl_add_u64 v[230:231], s[22:23], 0, v[128:129]
	ds_read_b128 v[190:193], v159 offset:32768
	ds_read_b128 v[194:197], v159 offset:33792
	ds_read_b128 v[198:201], v159 offset:34816
	ds_read_b128 v[202:205], v159 offset:35840
	ds_read_b128 v[206:209], v159 offset:36864
	ds_read_b128 v[210:213], v159 offset:37888
	ds_read_b128 v[214:217], v159 offset:38912
	ds_read_b128 v[218:221], v159 offset:39936
	global_load_lds_dwordx4 v[230:231], off
	v_lshl_add_u64 v[230:231], s[22:23], 0, v[132:133]
	s_mov_b32 m0, s46
	s_nop 0
	global_load_lds_dwordx4 v[230:231], off
	s_waitcnt vmcnt(8)
	s_waitcnt lgkmcnt(0)
	s_barrier
	s_setprio 1
	s_waitcnt lgkmcnt(0)
	v_mfma_f32_16x16x32_bf16 v[124:127], v[146:149], v[190:193], v[124:127]
	v_mfma_f32_16x16x32_bf16 v[120:123], v[166:169], v[190:193], v[120:123]
	v_mfma_f32_16x16x32_bf16 v[108:111], v[146:149], v[198:201], v[108:111]
	v_mfma_f32_16x16x32_bf16 v[104:107], v[166:169], v[198:201], v[104:107]
	v_mfma_f32_16x16x32_bf16 v[92:95], v[146:149], v[206:209], v[92:95]
	v_mfma_f32_16x16x32_bf16 v[88:91], v[166:169], v[206:209], v[88:91]
	v_mfma_f32_16x16x32_bf16 v[76:79], v[146:149], v[214:217], v[76:79]
	v_mfma_f32_16x16x32_bf16 v[72:75], v[166:169], v[214:217], v[72:75]
	v_mfma_f32_16x16x32_bf16 v[124:127], v[162:165], v[194:197], v[124:127]
	v_mfma_f32_16x16x32_bf16 v[120:123], v[170:173], v[194:197], v[120:123]
	v_mfma_f32_16x16x32_bf16 v[108:111], v[162:165], v[202:205], v[108:111]
	v_mfma_f32_16x16x32_bf16 v[104:107], v[170:173], v[202:205], v[104:107]
	v_mfma_f32_16x16x32_bf16 v[92:95], v[162:165], v[210:213], v[92:95]
	v_mfma_f32_16x16x32_bf16 v[88:91], v[170:173], v[210:213], v[88:91]
	v_mfma_f32_16x16x32_bf16 v[76:79], v[162:165], v[218:221], v[76:79]
	v_mfma_f32_16x16x32_bf16 v[72:75], v[170:173], v[218:221], v[72:75]
	s_setprio 0
	s_setprio 1
	v_mfma_f32_16x16x32_bf16 v[116:119], v[174:177], v[190:193], v[116:119]
	v_mfma_f32_16x16x32_bf16 v[112:115], v[182:185], v[190:193], v[112:115]
	v_mfma_f32_16x16x32_bf16 v[100:103], v[174:177], v[198:201], v[100:103]
	v_mfma_f32_16x16x32_bf16 v[96:99], v[182:185], v[198:201], v[96:99]
	v_mfma_f32_16x16x32_bf16 v[84:87], v[174:177], v[206:209], v[84:87]
	v_mfma_f32_16x16x32_bf16 v[80:83], v[182:185], v[206:209], v[80:83]
	v_mfma_f32_16x16x32_bf16 v[68:71], v[174:177], v[214:217], v[68:71]
	v_mfma_f32_16x16x32_bf16 v[64:67], v[182:185], v[214:217], v[64:67]
	v_mfma_f32_16x16x32_bf16 v[116:119], v[178:181], v[194:197], v[116:119]
	v_mfma_f32_16x16x32_bf16 v[112:115], v[186:189], v[194:197], v[112:115]
	v_mfma_f32_16x16x32_bf16 v[100:103], v[178:181], v[202:205], v[100:103]
	v_mfma_f32_16x16x32_bf16 v[96:99], v[186:189], v[202:205], v[96:99]
	v_mfma_f32_16x16x32_bf16 v[84:87], v[178:181], v[210:213], v[84:87]
	v_mfma_f32_16x16x32_bf16 v[80:83], v[186:189], v[210:213], v[80:83]
	v_mfma_f32_16x16x32_bf16 v[68:71], v[178:181], v[218:221], v[68:71]
	v_mfma_f32_16x16x32_bf16 v[64:67], v[186:189], v[218:221], v[64:67]
	s_setprio 0
	s_barrier
	s_add_i32 s22, s28, s34
	v_lshl_add_u64 v[222:223], v[222:223], 0, s[18:19]
	s_mov_b32 m0, s22
	ds_read_b128 v[190:193], v159 offset:49152
	ds_read_b128 v[194:197], v159 offset:50176
	ds_read_b128 v[198:201], v159 offset:51200
	ds_read_b128 v[202:205], v159 offset:52224
	ds_read_b128 v[206:209], v159 offset:53248
	ds_read_b128 v[210:213], v159 offset:54272
	ds_read_b128 v[214:217], v159 offset:55296
	ds_read_b128 v[218:221], v159 offset:56320
	global_load_lds_dwordx4 v[222:223], off
	s_add_i32 m0, s22, 0x2000
	s_add_u32 s20, s20, 0x2c080
	v_lshl_add_u64 v[222:223], v[224:225], 0, s[18:19]
	s_addc_u32 s21, s21, 0
	s_add_i32 s22, s29, s34
	global_load_lds_dwordx4 v[222:223], off
	v_lshl_add_u64 v[222:223], s[20:21], 0, v[130:131]
	s_mov_b32 m0, s22
	s_nop 0
	global_load_lds_dwordx4 v[222:223], off
	v_lshl_add_u64 v[222:223], s[20:21], 0, v[134:135]
	s_add_i32 m0, s22, 0x2000
	s_nop 0
	global_load_lds_dwordx4 v[222:223], off
	v_lshl_add_u64 v[222:223], v[226:227], 0, s[18:19]
	s_mov_b32 m0, s50
	s_nop 0
	global_load_lds_dwordx4 v[222:223], off
	v_lshl_add_u64 v[222:223], v[228:229], 0, s[18:19]
	s_mov_b32 m0, s51
	s_nop 0
	global_load_lds_dwordx4 v[222:223], off
	s_waitcnt vmcnt(8)
	s_waitcnt lgkmcnt(0)
	s_barrier
; __device__ __forceinline__ unsigned cvt_pk_bf16(float lo, float hi) { const cvt_f32x2_t v = {lo, hi}; const cvt_bf16x2_t b = __builtin_convertvector(v, cvt_bf16x2_t); return __builtin_bit_cast(unsigned, b); }
;     __device__ __forceinline__ void operator()(const f32x4 (&acc)[2][2][4][2], const Unit& u, int wr, int wc, int fr, int fq) const {
;     ...
;             for (int m = 0; m < 4; ++m) { const int rowg = u.pm * BM + ai * HALF + wr * 64 + m * 16, row = rowg + fr; const size_t off = (size_t)row * 1024 + col0;
;                 u32x4 w[2]; float ss = 0.f;
; #pragma unroll
;                 for (int bj = 0; bj < 2; ++bj) { f32x4 b0, b1;
;                     if (BASE_F32) { const float* bp = (const float*)base + off + 32 * bj; b0 = *(const f32x4*)bp; b1 = *(const f32x4*)(bp + 4); }
;                     else { const u32x4 bb = *(const u32x4*)((const bf16_t*)base + off + 32 * bj);
;                         b0 = (f32x4){__uint_as_float(bb.x << 16), __uint_as_float(bb.x & 0xffff0000u), __uint_as_float(bb.y << 16), __uint_as_float(bb.y & 0xffff0000u)};
;                         b1 = (f32x4){__uint_as_float(bb.z << 16), __uint_as_float(bb.z & 0xffff0000u), __uint_as_float(bb.w << 16), __uint_as_float(bb.w & 0xffff0000u)}; }
;                     const f32x4 o0 = b0 + acc[ai][bj][m][0], o1 = b1 + acc[ai][bj][m][1];
;                     ss += ((o0[0] * o0[0] + o0[1] * o0[1]) + (o0[2] * o0[2] + o0[3] * o0[3])) + ((o1[0] * o1[0] + o1[1] * o1[1]) + (o1[2] * o1[2] + o1[3] * o1[3]));
;                     w[bj].x = cvt_pk_bf16(o0[0], o0[1]); w[bj].y = cvt_pk_bf16(o0[2], o0[3]); w[bj].z = cvt_pk_bf16(o1[0], o1[1]); w[bj].w = cvt_pk_bf16(o1[2], o1[3]); }
;                 ss += __shfl_xor(ss, 16); ss += __shfl_xor(ss, 32); if (fq == 0) slots[(size_t)row * 16 + u.pn * 4 + wc] = ss;
	s_setprio 1
	s_waitcnt lgkmcnt(0)
	v_mfma_f32_16x16x32_bf16 v[60:63], v[146:149], v[190:193], v[60:63]
	v_mfma_f32_16x16x32_bf16 v[56:59], v[166:169], v[190:193], v[56:59]
	v_mfma_f32_16x16x32_bf16 v[44:47], v[146:149], v[198:201], v[44:47]
	v_mfma_f32_16x16x32_bf16 v[40:43], v[166:169], v[198:201], v[40:43]
	v_mfma_f32_16x16x32_bf16 v[28:31], v[146:149], v[206:209], v[28:31]
	v_mfma_f32_16x16x32_bf16 v[24:27], v[166:169], v[206:209], v[24:27]
	v_mfma_f32_16x16x32_bf16 v[12:15], v[146:149], v[214:217], v[12:15]
	v_mfma_f32_16x16x32_bf16 v[8:11], v[166:169], v[214:217], v[8:11]
	v_mfma_f32_16x16x32_bf16 v[60:63], v[162:165], v[194:197], v[60:63]
	v_mfma_f32_16x16x32_bf16 v[56:59], v[170:173], v[194:197], v[56:59]
	v_mfma_f32_16x16x32_bf16 v[44:47], v[162:165], v[202:205], v[44:47]
	v_mfma_f32_16x16x32_bf16 v[40:43], v[170:173], v[202:205], v[40:43]
	v_mfma_f32_16x16x32_bf16 v[28:31], v[162:165], v[210:213], v[28:31]
	v_mfma_f32_16x16x32_bf16 v[24:27], v[170:173], v[210:213], v[24:27]
	v_mfma_f32_16x16x32_bf16 v[12:15], v[162:165], v[218:221], v[12:15]
	v_mfma_f32_16x16x32_bf16 v[8:11], v[170:173], v[218:221], v[8:11]
	s_setprio 0
	s_setprio 1
	v_mfma_f32_16x16x32_bf16 v[52:55], v[174:177], v[190:193], v[52:55]
	v_mfma_f32_16x16x32_bf16 v[48:51], v[182:185], v[190:193], v[48:51]
	v_mfma_f32_16x16x32_bf16 v[36:39], v[174:177], v[198:201], v[36:39]
	v_mfma_f32_16x16x32_bf16 v[32:35], v[182:185], v[198:201], v[32:35]
	v_mfma_f32_16x16x32_bf16 v[20:23], v[174:177], v[206:209], v[20:23]
	v_mfma_f32_16x16x32_bf16 v[16:19], v[182:185], v[206:209], v[16:19]
	v_mfma_f32_16x16x32_bf16 v[4:7], v[174:177], v[214:217], v[4:7]
	v_mfma_f32_16x16x32_bf16 v[0:3], v[182:185], v[214:217], v[0:3]
	v_mfma_f32_16x16x32_bf16 v[52:55], v[178:181], v[194:197], v[52:55]
	v_mfma_f32_16x16x32_bf16 v[48:51], v[186:189], v[194:197], v[48:51]
	v_mfma_f32_16x16x32_bf16 v[36:39], v[178:181], v[202:205], v[36:39]
	v_mfma_f32_16x16x32_bf16 v[32:35], v[186:189], v[202:205], v[32:35]
	v_mfma_f32_16x16x32_bf16 v[20:23], v[178:181], v[210:213], v[20:23]
	v_mfma_f32_16x16x32_bf16 v[16:19], v[186:189], v[210:213], v[16:19]
	v_mfma_f32_16x16x32_bf16 v[4:7], v[178:181], v[218:221], v[4:7]
	v_mfma_f32_16x16x32_bf16 v[0:3], v[186:189], v[218:221], v[0:3]
	s_setprio 0
	s_barrier
	s_add_i32 s27, s27, 2
	s_add_u32 s0, s0, 0x100
	s_addc_u32 s1, s1, 0
	s_add_u32 s25, s25, 0x100
	s_addc_u32 s26, s26, 0
	s_cmp_gt_u32 s27, 41
	s_cbranch_scc0 .LBB0_757
	s_lshl_b32 s22, s24, 8
	s_add_i32 s22, s22, s49
	v_or_b32_e32 v148, s22, v150
	v_ashrrev_i32_e32 v149, 31, v148
	v_readlane_b32 s30, v239, 49
	v_lshl_or_b32 v146, s14, 8, v152
	v_lshlrev_b64 v[162:163], 11, v[148:149]
	v_readlane_b32 s31, v239, 50
	v_ashrrev_i32_e32 v147, 31, v146
	v_and_b32_e32 v170, 64, v160
	v_lshl_add_u64 v[162:163], s[30:31], 0, v[162:163]
	v_lshl_add_u64 v[166:167], v[146:147], 1, v[162:163]
	global_load_dwordx4 v[162:165], v[166:167], off
	s_nop 0
	global_load_dwordx4 v[166:169], v[166:167], off offset:64
	v_add_u32_e32 v178, 64, v170
	v_xor_b32_e32 v161, 16, v160
	v_cmp_lt_i32_e32 vcc, v161, v178
	s_lshl_b32 s0, s14, 2
	s_ashr_i32 s1, s0, 31
	v_cndmask_b32_e32 v161, v160, v161, vcc
	v_lshlrev_b32_e32 v161, 2, v161
	s_waitcnt vmcnt(0)
	v_lshlrev_b32_e32 v170, 16, v162
	v_and_b32_e32 v171, 0xffff0000, v162
	v_lshlrev_b32_e32 v162, 16, v163
	v_and_b32_e32 v163, 0xffff0000, v163
	v_lshlrev_b32_e32 v172, 16, v164
	v_and_b32_e32 v173, 0xffff0000, v164
	v_lshlrev_b32_e32 v164, 16, v165
	v_and_b32_e32 v165, 0xffff0000, v165
	v_lshlrev_b32_e32 v174, 16, v166
	v_and_b32_e32 v175, 0xffff0000, v166
	v_lshlrev_b32_e32 v166, 16, v167
	v_and_b32_e32 v167, 0xffff0000, v167
	v_lshlrev_b32_e32 v176, 16, v168
	v_and_b32_e32 v177, 0xffff0000, v168
	v_lshlrev_b32_e32 v168, 16, v169
	v_and_b32_e32 v169, 0xffff0000, v169
	v_pk_add_f32 v[126:127], v[126:127], v[162:163]
	v_pk_add_f32 v[124:125], v[124:125], v[170:171]
	v_pk_add_f32 v[122:123], v[122:123], v[164:165]
	v_pk_add_f32 v[120:121], v[120:121], v[172:173]
	v_pk_add_f32 v[118:119], v[118:119], v[166:167]
	v_pk_add_f32 v[116:117], v[116:117], v[174:175]
	v_pk_add_f32 v[114:115], v[114:115], v[168:169]
	v_pk_add_f32 v[112:113], v[112:113], v[176:177]
	v_mul_f32_e32 v162, v125, v125
	v_mul_f32_e32 v163, v127, v127
	v_mul_f32_e32 v164, v121, v121
	v_mul_f32_e32 v165, v123, v123
	v_mul_f32_e32 v166, v117, v117
	v_mul_f32_e32 v167, v119, v119
	v_mul_f32_e32 v168, v113, v113
	v_mul_f32_e32 v169, v115, v115
	v_fmac_f32_e32 v162, v124, v124
	v_fmac_f32_e32 v163, v126, v126
	v_fmac_f32_e32 v164, v120, v120
	v_fmac_f32_e32 v165, v122, v122
	v_fmac_f32_e32 v166, v116, v116
	v_fmac_f32_e32 v167, v118, v118
	v_fmac_f32_e32 v168, v112, v112
	v_fmac_f32_e32 v169, v114, v114
	v_add_f32_e32 v162, v162, v163
	v_add_f32_e32 v163, v164, v165
	v_add_f32_e32 v164, v166, v167
	v_add_f32_e32 v165, v168, v169
	v_add_f32_e32 v162, v162, v163
	v_add_f32_e32 v163, v164, v165
	v_add_f32_e32 v163, v162, v163
	ds_bpermute_b32 v164, v161, v163
	v_xor_b32_e32 v162, 32, v160
	v_cmp_lt_i32_e32 vcc, v162, v178
	s_waitcnt lgkmcnt(0)
	v_add_f32_e32 v163, v163, v164
	v_cndmask_b32_e32 v162, v160, v162, vcc
	v_lshlrev_b32_e32 v162, 2, v162
	ds_bpermute_b32 v164, v162, v163
	s_and_saveexec_b64 s[20:21], s[2:3]
	s_cbranch_execz .LBB0_762
	v_lshlrev_b64 v[148:149], 6, v[148:149]
	v_lshl_add_u64 v[148:149], s[82:83], 0, v[148:149]
	v_lshl_add_u64 v[148:149], s[0:1], 2, v[148:149]
	s_lshl_b32 s14, s48, 2
	v_lshl_add_u64 v[148:149], v[148:149], 0, s[14:15]
	s_waitcnt lgkmcnt(0)
	v_add_f32_e32 v163, v163, v164
	global_store_dword v[148:149], v163, off
; __device__ __forceinline__ unsigned swap8(unsigned v) { return (unsigned)__builtin_amdgcn_update_dpp(0, (int)v, 0x128  , 0xF, 0xF, false); }
; __device__ __forceinline__ void wide_store(bf16_t* O, int ldc, int rowg  , int col0  , int fr, u32x4 w0, u32x4 w1) {
;     const bool lo = fr < 8;
;     u32x4 snd = lo ? w1 : w0, rcv;
;     rcv.x = swap8(snd.x); rcv.y = swap8(snd.y); rcv.z = swap8(snd.z); rcv.w = swap8(snd.w);
;     const u32x4 first = lo ? w0 : rcv, second = lo ? rcv : w1;
;     bf16_t* p = O + (size_t)(rowg + (fr & 7)) * ldc + col0 + (lo ? 0 : 32);
;     __builtin_nontemporal_store(first, (u32x4*)p); __builtin_nontemporal_store(second, (u32x4*)(p + (size_t)8 * ldc));
; }
;     __device__ __forceinline__ void operator()(const f32x4 (&acc)[2][2][4][2], const Unit& u, int wr, int wc, int fr, int fq) const {
;         const int col0 = u.pn * BM + wc * 64 + 8 * fq;
; #pragma unroll
;         for (int ai = 0; ai < 2; ++ai)
; #pragma unroll
;             for (int m = 0; m < 4; ++m) { const int rowg = u.pm * BM + ai * HALF + wr * 64 + m * 16;
;                 const float sc = slots ? rstd_from_slots(slots, rowg + fr, fq) : 1.0f;
;                 u32x4 w[2];
; #pragma unroll
;                 for (int bj = 0; bj < 2; ++bj) { const f32x4 v0 = acc[ai][bj][m][0] * sc, v1 = acc[ai][bj][m][1] * sc;
;                     w[bj].x = cvt_pk_bf16(v0[0], v0[1]); w[bj].y = cvt_pk_bf16(v0[2], v0[3]); w[bj].z = cvt_pk_bf16(v1[0], v1[1]); w[bj].w = cvt_pk_bf16(v1[2], v1[3]); }
;                 wide_store(O, ldc, rowg, col0, fr, w[0], w[1]); }
;     }
;     __device__ __forceinline__ void operator()(const f32x4 (&acc)[2][2][4][2], const Unit& u, int wr, int wc, int fr, int fq) const {
;         const int col0 = u.pn * BM + wc * 64 + 8 * fq;
; #pragma unroll
;         for (int ai = 0; ai < 2; ++ai)
; #pragma unroll
;             for (int m = 0; m < 4; ++m) { const int rowg = u.pm * BM + ai * HALF + wr * 64 + m * 16, row = rowg + fr; const size_t off = (size_t)row * 1024 + col0;
;                 u32x4 w[2]; float ss = 0.f;
; #pragma unroll
;                 for (int bj = 0; bj < 2; ++bj) { f32x4 b0, b1;
;                     if (BASE_F32) { const float* bp = (const float*)base + off + 32 * bj; b0 = *(const f32x4*)bp; b1 = *(const f32x4*)(bp + 4); }
;                     else { const u32x4 bb = *(const u32x4*)((const bf16_t*)base + off + 32 * bj);
.LBB0_762:
	s_or_b64 exec, exec, s[20:21]
	v_cvt_pk_bf16_f32 v120, v120, v121
	v_cvt_pk_bf16_f32 v112, v112, v113
	v_cvt_pk_bf16_f32 v124, v124, v125
	v_cvt_pk_bf16_f32 v125, v126, v127
	v_cvt_pk_bf16_f32 v121, v122, v123
	v_cvt_pk_bf16_f32 v118, v118, v119
	v_cvt_pk_bf16_f32 v113, v114, v115
	v_cndmask_b32_e64 v115, v120, v112, s[4:5]
	v_mov_b32_e32 v126, v137
	v_cvt_pk_bf16_f32 v122, v116, v117
	v_cndmask_b32_e64 v114, v121, v113, s[4:5]
	v_cndmask_b32_e64 v116, v125, v118, s[4:5]
	v_mov_b32_e32 v119, v137
	v_mov_b32_dpp v126, v115 row_ror:8 row_mask:0xf bank_mask:0xf
	v_mov_b32_e32 v127, v137
	v_cndmask_b32_e64 v117, v124, v122, s[4:5]
	v_mov_b32_e32 v123, v137
	v_mov_b32_dpp v119, v116 row_ror:8 row_mask:0xf bank_mask:0xf
	v_mov_b32_dpp v127, v114 row_ror:8 row_mask:0xf bank_mask:0xf
	v_cndmask_b32_e64 v116, v126, v120, s[4:5]
	v_cndmask_b32_e64 v120, v112, v126, s[4:5]
	v_or_b32_e32 v112, s22, v156
	v_mov_b32_dpp v123, v117 row_ror:8 row_mask:0xf bank_mask:0xf
	v_cndmask_b32_e64 v117, v127, v121, s[4:5]
	v_cndmask_b32_e64 v121, v113, v127, s[4:5]
	v_ashrrev_i32_e32 v113, 31, v112
	v_lshlrev_b64 v[112:113], 11, v[112:113]
	v_cndmask_b32_e64 v115, v119, v125, s[4:5]
	v_cndmask_b32_e64 v114, v123, v124, s[4:5]
	v_cndmask_b32_e64 v119, v118, v119, s[4:5]
	v_cndmask_b32_e64 v118, v122, v123, s[4:5]
	v_lshl_add_u64 v[122:123], s[30:31], 0, v[112:113]
	v_lshlrev_b64 v[112:113], 1, v[146:147]
	v_lshl_add_u64 v[122:123], v[122:123], 0, v[112:113]
	v_lshl_add_u64 v[122:123], v[122:123], 0, v[136:137]
	s_cmp_lg_u64 s[36:37], 0
	s_cbranch_scc0 .LBB0_760
	s_barrier
.LBB0_760:
	global_store_dwordx4 v[122:123], v[114:117], off nt
	s_or_b32 s23, s22, 16
	s_nop 0
	v_add_co_u32_e32 v114, vcc, s47, v122
	s_nop 1
	v_addc_co_u32_e32 v115, vcc, 0, v123, vcc
	global_store_dwordx4 v[114:115], v[118:121], off nt
	v_or_b32_e32 v114, s23, v150
	v_ashrrev_i32_e32 v115, 31, v114
	v_lshlrev_b64 v[116:117], 11, v[114:115]
	v_lshl_add_u64 v[116:117], s[30:31], 0, v[116:117]
	v_lshl_add_u64 v[120:121], v[116:117], 0, v[112:113]
	global_load_dwordx4 v[116:119], v[120:121], off
	s_nop 0
	global_load_dwordx4 v[120:123], v[120:121], off offset:64
	s_waitcnt vmcnt(1)
	v_lshlrev_b32_e32 v124, 16, v116
	v_and_b32_e32 v125, 0xffff0000, v116
	v_lshlrev_b32_e32 v116, 16, v117
	v_and_b32_e32 v117, 0xffff0000, v117
	v_lshlrev_b32_e32 v126, 16, v118
	v_and_b32_e32 v127, 0xffff0000, v118
	v_lshlrev_b32_e32 v118, 16, v119
	v_and_b32_e32 v119, 0xffff0000, v119
	s_waitcnt vmcnt(0)
	v_lshlrev_b32_e32 v148, 16, v120
	v_and_b32_e32 v149, 0xffff0000, v120
	v_lshlrev_b32_e32 v120, 16, v121
	v_and_b32_e32 v121, 0xffff0000, v121
	s_waitcnt lgkmcnt(0)
	v_lshlrev_b32_e32 v164, 16, v122
	v_and_b32_e32 v165, 0xffff0000, v122
	v_lshlrev_b32_e32 v122, 16, v123
	v_and_b32_e32 v123, 0xffff0000, v123
	v_pk_add_f32 v[110:111], v[110:111], v[116:117]
	v_pk_add_f32 v[108:109], v[108:109], v[124:125]
	v_pk_add_f32 v[106:107], v[106:107], v[118:119]
	v_pk_add_f32 v[104:105], v[104:105], v[126:127]
	v_pk_add_f32 v[102:103], v[102:103], v[120:121]
	v_pk_add_f32 v[100:101], v[100:101], v[148:149]
	v_pk_add_f32 v[98:99], v[98:99], v[122:123]
	v_pk_add_f32 v[96:97], v[96:97], v[164:165]
	v_mul_f32_e32 v116, v109, v109
	v_mul_f32_e32 v117, v111, v111
	v_mul_f32_e32 v118, v105, v105
	v_mul_f32_e32 v119, v107, v107
	v_mul_f32_e32 v120, v101, v101
	v_mul_f32_e32 v121, v103, v103
	v_mul_f32_e32 v122, v97, v97
	v_mul_f32_e32 v123, v99, v99
	v_fmac_f32_e32 v116, v108, v108
	v_fmac_f32_e32 v117, v110, v110
	v_fmac_f32_e32 v118, v104, v104
	v_fmac_f32_e32 v119, v106, v106
	v_fmac_f32_e32 v120, v100, v100
	v_fmac_f32_e32 v121, v102, v102
	v_fmac_f32_e32 v122, v96, v96
	v_fmac_f32_e32 v123, v98, v98
	v_add_f32_e32 v116, v116, v117
	v_add_f32_e32 v117, v118, v119
	v_add_f32_e32 v118, v120, v121
	v_add_f32_e32 v119, v122, v123
	v_add_f32_e32 v116, v116, v117
	v_add_f32_e32 v117, v118, v119
	v_add_f32_e32 v116, v116, v117
	ds_bpermute_b32 v117, v161, v116
	s_waitcnt lgkmcnt(0)
	v_add_f32_e32 v116, v116, v117
	ds_bpermute_b32 v117, v162, v116
	s_and_saveexec_b64 s[20:21], s[2:3]
	s_cbranch_execz .LBB0_764
	v_lshlrev_b64 v[114:115], 6, v[114:115]
	v_lshl_add_u64 v[114:115], s[82:83], 0, v[114:115]
	v_lshl_add_u64 v[114:115], s[0:1], 2, v[114:115]
	s_lshl_b32 s14, s48, 2
	v_lshl_add_u64 v[114:115], v[114:115], 0, s[14:15]
	s_waitcnt lgkmcnt(0)
	v_add_f32_e32 v116, v116, v117
	global_store_dword v[114:115], v116, off

; #define PG8_STAGE(bufoff, gbase, voff) do { _Pragma("unroll") for (int _i = 0; _i < 2; ++_i) \
;         __builtin_amdgcn_global_load_lds((const unsigned*)((const char*)(gbase) + (voff)[_i]), (PG8_LAS unsigned*)(lds + (bufoff) + ldsw + _i * 8192), 16, 0, PG8_LOAD_AUX); } while (0)
; #define PG8_LDA(dst, b, h) do { _Pragma("unroll") for (int m = 0; m < 4; ++m) _Pragma("unroll") for (int k = 0; k < 2; ++k) dst[m][k] = *(const PG8_LAS bf16x8*)(lds + PG8_SA(b, h) + aoff + m * 2048 + k * 1024); } while (0)
; #define PG8_LDB(dst, b, h) do { _Pragma("unroll") for (int n = 0; n < 2; ++n) _Pragma("unroll") for (int k = 0; k < 2; ++k) dst[n][k] = *(const PG8_LAS bf16x8*)(lds + PG8_SB(b, h) + boff + n * 2048 + k * 1024); } while (0)
; #define PG8_MMA(ai, bj, At, Bt) do { __builtin_amdgcn_s_setprio(1); _Pragma("unroll") for (int m = 0; m < 4; ++m) _Pragma("unroll") for (int n = 0; n < 2; ++n) _Pragma("unroll") for (int k = 0; k < 2; ++k) \
;         acc[ai][bj][m][n] = __builtin_amdgcn_mfma_f32_16x16x32_bf16(Bt[n][k], At[m][k], acc[ai][bj][m][n], 0, 0, 0); __builtin_amdgcn_s_setprio(0); } while (0)
; #define PG8_WAIT_V(n) asm volatile("s_waitcnt vmcnt(" #n ")" ::: "memory")
; #define PG8_WAIT_L(n) asm volatile("s_waitcnt lgkmcnt(" #n ")" ::: "memory")
; #define PG8_BAR __builtin_amdgcn_s_barrier()
; #define PG8_SCHED __builtin_amdgcn_sched_barrier(0)
; template <class Epi, class Sched, bool ALIGN_EPI = false, bool SP2 = false>
; __device__ __forceinline__ void gemm_phase(PG8_LAS unsigned char* lds, const Gemm g, const Sched& S, const Epi& E) {
;     ...
;             PG8_LDB(B0, 1, 0); PG8_LDB(B1, 1, 1); PG8_SCHED; PG8_LDA(At, 1, 0); PG8_STAGE(PG8_SA(0, 1), a2 + hstepA, voffA);
;             PG8_WAIT_V(8); PG8_WAIT_L(0); PG8_BAR; PG8_MMA(0, 0, At, B0); PG8_MMA(0, 1, At, B1); PG8_BAR; PG8_SCHED;
;             PG8_LDA(At, 1, 1); PG8_STAGE(PG8_SB(1, 0), b3, voffB); PG8_STAGE(PG8_SB(1, 1), b3 + hstepB, voffB); PG8_STAGE(PG8_SA(1, 0), a3, voffA);
;             PG8_WAIT_V(8); PG8_WAIT_L(0); PG8_BAR; PG8_MMA(1, 0, At, B0); PG8_MMA(1, 1, At, B1); PG8_BAR; PG8_SCHED;
.Lkmid_P9:
	s_add_i32 s30, 0, 0x18000
	v_add_u32_e32 v150, s30, v157
	s_add_i32 s31, 0, 0x1c000
	ds_read_b128 v[164:167], v150
	ds_read_b128 v[168:171], v150 offset:1024
	ds_read_b128 v[172:175], v150 offset:2048
	ds_read_b128 v[176:179], v150 offset:3072
	v_add_u32_e32 v150, s31, v157
	ds_read_b128 v[180:183], v150
	ds_read_b128 v[184:187], v150 offset:1024
	ds_read_b128 v[188:191], v150 offset:2048
	ds_read_b128 v[192:195], v150 offset:3072
	s_add_u32 s22, s22, 0x40000
	s_addc_u32 s23, s23, 0
	s_mov_b32 m0, s50
	v_lshl_add_u64 v[234:235], s[22:23], 0, v[128:129]
	ds_read_b128 v[196:199], v161 offset:32768
	ds_read_b128 v[200:203], v161 offset:33792
	ds_read_b128 v[204:207], v161 offset:34816
	ds_read_b128 v[208:211], v161 offset:35840
	ds_read_b128 v[212:215], v161 offset:36864
	ds_read_b128 v[216:219], v161 offset:37888
	ds_read_b128 v[220:223], v161 offset:38912
	ds_read_b128 v[224:227], v161 offset:39936
	global_load_lds_dwordx4 v[234:235], off
	v_lshl_add_u64 v[234:235], s[22:23], 0, v[132:133]
	s_mov_b32 m0, s51
	s_nop 0
	global_load_lds_dwordx4 v[234:235], off
	s_waitcnt vmcnt(8)
	s_waitcnt lgkmcnt(0)
	s_barrier
	s_setprio 1
	s_waitcnt lgkmcnt(0)
	v_mfma_f32_16x16x32_bf16 v[124:127], v[164:167], v[196:199], v[124:127]
	v_mfma_f32_16x16x32_bf16 v[120:123], v[172:175], v[196:199], v[120:123]
	v_mfma_f32_16x16x32_bf16 v[108:111], v[164:167], v[204:207], v[108:111]
	v_mfma_f32_16x16x32_bf16 v[104:107], v[172:175], v[204:207], v[104:107]
	v_mfma_f32_16x16x32_bf16 v[92:95], v[164:167], v[212:215], v[92:95]
	v_mfma_f32_16x16x32_bf16 v[88:91], v[172:175], v[212:215], v[88:91]
	v_mfma_f32_16x16x32_bf16 v[76:79], v[164:167], v[220:223], v[76:79]
	v_mfma_f32_16x16x32_bf16 v[72:75], v[172:175], v[220:223], v[72:75]
	v_mfma_f32_16x16x32_bf16 v[124:127], v[168:171], v[200:203], v[124:127]
	v_mfma_f32_16x16x32_bf16 v[120:123], v[176:179], v[200:203], v[120:123]
	v_mfma_f32_16x16x32_bf16 v[108:111], v[168:171], v[208:211], v[108:111]
	v_mfma_f32_16x16x32_bf16 v[104:107], v[176:179], v[208:211], v[104:107]
	v_mfma_f32_16x16x32_bf16 v[92:95], v[168:171], v[216:219], v[92:95]
	v_mfma_f32_16x16x32_bf16 v[88:91], v[176:179], v[216:219], v[88:91]
	v_mfma_f32_16x16x32_bf16 v[76:79], v[168:171], v[224:227], v[76:79]
	v_mfma_f32_16x16x32_bf16 v[72:75], v[176:179], v[224:227], v[72:75]
	s_setprio 0
	s_setprio 1
	v_mfma_f32_16x16x32_bf16 v[116:119], v[180:183], v[196:199], v[116:119]
	v_mfma_f32_16x16x32_bf16 v[112:115], v[188:191], v[196:199], v[112:115]
	v_mfma_f32_16x16x32_bf16 v[100:103], v[180:183], v[204:207], v[100:103]
	v_mfma_f32_16x16x32_bf16 v[96:99], v[188:191], v[204:207], v[96:99]
	v_mfma_f32_16x16x32_bf16 v[84:87], v[180:183], v[212:215], v[84:87]
	v_mfma_f32_16x16x32_bf16 v[80:83], v[188:191], v[212:215], v[80:83]
	v_mfma_f32_16x16x32_bf16 v[68:71], v[180:183], v[220:223], v[68:71]
	v_mfma_f32_16x16x32_bf16 v[64:67], v[188:191], v[220:223], v[64:67]
	v_mfma_f32_16x16x32_bf16 v[116:119], v[184:187], v[200:203], v[116:119]
	v_mfma_f32_16x16x32_bf16 v[112:115], v[192:195], v[200:203], v[112:115]
	v_mfma_f32_16x16x32_bf16 v[100:103], v[184:187], v[208:211], v[100:103]
	v_mfma_f32_16x16x32_bf16 v[96:99], v[192:195], v[208:211], v[96:99]
	v_mfma_f32_16x16x32_bf16 v[84:87], v[184:187], v[216:219], v[84:87]
	v_mfma_f32_16x16x32_bf16 v[80:83], v[192:195], v[216:219], v[80:83]
	v_mfma_f32_16x16x32_bf16 v[68:71], v[184:187], v[224:227], v[68:71]
	v_mfma_f32_16x16x32_bf16 v[64:67], v[192:195], v[224:227], v[64:67]
	s_setprio 0
	s_barrier
	s_add_i32 s22, s30, s34
	v_lshl_add_u64 v[148:149], v[148:149], 0, s[16:17]
	s_mov_b32 m0, s22
	ds_read_b128 v[196:199], v161 offset:49152
	ds_read_b128 v[200:203], v161 offset:50176
	ds_read_b128 v[204:207], v161 offset:51200
	ds_read_b128 v[208:211], v161 offset:52224
	ds_read_b128 v[212:215], v161 offset:53248
	ds_read_b128 v[216:219], v161 offset:54272
	ds_read_b128 v[220:223], v161 offset:55296
	ds_read_b128 v[224:227], v161 offset:56320
	global_load_lds_dwordx4 v[148:149], off
	s_add_i32 m0, s22, 0x2000
	s_add_u32 s20, s20, 0x10080
	v_lshl_add_u64 v[148:149], v[228:229], 0, s[16:17]
	s_addc_u32 s21, s21, 0
	s_add_i32 s22, s31, s34
	global_load_lds_dwordx4 v[148:149], off
	v_lshl_add_u64 v[148:149], s[20:21], 0, v[130:131]
	s_mov_b32 m0, s22
	s_nop 0
	global_load_lds_dwordx4 v[148:149], off
	v_lshl_add_u64 v[148:149], s[20:21], 0, v[134:135]
	s_add_i32 m0, s22, 0x2000
	s_nop 0
	global_load_lds_dwordx4 v[148:149], off
	v_lshl_add_u64 v[148:149], v[230:231], 0, s[16:17]
	s_mov_b32 m0, s56
	s_nop 0
	global_load_lds_dwordx4 v[148:149], off
	v_lshl_add_u64 v[148:149], v[232:233], 0, s[16:17]
	s_mov_b32 m0, s57
	s_nop 0
	global_load_lds_dwordx4 v[148:149], off
	s_waitcnt vmcnt(8)
	s_waitcnt lgkmcnt(0)
	s_barrier
; __device__ __forceinline__ float rstd_from_slots(const float* slots, int row, int fq) {
;     const f32x4 s4 = *(const f32x4*)(slots + (size_t)row * 16 + 4 * fq);
;     float s = (s4[0] + s4[1]) + (s4[2] + s4[3]);
;     s += __shfl_xor(s, 16); s += __shfl_xor(s, 32);
;     return __builtin_amdgcn_rsqf(s * (1.0f / 1024.0f) + RMS_EPS_F);
;     __device__ __forceinline__ void operator()(const f32x4 (&acc)[2][2][4][2], const Unit& u, int wr, int wc, int fr, int fq) const {
;         const int col0 = u.pn * BM + wc * 64 + 8 * fq;
; #pragma unroll
;         for (int ai = 0; ai < 2; ++ai)
; #pragma unroll
;             for (int m = 0; m < 4; ++m) { const int rowg = u.pm * BM + ai * HALF + wr * 64 + m * 16;
;                 const float sc = slots ? rstd_from_slots(slots, rowg + fr, fq) : 1.0f;
	s_setprio 1
	s_waitcnt lgkmcnt(0)
	v_mfma_f32_16x16x32_bf16 v[60:63], v[164:167], v[196:199], v[60:63]
	v_mfma_f32_16x16x32_bf16 v[56:59], v[172:175], v[196:199], v[56:59]
	v_mfma_f32_16x16x32_bf16 v[44:47], v[164:167], v[204:207], v[44:47]
	v_mfma_f32_16x16x32_bf16 v[40:43], v[172:175], v[204:207], v[40:43]
	v_mfma_f32_16x16x32_bf16 v[28:31], v[164:167], v[212:215], v[28:31]
	v_mfma_f32_16x16x32_bf16 v[24:27], v[172:175], v[212:215], v[24:27]
	v_mfma_f32_16x16x32_bf16 v[12:15], v[164:167], v[220:223], v[12:15]
	v_mfma_f32_16x16x32_bf16 v[8:11], v[172:175], v[220:223], v[8:11]
	v_mfma_f32_16x16x32_bf16 v[60:63], v[168:171], v[200:203], v[60:63]
	v_mfma_f32_16x16x32_bf16 v[56:59], v[176:179], v[200:203], v[56:59]
	v_mfma_f32_16x16x32_bf16 v[44:47], v[168:171], v[208:211], v[44:47]
	v_mfma_f32_16x16x32_bf16 v[40:43], v[176:179], v[208:211], v[40:43]
	v_mfma_f32_16x16x32_bf16 v[28:31], v[168:171], v[216:219], v[28:31]
	v_mfma_f32_16x16x32_bf16 v[24:27], v[176:179], v[216:219], v[24:27]
	v_mfma_f32_16x16x32_bf16 v[12:15], v[168:171], v[224:227], v[12:15]
	v_mfma_f32_16x16x32_bf16 v[8:11], v[176:179], v[224:227], v[8:11]
	s_setprio 0
	s_setprio 1
	v_mfma_f32_16x16x32_bf16 v[52:55], v[180:183], v[196:199], v[52:55]
	v_mfma_f32_16x16x32_bf16 v[48:51], v[188:191], v[196:199], v[48:51]
	v_mfma_f32_16x16x32_bf16 v[36:39], v[180:183], v[204:207], v[36:39]
	v_mfma_f32_16x16x32_bf16 v[32:35], v[188:191], v[204:207], v[32:35]
	v_mfma_f32_16x16x32_bf16 v[20:23], v[180:183], v[212:215], v[20:23]
	v_mfma_f32_16x16x32_bf16 v[16:19], v[188:191], v[212:215], v[16:19]
	v_mfma_f32_16x16x32_bf16 v[4:7], v[180:183], v[220:223], v[4:7]
	v_mfma_f32_16x16x32_bf16 v[0:3], v[188:191], v[220:223], v[0:3]
	v_mfma_f32_16x16x32_bf16 v[52:55], v[184:187], v[200:203], v[52:55]
	v_mfma_f32_16x16x32_bf16 v[48:51], v[192:195], v[200:203], v[48:51]
	v_mfma_f32_16x16x32_bf16 v[36:39], v[184:187], v[208:211], v[36:39]
	v_mfma_f32_16x16x32_bf16 v[32:35], v[192:195], v[208:211], v[32:35]
	v_mfma_f32_16x16x32_bf16 v[20:23], v[184:187], v[216:219], v[20:23]
	v_mfma_f32_16x16x32_bf16 v[16:19], v[192:195], v[216:219], v[16:19]
	v_mfma_f32_16x16x32_bf16 v[4:7], v[184:187], v[224:227], v[4:7]
	v_mfma_f32_16x16x32_bf16 v[0:3], v[192:195], v[224:227], v[0:3]
	s_setprio 0
	s_barrier
	s_add_i32 s29, s29, 2
	s_add_u32 s0, s0, 0x100
	s_addc_u32 s1, s1, 0
	s_add_u32 s27, s27, 0x100
	s_addc_u32 s28, s28, 0
	s_cmp_gt_u32 s29, 13
	s_cbranch_scc0 .LBB0_850
	s_lshl_b32 s1, s6, 8
	v_cndmask_b32_e64 v148, 0, 1, s[14:15]
	s_add_i32 s0, s1, s55
	v_mov_b32_e32 v150, 1.0
	v_cmp_ne_u32_e64 s[6:7], 1, v148
	s_andn2_b64 vcc, exec, s[14:15]
	v_mbcnt_hi_u32_b32 v164, -1, v163
	v_mov_b32_e32 v152, 1.0
	s_cbranch_vccnz .LBB0_855
	v_or_b32_e32 v148, s0, v151
	v_ashrrev_i32_e32 v149, 31, v148
	v_lshlrev_b64 v[148:149], 6, v[148:149]
	v_lshl_add_u64 v[148:149], v[138:139], 0, v[148:149]
	global_load_dwordx4 v[166:169], v[148:149], off
	v_and_b32_e32 v149, 64, v164
	v_xor_b32_e32 v148, 16, v164
	v_add_u32_e32 v152, 64, v149
	v_cmp_lt_i32_e32 vcc, v148, v152
	s_waitcnt vmcnt(0)
	v_mov_b32_e32 v149, v168
	v_cndmask_b32_e32 v148, v164, v148, vcc
	v_lshlrev_b32_e32 v165, 2, v148
	v_mov_b32_e32 v148, v167
	v_mov_b32_e32 v167, v169
	v_pk_add_f32 v[148:149], v[148:149], v[166:167]
	s_nop 0
	v_add_f32_e32 v148, v148, v149
	ds_bpermute_b32 v149, v165, v148
	v_xor_b32_e32 v165, 32, v164
	v_cmp_lt_i32_e32 vcc, v165, v152
	s_waitcnt lgkmcnt(0)
	v_add_f32_e32 v148, v148, v149
	v_cndmask_b32_e32 v152, v164, v165, vcc
	v_lshlrev_b32_e32 v149, 2, v152
	ds_bpermute_b32 v149, v149, v148
	s_waitcnt lgkmcnt(0)
	v_add_f32_e32 v148, v148, v149
	v_fmamk_f32 v148, v148, 0x3a800000, v162
	v_rsq_f32_e32 v152, v148
; __device__ __forceinline__ unsigned cvt_pk_bf16(float lo, float hi) { const cvt_f32x2_t v = {lo, hi}; const cvt_bf16x2_t b = __builtin_convertvector(v, cvt_bf16x2_t); return __builtin_bit_cast(unsigned, b); }
; __device__ __forceinline__ unsigned swap8(unsigned v) { return (unsigned)__builtin_amdgcn_update_dpp(0, (int)v, 0x128  , 0xF, 0xF, false); }
; __device__ __forceinline__ void wide_store(bf16_t* O, int ldc, int rowg  , int col0  , int fr, u32x4 w0, u32x4 w1) {
;     const bool lo = fr < 8;
;     u32x4 snd = lo ? w1 : w0, rcv;
;     rcv.x = swap8(snd.x); rcv.y = swap8(snd.y); rcv.z = swap8(snd.z); rcv.w = swap8(snd.w);
;     const u32x4 first = lo ? w0 : rcv, second = lo ? rcv : w1;
;     bf16_t* p = O + (size_t)(rowg + (fr & 7)) * ldc + col0 + (lo ? 0 : 32);
;     __builtin_nontemporal_store(first, (u32x4*)p); __builtin_nontemporal_store(second, (u32x4*)(p + (size_t)8 * ldc));
; }
;     __device__ __forceinline__ void operator()(const f32x4 (&acc)[2][2][4][2], const Unit& u, int wr, int wc, int fr, int fq) const {
;         const int col0 = u.pn * BM + wc * 64 + 8 * fq;
; #pragma unroll
;         for (int ai = 0; ai < 2; ++ai)
; #pragma unroll
;             for (int m = 0; m < 4; ++m) { const int rowg = u.pm * BM + ai * HALF + wr * 64 + m * 16;
;                 const float sc = slots ? rstd_from_slots(slots, rowg + fr, fq) : 1.0f;
;                 u32x4 w[2];
; #pragma unroll
;                 for (int bj = 0; bj < 2; ++bj) { const f32x4 v0 = acc[ai][bj][m][0] * sc, v1 = acc[ai][bj][m][1] * sc;
;                     w[bj].x = cvt_pk_bf16(v0[0], v0[1]); w[bj].y = cvt_pk_bf16(v0[2], v0[3]); w[bj].z = cvt_pk_bf16(v1[0], v1[1]); w[bj].w = cvt_pk_bf16(v1[2], v1[3]); }
;                 wide_store(O, ldc, rowg, col0, fr, w[0], w[1]); }
.LBB0_855:
	s_nop 0
	v_pk_mul_f32 v[120:121], v[120:121], v[152:153] op_sel_hi:[1,0]
	v_pk_mul_f32 v[118:119], v[118:119], v[152:153] op_sel_hi:[1,0]
	v_pk_mul_f32 v[116:117], v[116:117], v[152:153] op_sel_hi:[1,0]
	v_pk_mul_f32 v[112:113], v[112:113], v[152:153] op_sel_hi:[1,0]
	v_pk_mul_f32 v[126:127], v[126:127], v[152:153] op_sel_hi:[1,0]
	v_pk_mul_f32 v[124:125], v[124:125], v[152:153] op_sel_hi:[1,0]
	v_pk_mul_f32 v[122:123], v[122:123], v[152:153] op_sel_hi:[1,0]
	v_cvt_pk_bf16_f32 v120, v120, v121
	v_pk_mul_f32 v[114:115], v[114:115], v[152:153] op_sel_hi:[1,0]
	v_cvt_pk_bf16_f32 v116, v116, v117
	v_cvt_pk_bf16_f32 v117, v118, v119
	v_cvt_pk_bf16_f32 v118, v112, v113
	v_cvt_pk_bf16_f32 v124, v124, v125
	v_cvt_pk_bf16_f32 v125, v126, v127
	v_cvt_pk_bf16_f32 v121, v122, v123
	v_cvt_pk_bf16_f32 v119, v114, v115
	v_cndmask_b32_e64 v114, v120, v118, s[2:3]
	v_mov_b32_e32 v126, v137
	v_cndmask_b32_e64 v112, v121, v119, s[2:3]
	v_mov_b32_e32 v127, v137
	v_mov_b32_dpp v126, v114 row_ror:8 row_mask:0xf bank_mask:0xf
	v_cndmask_b32_e64 v115, v124, v116, s[2:3]
	v_mov_b32_e32 v122, v137
	v_mov_b32_dpp v127, v112 row_ror:8 row_mask:0xf bank_mask:0xf
	v_cndmask_b32_e64 v114, v126, v120, s[2:3]
	v_or_b32_e32 v120, s0, v156
	v_mov_b32_dpp v122, v115 row_ror:8 row_mask:0xf bank_mask:0xf
	v_cndmask_b32_e64 v115, v127, v121, s[2:3]
	v_ashrrev_i32_e32 v121, 31, v120
	v_readlane_b32 s20, v239, 47
	v_lshl_or_b32 v148, s48, 8, v158
	v_lshlrev_b64 v[120:121], 11, v[120:121]
	v_readlane_b32 s21, v239, 48
	v_ashrrev_i32_e32 v149, 31, v148
	v_cndmask_b32_e64 v113, v125, v117, s[2:3]
	v_mov_b32_e32 v123, v137
	v_lshl_add_u64 v[120:121], s[20:21], 0, v[120:121]
	v_lshl_add_u64 v[120:121], v[148:149], 1, v[120:121]
	v_mov_b32_dpp v123, v113 row_ror:8 row_mask:0xf bank_mask:0xf
	v_cndmask_b32_e64 v113, v123, v125, s[2:3]
	v_cndmask_b32_e64 v112, v122, v124, s[2:3]
	v_lshl_add_u64 v[120:121], v[120:121], 0, v[136:137]
	s_cmp_lg_u64 s[18:19], 0
	s_cbranch_scc0 .LBB0_853
	s_barrier
.LBB0_853:
	global_store_dwordx4 v[120:121], v[112:115], off nt
	v_cndmask_b32_e64 v119, v119, v127, s[2:3]
	v_cndmask_b32_e64 v117, v117, v123, s[2:3]
	v_add_co_u32_e32 v112, vcc, 0x4000, v120
	v_cndmask_b32_e64 v118, v118, v126, s[2:3]
	s_nop 0
	v_addc_co_u32_e32 v113, vcc, 0, v121, vcc
	v_cndmask_b32_e64 v116, v116, v122, s[2:3]
	s_and_b64 vcc, exec, s[6:7]
	s_add_i32 s20, s1, s58
	global_store_dwordx4 v[112:113], v[116:119], off nt
	s_cbranch_vccnz .LBB0_857
	v_or_b32_e32 v112, s20, v151
	v_ashrrev_i32_e32 v113, 31, v112
	v_lshlrev_b64 v[112:113], 6, v[112:113]
	v_lshl_add_u64 v[112:113], v[138:139], 0, v[112:113]
	global_load_dwordx4 v[112:115], v[112:113], off
	v_and_b32_e32 v117, 64, v164
	v_xor_b32_e32 v116, 16, v164
	v_add_u32_e32 v118, 64, v117
	v_cmp_lt_i32_e32 vcc, v116, v118
	s_waitcnt vmcnt(0)
	v_mov_b32_e32 v117, v114
	v_cndmask_b32_e32 v116, v164, v116, vcc
	v_lshlrev_b32_e32 v119, 2, v116
	v_mov_b32_e32 v116, v113
	v_mov_b32_e32 v113, v115
	v_pk_add_f32 v[112:113], v[116:117], v[112:113]
	v_xor_b32_e32 v114, 32, v164
	v_add_f32_e32 v112, v112, v113
	ds_bpermute_b32 v113, v119, v112
	v_cmp_lt_i32_e32 vcc, v114, v118
	s_waitcnt lgkmcnt(0)
	v_add_f32_e32 v112, v112, v113
	v_cndmask_b32_e32 v114, v164, v114, vcc
	v_lshlrev_b32_e32 v113, 2, v114
	ds_bpermute_b32 v113, v113, v112
	s_waitcnt lgkmcnt(0)
	v_add_f32_e32 v112, v112, v113
	v_fmamk_f32 v112, v112, 0x3a800000, v162
	v_rsq_f32_e32 v150, v112

; #define PG8_STAGE(bufoff, gbase, voff) do { _Pragma("unroll") for (int _i = 0; _i < 2; ++_i) \
;         __builtin_amdgcn_global_load_lds((const unsigned*)((const char*)(gbase) + (voff)[_i]), (PG8_LAS unsigned*)(lds + (bufoff) + ldsw + _i * 8192), 16, 0, PG8_LOAD_AUX); } while (0)
; #define PG8_LDA(dst, b, h) do { _Pragma("unroll") for (int m = 0; m < 4; ++m) _Pragma("unroll") for (int k = 0; k < 2; ++k) dst[m][k] = *(const PG8_LAS bf16x8*)(lds + PG8_SA(b, h) + aoff + m * 2048 + k * 1024); } while (0)
; #define PG8_LDB(dst, b, h) do { _Pragma("unroll") for (int n = 0; n < 2; ++n) _Pragma("unroll") for (int k = 0; k < 2; ++k) dst[n][k] = *(const PG8_LAS bf16x8*)(lds + PG8_SB(b, h) + boff + n * 2048 + k * 1024); } while (0)
; #define PG8_MMA(ai, bj, At, Bt) do { __builtin_amdgcn_s_setprio(1); _Pragma("unroll") for (int m = 0; m < 4; ++m) _Pragma("unroll") for (int n = 0; n < 2; ++n) _Pragma("unroll") for (int k = 0; k < 2; ++k) \
;         acc[ai][bj][m][n] = __builtin_amdgcn_mfma_f32_16x16x32_bf16(Bt[n][k], At[m][k], acc[ai][bj][m][n], 0, 0, 0); __builtin_amdgcn_s_setprio(0); } while (0)
; #define PG8_WAIT_V(n) asm volatile("s_waitcnt vmcnt(" #n ")" ::: "memory")
; #define PG8_WAIT_L(n) asm volatile("s_waitcnt lgkmcnt(" #n ")" ::: "memory")
; #define PG8_BAR __builtin_amdgcn_s_barrier()
; #define PG8_SCHED __builtin_amdgcn_sched_barrier(0)
; template <class Epi, class Sched, bool ALIGN_EPI = false, bool SP2 = false>
; __device__ __forceinline__ void gemm_phase(PG8_LAS unsigned char* lds, const Gemm g, const Sched& S, const Epi& E) {
;     ...
;             PG8_LDB(B0, 1, 0); PG8_LDB(B1, 1, 1); PG8_SCHED; PG8_LDA(At, 1, 0); PG8_STAGE(PG8_SA(0, 1), a2 + hstepA, voffA);
;             PG8_WAIT_V(8); PG8_WAIT_L(0); PG8_BAR; PG8_MMA(0, 0, At, B0); PG8_MMA(0, 1, At, B1); PG8_BAR; PG8_SCHED;
;             PG8_LDA(At, 1, 1); PG8_STAGE(PG8_SB(1, 0), b3, voffB); PG8_STAGE(PG8_SB(1, 1), b3 + hstepB, voffB); PG8_STAGE(PG8_SA(1, 0), a3, voffA);
;             PG8_WAIT_V(8); PG8_WAIT_L(0); PG8_BAR; PG8_MMA(1, 0, At, B0); PG8_MMA(1, 1, At, B1); PG8_BAR; PG8_SCHED;
.Lkmid_P11:
	v_add_u32_e32 v164, s29, v147
	v_add_u32_e32 v180, s28, v147
	ds_read_b128 v[142:145], v164
	ds_read_b128 v[156:159], v164 offset:1024
	ds_read_b128 v[160:163], v164 offset:2048
	ds_read_b128 v[164:167], v164 offset:3072
	ds_read_b128 v[168:171], v180
	ds_read_b128 v[172:175], v180 offset:1024
	ds_read_b128 v[176:179], v180 offset:2048
	ds_read_b128 v[180:183], v180 offset:3072
	s_mov_b32 m0, s60
	v_lshl_add_u64 v[224:225], s[48:49], 0, v[128:129]
	ds_read_b128 v[184:187], v152 offset:32768
	ds_read_b128 v[188:191], v152 offset:33792
	ds_read_b128 v[192:195], v152 offset:34816
	ds_read_b128 v[196:199], v152 offset:35840
	ds_read_b128 v[200:203], v152 offset:36864
	ds_read_b128 v[204:207], v152 offset:37888
	ds_read_b128 v[208:211], v152 offset:38912
	ds_read_b128 v[212:215], v152 offset:39936
	global_load_lds_dwordx4 v[224:225], off
	v_lshl_add_u64 v[224:225], s[48:49], 0, v[132:133]
	s_mov_b32 m0, s61
	s_nop 0
	global_load_lds_dwordx4 v[224:225], off
	s_waitcnt vmcnt(8)
	s_waitcnt lgkmcnt(0)
	s_barrier
	s_setprio 1
	s_waitcnt lgkmcnt(0)
	v_mfma_f32_16x16x32_bf16 v[124:127], v[142:145], v[184:187], v[124:127]
	v_mfma_f32_16x16x32_bf16 v[120:123], v[160:163], v[184:187], v[120:123]
	v_mfma_f32_16x16x32_bf16 v[108:111], v[142:145], v[192:195], v[108:111]
	v_mfma_f32_16x16x32_bf16 v[104:107], v[160:163], v[192:195], v[104:107]
	v_mfma_f32_16x16x32_bf16 v[92:95], v[142:145], v[200:203], v[92:95]
	v_mfma_f32_16x16x32_bf16 v[88:91], v[160:163], v[200:203], v[88:91]
	v_mfma_f32_16x16x32_bf16 v[76:79], v[142:145], v[208:211], v[76:79]
	v_mfma_f32_16x16x32_bf16 v[72:75], v[160:163], v[208:211], v[72:75]
	v_mfma_f32_16x16x32_bf16 v[124:127], v[156:159], v[188:191], v[124:127]
	v_mfma_f32_16x16x32_bf16 v[120:123], v[164:167], v[188:191], v[120:123]
	v_mfma_f32_16x16x32_bf16 v[108:111], v[156:159], v[196:199], v[108:111]
	v_mfma_f32_16x16x32_bf16 v[104:107], v[164:167], v[196:199], v[104:107]
	v_mfma_f32_16x16x32_bf16 v[92:95], v[156:159], v[204:207], v[92:95]
	v_mfma_f32_16x16x32_bf16 v[88:91], v[164:167], v[204:207], v[88:91]
	v_mfma_f32_16x16x32_bf16 v[76:79], v[156:159], v[212:215], v[76:79]
	v_mfma_f32_16x16x32_bf16 v[72:75], v[164:167], v[212:215], v[72:75]
	s_setprio 0
	s_setprio 1
	v_mfma_f32_16x16x32_bf16 v[116:119], v[168:171], v[184:187], v[116:119]
	v_mfma_f32_16x16x32_bf16 v[112:115], v[176:179], v[184:187], v[112:115]
	v_mfma_f32_16x16x32_bf16 v[100:103], v[168:171], v[192:195], v[100:103]
	v_mfma_f32_16x16x32_bf16 v[96:99], v[176:179], v[192:195], v[96:99]
	v_mfma_f32_16x16x32_bf16 v[84:87], v[168:171], v[200:203], v[84:87]
	v_mfma_f32_16x16x32_bf16 v[80:83], v[176:179], v[200:203], v[80:83]
	v_mfma_f32_16x16x32_bf16 v[68:71], v[168:171], v[208:211], v[68:71]
	v_mfma_f32_16x16x32_bf16 v[64:67], v[176:179], v[208:211], v[64:67]
	v_mfma_f32_16x16x32_bf16 v[116:119], v[172:175], v[188:191], v[116:119]
	v_mfma_f32_16x16x32_bf16 v[112:115], v[180:183], v[188:191], v[112:115]
	v_mfma_f32_16x16x32_bf16 v[100:103], v[172:175], v[196:199], v[100:103]
	v_mfma_f32_16x16x32_bf16 v[96:99], v[180:183], v[196:199], v[96:99]
	v_mfma_f32_16x16x32_bf16 v[84:87], v[172:175], v[204:207], v[84:87]
	v_mfma_f32_16x16x32_bf16 v[80:83], v[180:183], v[204:207], v[80:83]
	v_mfma_f32_16x16x32_bf16 v[68:71], v[172:175], v[212:215], v[68:71]
	v_mfma_f32_16x16x32_bf16 v[64:67], v[180:183], v[212:215], v[64:67]
	s_setprio 0
	s_barrier
	s_mov_b32 m0, s27
	v_lshl_add_u64 v[216:217], v[216:217], 0, s[18:19]
	ds_read_b128 v[184:187], v152 offset:49152
	ds_read_b128 v[188:191], v152 offset:50176
	ds_read_b128 v[192:195], v152 offset:51200
	ds_read_b128 v[196:199], v152 offset:52224
	ds_read_b128 v[200:203], v152 offset:53248
	ds_read_b128 v[204:207], v152 offset:54272
	ds_read_b128 v[208:211], v152 offset:55296
	ds_read_b128 v[212:215], v152 offset:56320
	global_load_lds_dwordx4 v[216:217], off
	v_lshl_add_u64 v[216:217], v[218:219], 0, s[18:19]
	s_mov_b32 m0, s26
	s_nop 0
	global_load_lds_dwordx4 v[216:217], off
	v_lshl_add_u64 v[216:217], s[34:35], 0, v[130:131]
	s_mov_b32 m0, s41
	s_nop 0
	global_load_lds_dwordx4 v[216:217], off
	v_lshl_add_u64 v[216:217], s[34:35], 0, v[134:135]
	s_mov_b32 m0, s39
	s_nop 0
	global_load_lds_dwordx4 v[216:217], off
	v_lshl_add_u64 v[216:217], v[220:221], 0, s[18:19]
	s_mov_b32 m0, s65
	s_nop 0
	global_load_lds_dwordx4 v[216:217], off
	v_lshl_add_u64 v[216:217], v[222:223], 0, s[18:19]
	s_mov_b32 m0, s66
	s_nop 0
	global_load_lds_dwordx4 v[216:217], off
	s_waitcnt vmcnt(8)
	s_waitcnt lgkmcnt(0)
	s_barrier
	s_setprio 1
	s_waitcnt lgkmcnt(0)
	v_mfma_f32_16x16x32_bf16 v[60:63], v[142:145], v[184:187], v[60:63]
	v_mfma_f32_16x16x32_bf16 v[56:59], v[160:163], v[184:187], v[56:59]
	v_mfma_f32_16x16x32_bf16 v[44:47], v[142:145], v[192:195], v[44:47]
	v_mfma_f32_16x16x32_bf16 v[40:43], v[160:163], v[192:195], v[40:43]
	v_mfma_f32_16x16x32_bf16 v[28:31], v[142:145], v[200:203], v[28:31]
	v_mfma_f32_16x16x32_bf16 v[24:27], v[160:163], v[200:203], v[24:27]
	v_mfma_f32_16x16x32_bf16 v[12:15], v[142:145], v[208:211], v[12:15]
	v_mfma_f32_16x16x32_bf16 v[8:11], v[160:163], v[208:211], v[8:11]
	v_mfma_f32_16x16x32_bf16 v[60:63], v[156:159], v[188:191], v[60:63]
	v_mfma_f32_16x16x32_bf16 v[56:59], v[164:167], v[188:191], v[56:59]
	v_mfma_f32_16x16x32_bf16 v[44:47], v[156:159], v[196:199], v[44:47]
	v_mfma_f32_16x16x32_bf16 v[40:43], v[164:167], v[196:199], v[40:43]
	v_mfma_f32_16x16x32_bf16 v[28:31], v[156:159], v[204:207], v[28:31]
	v_mfma_f32_16x16x32_bf16 v[24:27], v[164:167], v[204:207], v[24:27]
	v_mfma_f32_16x16x32_bf16 v[12:15], v[156:159], v[212:215], v[12:15]
	v_mfma_f32_16x16x32_bf16 v[8:11], v[164:167], v[212:215], v[8:11]
	s_setprio 0
	s_setprio 1
	v_mfma_f32_16x16x32_bf16 v[52:55], v[168:171], v[184:187], v[52:55]
	v_mfma_f32_16x16x32_bf16 v[48:51], v[176:179], v[184:187], v[48:51]
	v_mfma_f32_16x16x32_bf16 v[36:39], v[168:171], v[192:195], v[36:39]
	v_mfma_f32_16x16x32_bf16 v[32:35], v[176:179], v[192:195], v[32:35]
	v_mfma_f32_16x16x32_bf16 v[20:23], v[168:171], v[200:203], v[20:23]
	v_mfma_f32_16x16x32_bf16 v[16:19], v[176:179], v[200:203], v[16:19]
	v_mfma_f32_16x16x32_bf16 v[4:7], v[168:171], v[208:211], v[4:7]
	v_mfma_f32_16x16x32_bf16 v[0:3], v[176:179], v[208:211], v[0:3]
	v_mfma_f32_16x16x32_bf16 v[52:55], v[172:175], v[188:191], v[52:55]
	v_mfma_f32_16x16x32_bf16 v[48:51], v[180:183], v[188:191], v[48:51]
	v_mfma_f32_16x16x32_bf16 v[36:39], v[172:175], v[196:199], v[36:39]
	v_mfma_f32_16x16x32_bf16 v[32:35], v[180:183], v[196:199], v[32:35]
	v_mfma_f32_16x16x32_bf16 v[20:23], v[172:175], v[204:207], v[20:23]
	v_mfma_f32_16x16x32_bf16 v[16:19], v[180:183], v[204:207], v[16:19]
	v_mfma_f32_16x16x32_bf16 v[4:7], v[172:175], v[212:215], v[4:7]
	v_mfma_f32_16x16x32_bf16 v[0:3], v[180:183], v[212:215], v[0:3]
	s_setprio 0
	s_barrier
; __device__ __forceinline__ unsigned cvt_pk_bf16(float lo, float hi) { const cvt_f32x2_t v = {lo, hi}; const cvt_bf16x2_t b = __builtin_convertvector(v, cvt_bf16x2_t); return __builtin_bit_cast(unsigned, b); }
;     __device__ __forceinline__ void operator()(const f32x4 (&acc)[2][2][4][2], const Unit& u, int wr, int wc, int fr, int fq) const {
;     ...
;             for (int m = 0; m < 4; ++m) { const int rowg = u.pm * BM + ai * HALF + wr * 64 + m * 16, row = rowg + fr; const size_t off = (size_t)row * 1024 + col0;
;                 u32x4 w[2]; float ss = 0.f;
; #pragma unroll
;                 for (int bj = 0; bj < 2; ++bj) { f32x4 b0, b1;
;                     if (BASE_F32) { const float* bp = (const float*)base + off + 32 * bj; b0 = *(const f32x4*)bp; b1 = *(const f32x4*)(bp + 4); }
;                     else { const u32x4 bb = *(const u32x4*)((const bf16_t*)base + off + 32 * bj);
;                         b0 = (f32x4){__uint_as_float(bb.x << 16), __uint_as_float(bb.x & 0xffff0000u), __uint_as_float(bb.y << 16), __uint_as_float(bb.y & 0xffff0000u)};
;                         b1 = (f32x4){__uint_as_float(bb.z << 16), __uint_as_float(bb.z & 0xffff0000u), __uint_as_float(bb.w << 16), __uint_as_float(bb.w & 0xffff0000u)}; }
;                     const f32x4 o0 = b0 + acc[ai][bj][m][0], o1 = b1 + acc[ai][bj][m][1];
;                     ss += ((o0[0] * o0[0] + o0[1] * o0[1]) + (o0[2] * o0[2] + o0[3] * o0[3])) + ((o1[0] * o1[0] + o1[1] * o1[1]) + (o1[2] * o1[2] + o1[3] * o1[3]));
;                     w[bj].x = cvt_pk_bf16(o0[0], o0[1]); w[bj].y = cvt_pk_bf16(o0[2], o0[3]); w[bj].z = cvt_pk_bf16(o1[0], o1[1]); w[bj].w = cvt_pk_bf16(o1[2], o1[3]); }
;                 ss += __shfl_xor(ss, 16); ss += __shfl_xor(ss, 32); if (fq == 0) slots[(size_t)row * 16 + u.pn * 4 + wc] = ss;
	s_movk_i32 s26, 0x100
	s_andn2_b64 vcc, exec, s[22:23]
	s_mov_b64 s[34:35], -1
	s_mov_b64 s[22:23], 0
	s_cbranch_vccz .LBB0_1018
	s_lshl_b32 s22, s46, 8
	s_add_i32 s22, s22, s64
	v_or_b32_e32 v144, s22, v146
	v_ashrrev_i32_e32 v145, 31, v144
	v_readlane_b32 s30, v239, 49
	v_lshl_or_b32 v142, s14, 8, v148
	v_lshlrev_b64 v[156:157], 11, v[144:145]
	v_readlane_b32 s31, v239, 50
	v_ashrrev_i32_e32 v143, 31, v142
	s_lshl_b32 s0, s14, 2
	v_lshl_add_u64 v[156:157], s[30:31], 0, v[156:157]
	v_lshl_add_u64 v[156:157], v[142:143], 1, v[156:157]
	global_load_dwordx4 v[158:161], v[156:157], off
	global_load_dwordx4 v[162:165], v[156:157], off offset:64
	v_and_b32_e32 v157, 64, v155
	v_xor_b32_e32 v156, 16, v155
	v_add_u32_e32 v157, 64, v157
	v_cmp_lt_i32_e32 vcc, v156, v157
	s_ashr_i32 s1, s0, 31
	s_waitcnt vmcnt(0)
	v_lshlrev_b32_e32 v166, 16, v158
	v_and_b32_e32 v167, 0xffff0000, v158
	v_lshlrev_b32_e32 v158, 16, v159
	v_and_b32_e32 v159, 0xffff0000, v159
	v_lshlrev_b32_e32 v168, 16, v160
	v_and_b32_e32 v169, 0xffff0000, v160
	v_lshlrev_b32_e32 v160, 16, v161
	v_and_b32_e32 v161, 0xffff0000, v161
	v_lshlrev_b32_e32 v170, 16, v162
	v_and_b32_e32 v171, 0xffff0000, v162
	v_lshlrev_b32_e32 v162, 16, v163
	v_and_b32_e32 v163, 0xffff0000, v163
	v_lshlrev_b32_e32 v172, 16, v164
	v_and_b32_e32 v173, 0xffff0000, v164
	v_lshlrev_b32_e32 v164, 16, v165
	v_and_b32_e32 v165, 0xffff0000, v165
	v_pk_add_f32 v[126:127], v[126:127], v[158:159]
	v_pk_add_f32 v[124:125], v[124:125], v[166:167]
	v_pk_add_f32 v[122:123], v[122:123], v[160:161]
	v_pk_add_f32 v[120:121], v[120:121], v[168:169]
	v_pk_add_f32 v[118:119], v[118:119], v[162:163]
	v_pk_add_f32 v[116:117], v[116:117], v[170:171]
	v_pk_add_f32 v[114:115], v[114:115], v[164:165]
	v_pk_add_f32 v[112:113], v[112:113], v[172:173]
	v_mul_f32_e32 v158, v125, v125
	v_mul_f32_e32 v159, v127, v127
	v_mul_f32_e32 v160, v121, v121
	v_mul_f32_e32 v161, v123, v123
	v_mul_f32_e32 v162, v117, v117
	v_mul_f32_e32 v163, v119, v119
	v_mul_f32_e32 v164, v113, v113
	v_mul_f32_e32 v165, v115, v115
	v_fmac_f32_e32 v158, v124, v124
	v_fmac_f32_e32 v159, v126, v126
	v_fmac_f32_e32 v160, v120, v120
	v_fmac_f32_e32 v161, v122, v122
	v_fmac_f32_e32 v162, v116, v116
	v_fmac_f32_e32 v163, v118, v118
	v_fmac_f32_e32 v164, v112, v112
	v_fmac_f32_e32 v165, v114, v114
	v_add_f32_e32 v158, v158, v159
	v_add_f32_e32 v159, v160, v161
	v_add_f32_e32 v160, v162, v163
	v_add_f32_e32 v161, v164, v165
	v_cndmask_b32_e32 v156, v155, v156, vcc
	v_add_f32_e32 v158, v158, v159
	v_add_f32_e32 v159, v160, v161
	v_lshlrev_b32_e32 v156, 2, v156
	v_add_f32_e32 v158, v158, v159
	ds_bpermute_b32 v159, v156, v158
	v_xor_b32_e32 v160, 32, v155
	v_cmp_lt_i32_e32 vcc, v160, v157
	s_waitcnt lgkmcnt(0)
	v_add_f32_e32 v158, v158, v159
	v_cndmask_b32_e32 v157, v155, v160, vcc
	v_lshlrev_b32_e32 v157, 2, v157
	ds_bpermute_b32 v159, v157, v158
	s_and_saveexec_b64 s[20:21], s[2:3]
	s_cbranch_execz .LBB0_1023
	v_lshlrev_b64 v[144:145], 6, v[144:145]
	v_lshl_add_u64 v[144:145], s[82:83], 0, v[144:145]
	v_lshl_add_u64 v[144:145], s[0:1], 2, v[144:145]
	s_lshl_b32 s14, s63, 2
	v_lshl_add_u64 v[144:145], v[144:145], 0, s[14:15]
	s_waitcnt lgkmcnt(0)
	v_add_f32_e32 v158, v158, v159
	global_store_dword v[144:145], v158, off
; __device__ __forceinline__ unsigned swap8(unsigned v) { return (unsigned)__builtin_amdgcn_update_dpp(0, (int)v, 0x128  , 0xF, 0xF, false); }
; __device__ __forceinline__ void wide_store(bf16_t* O, int ldc, int rowg  , int col0  , int fr, u32x4 w0, u32x4 w1) {
;     const bool lo = fr < 8;
;     u32x4 snd = lo ? w1 : w0, rcv;
;     rcv.x = swap8(snd.x); rcv.y = swap8(snd.y); rcv.z = swap8(snd.z); rcv.w = swap8(snd.w);
;     const u32x4 first = lo ? w0 : rcv, second = lo ? rcv : w1;
;     bf16_t* p = O + (size_t)(rowg + (fr & 7)) * ldc + col0 + (lo ? 0 : 32);
;     __builtin_nontemporal_store(first, (u32x4*)p); __builtin_nontemporal_store(second, (u32x4*)(p + (size_t)8 * ldc));
; }
;     __device__ __forceinline__ void operator()(const f32x4 (&acc)[2][2][4][2], const Unit& u, int wr, int wc, int fr, int fq) const {
;         const int col0 = u.pn * BM + wc * 64 + 8 * fq;
; #pragma unroll
;         for (int ai = 0; ai < 2; ++ai)
; #pragma unroll
;             for (int m = 0; m < 4; ++m) { const int rowg = u.pm * BM + ai * HALF + wr * 64 + m * 16;
;                 const float sc = slots ? rstd_from_slots(slots, rowg + fr, fq) : 1.0f;
;                 u32x4 w[2];
; #pragma unroll
;                 for (int bj = 0; bj < 2; ++bj) { const f32x4 v0 = acc[ai][bj][m][0] * sc, v1 = acc[ai][bj][m][1] * sc;
;                     w[bj].x = cvt_pk_bf16(v0[0], v0[1]); w[bj].y = cvt_pk_bf16(v0[2], v0[3]); w[bj].z = cvt_pk_bf16(v1[0], v1[1]); w[bj].w = cvt_pk_bf16(v1[2], v1[3]); }
;                 wide_store(O, ldc, rowg, col0, fr, w[0], w[1]); }
;     }
;     __device__ __forceinline__ void operator()(const f32x4 (&acc)[2][2][4][2], const Unit& u, int wr, int wc, int fr, int fq) const {
;         const int col0 = u.pn * BM + wc * 64 + 8 * fq;
; #pragma unroll
;         for (int ai = 0; ai < 2; ++ai)
; #pragma unroll
;             for (int m = 0; m < 4; ++m) { const int rowg = u.pm * BM + ai * HALF + wr * 64 + m * 16, row = rowg + fr; const size_t off = (size_t)row * 1024 + col0;
;                 u32x4 w[2]; float ss = 0.f;
; #pragma unroll
;                 for (int bj = 0; bj < 2; ++bj) { f32x4 b0, b1;
;                     if (BASE_F32) { const float* bp = (const float*)base + off + 32 * bj; b0 = *(const f32x4*)bp; b1 = *(const f32x4*)(bp + 4); }
;                     else { const u32x4 bb = *(const u32x4*)((const bf16_t*)base + off + 32 * bj);
.LBB0_1023:
	s_or_b64 exec, exec, s[20:21]
	v_cvt_pk_bf16_f32 v120, v120, v121
	v_cvt_pk_bf16_f32 v112, v112, v113
	v_cvt_pk_bf16_f32 v124, v124, v125
	v_cvt_pk_bf16_f32 v125, v126, v127
	v_cvt_pk_bf16_f32 v121, v122, v123
	v_cvt_pk_bf16_f32 v118, v118, v119
	v_cvt_pk_bf16_f32 v113, v114, v115
	v_cndmask_b32_e64 v115, v120, v112, s[4:5]
	v_mov_b32_e32 v126, v137
	v_cvt_pk_bf16_f32 v122, v116, v117
	v_cndmask_b32_e64 v114, v121, v113, s[4:5]
	v_cndmask_b32_e64 v116, v125, v118, s[4:5]
	v_mov_b32_e32 v119, v137
	v_mov_b32_dpp v126, v115 row_ror:8 row_mask:0xf bank_mask:0xf
	v_mov_b32_e32 v127, v137
	v_cndmask_b32_e64 v117, v124, v122, s[4:5]
	v_mov_b32_e32 v123, v137
	v_mov_b32_dpp v119, v116 row_ror:8 row_mask:0xf bank_mask:0xf
	v_mov_b32_dpp v127, v114 row_ror:8 row_mask:0xf bank_mask:0xf
	v_cndmask_b32_e64 v116, v126, v120, s[4:5]
	v_cndmask_b32_e64 v120, v112, v126, s[4:5]
	v_or_b32_e32 v112, s22, v149
	v_mov_b32_dpp v123, v117 row_ror:8 row_mask:0xf bank_mask:0xf
	v_cndmask_b32_e64 v117, v127, v121, s[4:5]
	v_cndmask_b32_e64 v121, v113, v127, s[4:5]
	v_ashrrev_i32_e32 v113, 31, v112
	v_lshlrev_b64 v[112:113], 11, v[112:113]
	v_cndmask_b32_e64 v115, v119, v125, s[4:5]
	v_cndmask_b32_e64 v114, v123, v124, s[4:5]
	v_cndmask_b32_e64 v119, v118, v119, s[4:5]
	v_cndmask_b32_e64 v118, v122, v123, s[4:5]
	v_lshl_add_u64 v[122:123], s[30:31], 0, v[112:113]
	v_lshlrev_b64 v[112:113], 1, v[142:143]
	v_lshl_add_u64 v[122:123], v[122:123], 0, v[112:113]
	v_lshl_add_u64 v[122:123], v[122:123], 0, v[136:137]
	s_cmp_lg_u64 s[36:37], 0
	s_cbranch_scc0 .LBB0_1021
	s_barrier
.LBB0_1021:
	global_store_dwordx4 v[122:123], v[114:117], off nt
	s_or_b32 s23, s22, 16
	s_nop 0
	v_add_co_u32_e32 v114, vcc, s62, v122
	s_nop 1
	v_addc_co_u32_e32 v115, vcc, 0, v123, vcc
	global_store_dwordx4 v[114:115], v[118:121], off nt
	v_or_b32_e32 v114, s23, v146
	v_ashrrev_i32_e32 v115, 31, v114
	v_lshlrev_b64 v[116:117], 11, v[114:115]
	v_lshl_add_u64 v[116:117], s[30:31], 0, v[116:117]
	v_lshl_add_u64 v[120:121], v[116:117], 0, v[112:113]
	global_load_dwordx4 v[116:119], v[120:121], off
	s_nop 0
	global_load_dwordx4 v[120:123], v[120:121], off offset:64
	s_waitcnt vmcnt(1)
	v_lshlrev_b32_e32 v124, 16, v116
	v_and_b32_e32 v125, 0xffff0000, v116
	v_lshlrev_b32_e32 v116, 16, v117
	v_and_b32_e32 v117, 0xffff0000, v117
	v_lshlrev_b32_e32 v126, 16, v118
	v_and_b32_e32 v127, 0xffff0000, v118
	v_lshlrev_b32_e32 v118, 16, v119
	v_and_b32_e32 v119, 0xffff0000, v119
	s_waitcnt vmcnt(0)
	v_lshlrev_b32_e32 v144, 16, v120
	v_and_b32_e32 v145, 0xffff0000, v120
	v_lshlrev_b32_e32 v120, 16, v121
	v_and_b32_e32 v121, 0xffff0000, v121
	v_lshlrev_b32_e32 v158, 16, v122
	s_waitcnt lgkmcnt(0)
	v_and_b32_e32 v159, 0xffff0000, v122
	v_lshlrev_b32_e32 v122, 16, v123
	v_and_b32_e32 v123, 0xffff0000, v123
	v_pk_add_f32 v[110:111], v[110:111], v[116:117]
	v_pk_add_f32 v[108:109], v[108:109], v[124:125]
	v_pk_add_f32 v[106:107], v[106:107], v[118:119]
	v_pk_add_f32 v[104:105], v[104:105], v[126:127]
	v_pk_add_f32 v[102:103], v[102:103], v[120:121]
	v_pk_add_f32 v[100:101], v[100:101], v[144:145]
	v_pk_add_f32 v[98:99], v[98:99], v[122:123]
	v_pk_add_f32 v[96:97], v[96:97], v[158:159]
	v_mul_f32_e32 v116, v109, v109
	v_mul_f32_e32 v117, v111, v111
	v_mul_f32_e32 v118, v105, v105
	v_mul_f32_e32 v119, v107, v107
	v_mul_f32_e32 v120, v101, v101
	v_mul_f32_e32 v121, v103, v103
	v_mul_f32_e32 v122, v97, v97
	v_mul_f32_e32 v123, v99, v99
	v_fmac_f32_e32 v116, v108, v108
	v_fmac_f32_e32 v117, v110, v110
	v_fmac_f32_e32 v118, v104, v104
	v_fmac_f32_e32 v119, v106, v106
	v_fmac_f32_e32 v120, v100, v100
	v_fmac_f32_e32 v121, v102, v102
	v_fmac_f32_e32 v122, v96, v96
	v_fmac_f32_e32 v123, v98, v98
	v_add_f32_e32 v116, v116, v117
	v_add_f32_e32 v117, v118, v119
	v_add_f32_e32 v118, v120, v121
	v_add_f32_e32 v119, v122, v123
	v_add_f32_e32 v116, v116, v117
	v_add_f32_e32 v117, v118, v119
	v_add_f32_e32 v116, v116, v117
	ds_bpermute_b32 v117, v156, v116
	s_waitcnt lgkmcnt(0)
	v_add_f32_e32 v116, v116, v117
	ds_bpermute_b32 v117, v157, v116
	s_and_saveexec_b64 s[20:21], s[2:3]
	s_cbranch_execz .LBB0_1025
	v_lshlrev_b64 v[114:115], 6, v[114:115]
	v_lshl_add_u64 v[114:115], s[82:83], 0, v[114:115]
	v_lshl_add_u64 v[114:115], s[0:1], 2, v[114:115]
	s_lshl_b32 s14, s63, 2
	v_lshl_add_u64 v[114:115], v[114:115], 0, s[14:15]
	s_waitcnt lgkmcnt(0)
	v_add_f32_e32 v116, v116, v117
	global_store_dword v[114:115], v116, off

; #define PG8_STAGE(bufoff, gbase, voff) do { _Pragma("unroll") for (int _i = 0; _i < 2; ++_i) \
;         __builtin_amdgcn_global_load_lds((const unsigned*)((const char*)(gbase) + (voff)[_i]), (PG8_LAS unsigned*)(lds + (bufoff) + ldsw + _i * 8192), 16, 0, PG8_LOAD_AUX); } while (0)
; #define PG8_LDA(dst, b, h) do { _Pragma("unroll") for (int m = 0; m < 4; ++m) _Pragma("unroll") for (int k = 0; k < 2; ++k) dst[m][k] = *(const PG8_LAS bf16x8*)(lds + PG8_SA(b, h) + aoff + m * 2048 + k * 1024); } while (0)
; #define PG8_LDB(dst, b, h) do { _Pragma("unroll") for (int n = 0; n < 2; ++n) _Pragma("unroll") for (int k = 0; k < 2; ++k) dst[n][k] = *(const PG8_LAS bf16x8*)(lds + PG8_SB(b, h) + boff + n * 2048 + k * 1024); } while (0)
; #define PG8_MMA(ai, bj, At, Bt) do { __builtin_amdgcn_s_setprio(1); _Pragma("unroll") for (int m = 0; m < 4; ++m) _Pragma("unroll") for (int n = 0; n < 2; ++n) _Pragma("unroll") for (int k = 0; k < 2; ++k) \
;         acc[ai][bj][m][n] = __builtin_amdgcn_mfma_f32_16x16x32_bf16(Bt[n][k], At[m][k], acc[ai][bj][m][n], 0, 0, 0); __builtin_amdgcn_s_setprio(0); } while (0)
; #define PG8_WAIT_V(n) asm volatile("s_waitcnt vmcnt(" #n ")" ::: "memory")
; #define PG8_WAIT_L(n) asm volatile("s_waitcnt lgkmcnt(" #n ")" ::: "memory")
; #define PG8_BAR __builtin_amdgcn_s_barrier()
; #define PG8_SCHED __builtin_amdgcn_sched_barrier(0)
; template <class Epi, class Sched, bool ALIGN_EPI = false, bool SP2 = false>
; __device__ __forceinline__ void gemm_phase(PG8_LAS unsigned char* lds, const Gemm g, const Sched& S, const Epi& E) {
;     ...
;             PG8_LDB(B0, 1, 0); PG8_LDB(B1, 1, 1); PG8_SCHED; PG8_LDA(At, 1, 0); PG8_STAGE(PG8_SA(0, 1), a2 + hstepA, voffA);
;             PG8_WAIT_V(8); PG8_WAIT_L(0); PG8_BAR; PG8_MMA(0, 0, At, B0); PG8_MMA(0, 1, At, B1); PG8_BAR; PG8_SCHED;
;             PG8_LDA(At, 1, 1); PG8_STAGE(PG8_SB(1, 0), b3, voffB); PG8_STAGE(PG8_SB(1, 1), b3 + hstepB, voffB); PG8_STAGE(PG8_SA(1, 0), a3, voffA);
;             PG8_WAIT_V(8); PG8_WAIT_L(0); PG8_BAR; PG8_MMA(1, 0, At, B0); PG8_MMA(1, 1, At, B1); PG8_BAR; PG8_SCHED;
.Lkmid_P12:
	s_add_i32 s29, 0, 0x18000
	s_add_i32 s33, 0, 0x1c000
	v_add_u32_e32 v170, s29, v155
	v_add_u32_e32 v186, s33, v155
	ds_read_b128 v[146:149], v170
	ds_read_b128 v[162:165], v170 offset:1024
	ds_read_b128 v[166:169], v170 offset:2048
	ds_read_b128 v[170:173], v170 offset:3072
	ds_read_b128 v[174:177], v186
	ds_read_b128 v[178:181], v186 offset:1024
	ds_read_b128 v[182:185], v186 offset:2048
	ds_read_b128 v[186:189], v186 offset:3072
	s_add_u32 s30, s34, 0x40000
	s_addc_u32 s31, s35, 0
	s_mov_b32 m0, s47
	v_lshl_add_u64 v[228:229], s[30:31], 0, v[134:135]
	ds_read_b128 v[190:193], v159 offset:32768
	ds_read_b128 v[194:197], v159 offset:33792
	ds_read_b128 v[198:201], v159 offset:34816
	ds_read_b128 v[202:205], v159 offset:35840
	ds_read_b128 v[206:209], v159 offset:36864
	ds_read_b128 v[210:213], v159 offset:37888
	ds_read_b128 v[214:217], v159 offset:38912
	ds_read_b128 v[218:221], v159 offset:39936
	global_load_lds_dwordx4 v[228:229], off
	v_lshl_add_u64 v[228:229], s[30:31], 0, v[130:131]
	s_mov_b32 m0, s48
	s_nop 0
	global_load_lds_dwordx4 v[228:229], off
	s_waitcnt vmcnt(8)
	s_waitcnt lgkmcnt(0)
	s_barrier
	s_setprio 1
	s_waitcnt lgkmcnt(0)
	v_mfma_f32_16x16x32_bf16 v[124:127], v[146:149], v[190:193], v[124:127]
	v_mfma_f32_16x16x32_bf16 v[120:123], v[166:169], v[190:193], v[120:123]
	v_mfma_f32_16x16x32_bf16 v[108:111], v[146:149], v[198:201], v[108:111]
	v_mfma_f32_16x16x32_bf16 v[104:107], v[166:169], v[198:201], v[104:107]
	v_mfma_f32_16x16x32_bf16 v[92:95], v[146:149], v[206:209], v[92:95]
	v_mfma_f32_16x16x32_bf16 v[88:91], v[166:169], v[206:209], v[88:91]
	v_mfma_f32_16x16x32_bf16 v[76:79], v[146:149], v[214:217], v[76:79]
	v_mfma_f32_16x16x32_bf16 v[72:75], v[166:169], v[214:217], v[72:75]
	v_mfma_f32_16x16x32_bf16 v[124:127], v[162:165], v[194:197], v[124:127]
	v_mfma_f32_16x16x32_bf16 v[120:123], v[170:173], v[194:197], v[120:123]
	v_mfma_f32_16x16x32_bf16 v[108:111], v[162:165], v[202:205], v[108:111]
	v_mfma_f32_16x16x32_bf16 v[104:107], v[170:173], v[202:205], v[104:107]
	v_mfma_f32_16x16x32_bf16 v[92:95], v[162:165], v[210:213], v[92:95]
	v_mfma_f32_16x16x32_bf16 v[88:91], v[170:173], v[210:213], v[88:91]
	v_mfma_f32_16x16x32_bf16 v[76:79], v[162:165], v[218:221], v[76:79]
	v_mfma_f32_16x16x32_bf16 v[72:75], v[170:173], v[218:221], v[72:75]
	s_setprio 0
	s_setprio 1
	v_mfma_f32_16x16x32_bf16 v[116:119], v[174:177], v[190:193], v[116:119]
	v_mfma_f32_16x16x32_bf16 v[112:115], v[182:185], v[190:193], v[112:115]
	v_mfma_f32_16x16x32_bf16 v[100:103], v[174:177], v[198:201], v[100:103]
	v_mfma_f32_16x16x32_bf16 v[96:99], v[182:185], v[198:201], v[96:99]
	v_mfma_f32_16x16x32_bf16 v[84:87], v[174:177], v[206:209], v[84:87]
	v_mfma_f32_16x16x32_bf16 v[80:83], v[182:185], v[206:209], v[80:83]
	v_mfma_f32_16x16x32_bf16 v[68:71], v[174:177], v[214:217], v[68:71]
	v_mfma_f32_16x16x32_bf16 v[64:67], v[182:185], v[214:217], v[64:67]
	v_mfma_f32_16x16x32_bf16 v[116:119], v[178:181], v[194:197], v[116:119]
	v_mfma_f32_16x16x32_bf16 v[112:115], v[186:189], v[194:197], v[112:115]
	v_mfma_f32_16x16x32_bf16 v[100:103], v[178:181], v[202:205], v[100:103]
	v_mfma_f32_16x16x32_bf16 v[96:99], v[186:189], v[202:205], v[96:99]
	v_mfma_f32_16x16x32_bf16 v[84:87], v[178:181], v[210:213], v[84:87]
	v_mfma_f32_16x16x32_bf16 v[80:83], v[186:189], v[210:213], v[80:83]
	v_mfma_f32_16x16x32_bf16 v[68:71], v[178:181], v[218:221], v[68:71]
	v_mfma_f32_16x16x32_bf16 v[64:67], v[186:189], v[218:221], v[64:67]
	s_setprio 0
	s_barrier
	s_add_i32 s29, s29, s42
	v_lshl_add_u64 v[150:151], v[150:151], 0, s[8:9]
	s_mov_b32 m0, s29
	ds_read_b128 v[190:193], v159 offset:49152
	ds_read_b128 v[194:197], v159 offset:50176
	ds_read_b128 v[198:201], v159 offset:51200
	ds_read_b128 v[202:205], v159 offset:52224
	ds_read_b128 v[206:209], v159 offset:53248
	ds_read_b128 v[210:213], v159 offset:54272
	ds_read_b128 v[214:217], v159 offset:55296
	ds_read_b128 v[218:221], v159 offset:56320
	global_load_lds_dwordx4 v[150:151], off
	s_add_i32 m0, s29, 0x2000
	s_add_u32 s22, s22, 0x40080
	v_lshl_add_u64 v[150:151], v[222:223], 0, s[8:9]
	s_addc_u32 s23, s23, 0
	s_add_i32 s29, s33, s42
	global_load_lds_dwordx4 v[150:151], off
	v_lshl_add_u64 v[150:151], s[22:23], 0, v[132:133]
	s_mov_b32 m0, s29
	s_nop 0
	global_load_lds_dwordx4 v[150:151], off
	v_lshl_add_u64 v[150:151], s[22:23], 0, v[128:129]
	s_add_i32 m0, s29, 0x2000
	s_nop 0
	global_load_lds_dwordx4 v[150:151], off
	v_lshl_add_u64 v[150:151], v[224:225], 0, s[8:9]
	s_mov_b32 m0, s50
	s_nop 0
	global_load_lds_dwordx4 v[150:151], off
	v_lshl_add_u64 v[150:151], v[226:227], 0, s[8:9]
	s_mov_b32 m0, s51
	s_nop 0
	global_load_lds_dwordx4 v[150:151], off
	s_waitcnt vmcnt(8)
	s_waitcnt lgkmcnt(0)
	s_barrier
; __device__ __forceinline__ float rstd_from_slots(const float* slots, int row, int fq) {
;     const f32x4 s4 = *(const f32x4*)(slots + (size_t)row * 16 + 4 * fq);
;     float s = (s4[0] + s4[1]) + (s4[2] + s4[3]);
;     s += __shfl_xor(s, 16); s += __shfl_xor(s, 32);
;     return __builtin_amdgcn_rsqf(s * (1.0f / 1024.0f) + RMS_EPS_F);
; }
;     __device__ __forceinline__ void operator()(const f32x4 (&acc)[2][2][4][2], const Unit& u, int wr, int wc, int fr, int fq) const {
;         const int row0 = u.pm * BM + wr * 64 + fr; const int col0 = u.pn * BM + wc * 32 + 8 * fq;
; #pragma unroll
;         for (int ai = 0; ai < 2; ++ai)
; #pragma unroll
;             for (int m = 0; m < 4; ++m) { const int row = row0 + ai * HALF + m * 16; bf16_t* rowp = O + (size_t)row * ldc + col0;
;                 const float sc = slots ? rstd_from_slots(slots, row, fq) : 1.0f;
; #pragma unroll
;                 for (int bj = 0; bj < 2; ++bj) { const f32x4 v0 = acc[ai][bj][m][0] * sc, v1 = acc[ai][bj][m][1] * sc;
;                     u32x4 w; w.x = cvt_pk_bf16(v0[0], v0[1]); w.y = cvt_pk_bf16(v0[2], v0[3]); w.z = cvt_pk_bf16(v1[0], v1[1]); w.w = cvt_pk_bf16(v1[2], v1[3]);
;                     *(u32x4*)(rowp + bj * HALF) = w; } }
;     }
; __device__ __forceinline__ float silu_mul(float g, float u) { return g * u * __builtin_amdgcn_rcpf(1.0f + __builtin_amdgcn_exp2f(g * -1.4426950408889634f)); }
;     __device__ __forceinline__ void operator()(const f32x4 (&acc)[2][2][4][2], const Unit& u, int wr, int wc, int fr, int fq) const {
; template <class Epi, class Sched, bool ALIGN_EPI = false, bool SP2 = false>
; __device__ __forceinline__ void gemm_phase(PG8_LAS unsigned char* lds, const Gemm g, const Sched& S, const Epi& E) {
;     ...
;             PG8_WAIT_V(8); PG8_WAIT_L(0); PG8_BAR; PG8_MMA(1, 0, At, B0); PG8_MMA(1, 1, At, B1); PG8_BAR; PG8_SCHED;
;             PG8_LDB(B0, 1, 0); PG8_LDB(B1, 1, 1); PG8_SCHED; PG8_LDA(At, 1, 0); PG8_STAGE(PG8_SA(0, 1), a2 + hstepA, voffA);
;             PG8_WAIT_V(8); PG8_WAIT_L(0); PG8_BAR; PG8_MMA(0, 0, At, B0); PG8_MMA(0, 1, At, B1); PG8_BAR; PG8_SCHED;
;             PG8_LDA(At, 1, 1); PG8_STAGE(PG8_SB(1, 0), b3, voffB); PG8_STAGE(PG8_SB(1, 1), b3 + hstepB, voffB); PG8_STAGE(PG8_SA(1, 0), a3, voffA);
;             PG8_WAIT_V(8); PG8_WAIT_L(0); PG8_BAR; PG8_MMA(1, 0, At, B0); PG8_MMA(1, 1, At, B1); PG8_BAR; PG8_SCHED;
	s_setprio 1
	s_waitcnt lgkmcnt(0)
	v_mfma_f32_16x16x32_bf16 v[60:63], v[146:149], v[190:193], v[60:63]
	v_mfma_f32_16x16x32_bf16 v[56:59], v[166:169], v[190:193], v[56:59]
	v_mfma_f32_16x16x32_bf16 v[44:47], v[146:149], v[198:201], v[44:47]
	v_mfma_f32_16x16x32_bf16 v[40:43], v[166:169], v[198:201], v[40:43]
	v_mfma_f32_16x16x32_bf16 v[28:31], v[146:149], v[206:209], v[28:31]
	v_mfma_f32_16x16x32_bf16 v[24:27], v[166:169], v[206:209], v[24:27]
	v_mfma_f32_16x16x32_bf16 v[12:15], v[146:149], v[214:217], v[12:15]
	v_mfma_f32_16x16x32_bf16 v[8:11], v[166:169], v[214:217], v[8:11]
	v_mfma_f32_16x16x32_bf16 v[60:63], v[162:165], v[194:197], v[60:63]
	v_mfma_f32_16x16x32_bf16 v[56:59], v[170:173], v[194:197], v[56:59]
	v_mfma_f32_16x16x32_bf16 v[44:47], v[162:165], v[202:205], v[44:47]
	v_mfma_f32_16x16x32_bf16 v[40:43], v[170:173], v[202:205], v[40:43]
	v_mfma_f32_16x16x32_bf16 v[28:31], v[162:165], v[210:213], v[28:31]
	v_mfma_f32_16x16x32_bf16 v[24:27], v[170:173], v[210:213], v[24:27]
	v_mfma_f32_16x16x32_bf16 v[12:15], v[162:165], v[218:221], v[12:15]
	v_mfma_f32_16x16x32_bf16 v[8:11], v[170:173], v[218:221], v[8:11]
	s_setprio 0
	s_setprio 1
	v_mfma_f32_16x16x32_bf16 v[52:55], v[174:177], v[190:193], v[52:55]
	v_mfma_f32_16x16x32_bf16 v[48:51], v[182:185], v[190:193], v[48:51]
	v_mfma_f32_16x16x32_bf16 v[36:39], v[174:177], v[198:201], v[36:39]
	v_mfma_f32_16x16x32_bf16 v[32:35], v[182:185], v[198:201], v[32:35]
	v_mfma_f32_16x16x32_bf16 v[20:23], v[174:177], v[206:209], v[20:23]
	v_mfma_f32_16x16x32_bf16 v[16:19], v[182:185], v[206:209], v[16:19]
	v_mfma_f32_16x16x32_bf16 v[4:7], v[174:177], v[214:217], v[4:7]
	v_mfma_f32_16x16x32_bf16 v[0:3], v[182:185], v[214:217], v[0:3]
	v_mfma_f32_16x16x32_bf16 v[52:55], v[178:181], v[194:197], v[52:55]
	v_mfma_f32_16x16x32_bf16 v[48:51], v[186:189], v[194:197], v[48:51]
	v_mfma_f32_16x16x32_bf16 v[36:39], v[178:181], v[202:205], v[36:39]
	v_mfma_f32_16x16x32_bf16 v[32:35], v[186:189], v[202:205], v[32:35]
	v_mfma_f32_16x16x32_bf16 v[20:23], v[178:181], v[210:213], v[20:23]
	v_mfma_f32_16x16x32_bf16 v[16:19], v[186:189], v[210:213], v[16:19]
	v_mfma_f32_16x16x32_bf16 v[4:7], v[178:181], v[218:221], v[4:7]
	v_mfma_f32_16x16x32_bf16 v[0:3], v[186:189], v[218:221], v[0:3]
	s_setprio 0
	s_barrier
	s_add_i32 s28, s28, 2
	s_add_u32 s20, s20, 0x100
	s_addc_u32 s21, s21, 0
	s_add_u32 s26, s26, 0x100
	s_addc_u32 s27, s27, 0
	s_cmp_gt_u32 s28, 13
	s_cbranch_scc0 .LBB0_1111
	v_lshl_add_u32 v204, s0, 8, v152
	v_ashrrev_i32_e32 v205, 31, v204
	v_lshlrev_b64 v[204:205], 6, v[204:205]
	v_lshl_add_u64 v[204:205], v[136:137], 0, v[204:205]
	v_add_co_u32_e32 v206, vcc, 0x2000, v204
	s_nop 1
	v_addc_co_u32_e32 v207, vcc, 0, v205, vcc
	global_load_dwordx4 v[172:175], v[204:205], off
	global_load_dwordx4 v[176:179], v[204:205], off offset:1024
	global_load_dwordx4 v[180:183], v[204:205], off offset:2048
	global_load_dwordx4 v[184:187], v[204:205], off offset:3072
	global_load_dwordx4 v[188:191], v[206:207], off
	global_load_dwordx4 v[192:195], v[206:207], off offset:1024
	global_load_dwordx4 v[196:199], v[206:207], off offset:2048
	global_load_dwordx4 v[200:203], v[206:207], off offset:3072
	v_lshl_add_u32 v150, s0, 8, v152
	v_ashrrev_i32_e32 v151, 31, v150
	v_lshlrev_b64 v[146:147], 6, v[150:151]
	v_lshl_add_u64 v[146:147], v[136:137], 0, v[146:147]
	v_and_b32_e32 v151, 64, v160
	v_xor_b32_e32 v149, 16, v160
	v_add_u32_e32 v169, 64, v151
	v_cmp_lt_i32_e32 vcc, v149, v169
	v_xor_b32_e32 v168, 32, v160
	v_lshl_or_b32 v148, s1, 7, v156
	v_cndmask_b32_e32 v149, v160, v149, vcc
	v_lshlrev_b32_e32 v151, 2, v149
	v_cmp_lt_i32_e32 vcc, v168, v169
	v_mov_b64_e32 v[146:147], s[10:11]
	v_ashrrev_i32_e32 v149, 31, v148
	v_lshlrev_b64 v[148:149], 1, v[148:149]
	s_waitcnt vmcnt(7)
	v_mov_b32_e32 v162, v172
	v_mov_b32_e32 v163, v173
	v_mov_b32_e32 v164, v174
	v_mov_b32_e32 v165, v175
	v_mov_b32_e32 v166, v163
	v_mov_b32_e32 v167, v164
	v_mov_b32_e32 v163, v165
	v_pk_add_f32 v[162:163], v[166:167], v[162:163]
	v_or_b32_e32 v166, 16, v150
	v_add_f32_e32 v163, v162, v163
	ds_bpermute_b32 v164, v151, v163
	v_cndmask_b32_e32 v162, v160, v168, vcc
	v_lshlrev_b32_e32 v162, 2, v162
	v_ashrrev_i32_e32 v167, 31, v166
	v_lshlrev_b64 v[170:171], 6, v[166:167]
	s_waitcnt lgkmcnt(0)
	v_add_f32_e32 v163, v163, v164
	ds_bpermute_b32 v168, v162, v163
	v_mad_i64_i32 v[164:165], s[0:1], v150, s56, v[146:147]
	v_lshl_add_u64 v[164:165], v[164:165], 0, v[148:149]
	v_lshl_add_u64 v[170:171], v[136:137], 0, v[170:171]
	s_waitcnt lgkmcnt(0)
	v_add_f32_e32 v163, v163, v168
	v_fmamk_f32 v163, v163, 0x3a800000, v161
	v_rsq_f32_e32 v168, v163
	s_andn2_b64 vcc, exec, s[2:3]
	v_pk_mul_f32 v[126:127], v[126:127], v[168:169] op_sel_hi:[1,0]
	v_pk_mul_f32 v[124:125], v[124:125], v[168:169] op_sel_hi:[1,0]
	v_pk_mul_f32 v[122:123], v[122:123], v[168:169] op_sel_hi:[1,0]
	v_pk_mul_f32 v[120:121], v[120:121], v[168:169] op_sel_hi:[1,0]
	v_pk_mul_f32 v[116:117], v[116:117], v[168:169] op_sel_hi:[1,0]
	v_pk_mul_f32 v[118:119], v[118:119], v[168:169] op_sel_hi:[1,0]
	v_pk_mul_f32 v[112:113], v[112:113], v[168:169] op_sel_hi:[1,0]
	v_pk_mul_f32 v[114:115], v[114:115], v[168:169] op_sel_hi:[1,0]
	v_mul_f32_e32 v163, 0xbfb8aa3b, v124
	v_mul_f32_e32 v167, 0xbfb8aa3b, v125
	v_pk_mul_f32 v[118:119], v[126:127], v[118:119]
	v_pk_mul_f32 v[116:117], v[124:125], v[116:117]
	v_mul_f32_e32 v124, 0xbfb8aa3b, v126
	v_mul_f32_e32 v125, 0xbfb8aa3b, v127
	v_mul_f32_e32 v126, 0xbfb8aa3b, v120
	v_mul_f32_e32 v127, 0xbfb8aa3b, v121
	v_pk_mul_f32 v[112:113], v[120:121], v[112:113]
	v_mul_f32_e32 v120, 0xbfb8aa3b, v122
	v_mul_f32_e32 v121, 0xbfb8aa3b, v123
	v_pk_mul_f32 v[114:115], v[122:123], v[114:115]
	v_exp_f32_e32 v122, v163
	v_exp_f32_e32 v123, v167
	v_exp_f32_e32 v124, v124
	v_exp_f32_e32 v125, v125
	v_exp_f32_e32 v126, v126
	v_exp_f32_e32 v127, v127
	v_exp_f32_e32 v120, v120
	v_exp_f32_e32 v121, v121
	v_add_f32_e32 v122, 1.0, v122
	v_add_f32_e32 v123, 1.0, v123
	v_add_f32_e32 v124, 1.0, v124
	v_add_f32_e32 v125, 1.0, v125
	v_add_f32_e32 v126, 1.0, v126
	v_add_f32_e32 v127, 1.0, v127
	v_add_f32_e32 v163, 1.0, v120
	v_add_f32_e32 v167, 1.0, v121
	v_rcp_f32_e32 v120, v122
	v_rcp_f32_e32 v121, v123
	v_rcp_f32_e32 v122, v124
	v_rcp_f32_e32 v123, v125
	v_rcp_f32_e32 v124, v126
	v_rcp_f32_e32 v125, v127
	v_rcp_f32_e32 v126, v163
	v_rcp_f32_e32 v127, v167
	v_pk_mul_f32 v[116:117], v[116:117], v[120:121]
	v_pk_mul_f32 v[118:119], v[118:119], v[122:123]
	v_pk_mul_f32 v[120:121], v[112:113], v[124:125]
	v_pk_mul_f32 v[122:123], v[114:115], v[126:127]
	v_cvt_pk_bf16_f32 v112, v116, v117
	v_cvt_pk_bf16_f32 v113, v118, v119
	v_cvt_pk_bf16_f32 v114, v120, v121
	v_cvt_pk_bf16_f32 v115, v122, v123
	s_cmp_lg_u64 s[12:13], 0
	s_cbranch_scc0 .LBB0_1114
	s_barrier
; __device__ __forceinline__ float rstd_from_slots(const float* slots, int row, int fq) {
;     const f32x4 s4 = *(const f32x4*)(slots + (size_t)row * 16 + 4 * fq);
;     float s = (s4[0] + s4[1]) + (s4[2] + s4[3]);
;     s += __shfl_xor(s, 16); s += __shfl_xor(s, 32);
;     return __builtin_amdgcn_rsqf(s * (1.0f / 1024.0f) + RMS_EPS_F);
; }
;     __device__ __forceinline__ void operator()(const f32x4 (&acc)[2][2][4][2], const Unit& u, int wr, int wc, int fr, int fq) const {
;         const int row0 = u.pm * BM + wr * 64 + fr; const int col0 = u.pn * BM + wc * 32 + 8 * fq;
; #pragma unroll
;         for (int ai = 0; ai < 2; ++ai)
; #pragma unroll
;             for (int m = 0; m < 4; ++m) { const int row = row0 + ai * HALF + m * 16; bf16_t* rowp = O + (size_t)row * ldc + col0;
;                 const float sc = slots ? rstd_from_slots(slots, row, fq) : 1.0f;
; #pragma unroll
;                 for (int bj = 0; bj < 2; ++bj) { const f32x4 v0 = acc[ai][bj][m][0] * sc, v1 = acc[ai][bj][m][1] * sc;
;                     u32x4 w; w.x = cvt_pk_bf16(v0[0], v0[1]); w.y = cvt_pk_bf16(v0[2], v0[3]); w.z = cvt_pk_bf16(v1[0], v1[1]); w.w = cvt_pk_bf16(v1[2], v1[3]);
;                     *(u32x4*)(rowp + bj * HALF) = w; } }
;     }
; __device__ __forceinline__ float silu_mul(float g, float u) { return g * u * __builtin_amdgcn_rcpf(1.0f + __builtin_amdgcn_exp2f(g * -1.4426950408889634f)); }
;     __device__ __forceinline__ void operator()(const f32x4 (&acc)[2][2][4][2], const Unit& u, int wr, int wc, int fr, int fq) const {
;         const int row0 = u.pm * BM + wr * 64 + fr; const int col0 = u.pn * HALF + wc * 32 + 8 * fq;
; #pragma unroll
;         for (int ai = 0; ai < 2; ++ai)
; #pragma unroll
;             for (int m = 0; m < 4; ++m) { const int row = row0 + ai * HALF + m * 16;
;                 const float sc = rstd_from_slots(slots, row, fq);
;                 const f32x4 g0 = acc[ai][0][m][0] * sc, g1 = acc[ai][0][m][1] * sc, u0 = acc[ai][1][m][0] * sc, u1 = acc[ai][1][m][1] * sc;
;                 u32x4 w; w.x = cvt_pk_bf16(silu_mul(g0[0], u0[0]), silu_mul(g0[1], u0[1])); w.y = cvt_pk_bf16(silu_mul(g0[2], u0[2]), silu_mul(g0[3], u0[3]));
;                 w.z = cvt_pk_bf16(silu_mul(g1[0], u1[0]), silu_mul(g1[1], u1[1])); w.w = cvt_pk_bf16(silu_mul(g1[2], u1[2]), silu_mul(g1[3], u1[3]));
.LBB0_1114:
	global_store_dwordx4 v[164:165], v[112:115], off nt
	s_nop 1
	s_waitcnt vmcnt(7)
	v_mov_b32_e32 v112, v176
	v_mov_b32_e32 v113, v177
	v_mov_b32_e32 v114, v178
	v_mov_b32_e32 v115, v179
	v_mov_b32_e32 v116, v113
	v_mov_b32_e32 v117, v114
	v_mov_b32_e32 v113, v115
	v_pk_add_f32 v[112:113], v[116:117], v[112:113]
	v_mad_i64_i32 v[114:115], s[0:1], v166, s56, v[146:147]
	v_add_f32_e32 v112, v112, v113
	ds_bpermute_b32 v113, v151, v112
	v_lshl_add_u64 v[114:115], v[114:115], 0, v[148:149]
	s_waitcnt lgkmcnt(0)
	v_add_f32_e32 v116, v112, v113
	ds_bpermute_b32 v117, v162, v116
	v_or_b32_e32 v112, 32, v150
	v_ashrrev_i32_e32 v113, 31, v112
	v_lshlrev_b64 v[118:119], 6, v[112:113]
	v_lshl_add_u64 v[118:119], v[136:137], 0, v[118:119]
	s_waitcnt lgkmcnt(0)
	v_add_f32_e32 v116, v116, v117
	v_fmamk_f32 v116, v116, 0x3a800000, v161
	v_rsq_f32_e32 v116, v116
	s_nop 0
	v_pk_mul_f32 v[110:111], v[110:111], v[116:117] op_sel_hi:[1,0]
	v_pk_mul_f32 v[108:109], v[108:109], v[116:117] op_sel_hi:[1,0]
	v_pk_mul_f32 v[106:107], v[106:107], v[116:117] op_sel_hi:[1,0]
	v_pk_mul_f32 v[104:105], v[104:105], v[116:117] op_sel_hi:[1,0]
	v_pk_mul_f32 v[100:101], v[100:101], v[116:117] op_sel_hi:[1,0]
	v_pk_mul_f32 v[102:103], v[102:103], v[116:117] op_sel_hi:[1,0]
	v_pk_mul_f32 v[96:97], v[96:97], v[116:117] op_sel_hi:[1,0]
	v_pk_mul_f32 v[98:99], v[98:99], v[116:117] op_sel_hi:[1,0]
	v_mul_f32_e32 v113, 0xbfb8aa3b, v108
	v_mul_f32_e32 v116, 0xbfb8aa3b, v109
	v_pk_mul_f32 v[102:103], v[110:111], v[102:103]
	v_pk_mul_f32 v[100:101], v[108:109], v[100:101]
	v_mul_f32_e32 v108, 0xbfb8aa3b, v110
	v_mul_f32_e32 v109, 0xbfb8aa3b, v111
	v_mul_f32_e32 v110, 0xbfb8aa3b, v104
	v_mul_f32_e32 v111, 0xbfb8aa3b, v105
	v_pk_mul_f32 v[96:97], v[104:105], v[96:97]
	v_mul_f32_e32 v104, 0xbfb8aa3b, v106
	v_mul_f32_e32 v105, 0xbfb8aa3b, v107
	v_pk_mul_f32 v[98:99], v[106:107], v[98:99]
	v_exp_f32_e32 v106, v113
	v_exp_f32_e32 v107, v116
	v_exp_f32_e32 v108, v108
	v_exp_f32_e32 v109, v109
	v_exp_f32_e32 v110, v110
	v_exp_f32_e32 v111, v111
	v_exp_f32_e32 v104, v104
	v_exp_f32_e32 v105, v105
	v_add_f32_e32 v106, 1.0, v106
	v_add_f32_e32 v107, 1.0, v107
	v_add_f32_e32 v108, 1.0, v108
	v_add_f32_e32 v109, 1.0, v109
	v_add_f32_e32 v110, 1.0, v110
	v_add_f32_e32 v111, 1.0, v111
	v_add_f32_e32 v113, 1.0, v104
	v_add_f32_e32 v116, 1.0, v105
	v_rcp_f32_e32 v104, v106
	v_rcp_f32_e32 v105, v107
	v_rcp_f32_e32 v106, v108
	v_rcp_f32_e32 v107, v109
	v_rcp_f32_e32 v108, v110
	v_rcp_f32_e32 v109, v111
	v_rcp_f32_e32 v110, v113
	v_rcp_f32_e32 v111, v116
	v_pk_mul_f32 v[100:101], v[100:101], v[104:105]
	v_pk_mul_f32 v[102:103], v[102:103], v[106:107]
	v_pk_mul_f32 v[104:105], v[96:97], v[108:109]
	v_pk_mul_f32 v[106:107], v[98:99], v[110:111]
	v_cvt_pk_bf16_f32 v96, v100, v101
	v_cvt_pk_bf16_f32 v97, v102, v103
	v_cvt_pk_bf16_f32 v98, v104, v105
	v_cvt_pk_bf16_f32 v99, v106, v107
	global_store_dwordx4 v[114:115], v[96:99], off nt
	s_nop 1
	s_waitcnt vmcnt(7)
	v_mov_b32_e32 v96, v180
	v_mov_b32_e32 v97, v181
	v_mov_b32_e32 v98, v182
	v_mov_b32_e32 v99, v183
	v_mov_b32_e32 v100, v97
	v_mov_b32_e32 v101, v98
	v_mov_b32_e32 v97, v99
	v_pk_add_f32 v[96:97], v[100:101], v[96:97]
	v_mad_i64_i32 v[98:99], s[0:1], v112, s56, v[146:147]
	v_add_f32_e32 v96, v96, v97
	ds_bpermute_b32 v97, v151, v96
	v_lshl_add_u64 v[98:99], v[98:99], 0, v[148:149]
	s_waitcnt lgkmcnt(0)
	v_add_f32_e32 v100, v96, v97
	ds_bpermute_b32 v101, v162, v100
	v_or_b32_e32 v96, 48, v150
	v_ashrrev_i32_e32 v97, 31, v96
	v_lshlrev_b64 v[102:103], 6, v[96:97]
	v_lshl_add_u64 v[102:103], v[136:137], 0, v[102:103]
	s_waitcnt lgkmcnt(0)
	v_add_f32_e32 v100, v100, v101
	v_fmamk_f32 v100, v100, 0x3a800000, v161
	v_rsq_f32_e32 v100, v100
	s_nop 0
	v_pk_mul_f32 v[94:95], v[94:95], v[100:101] op_sel_hi:[1,0]
	v_pk_mul_f32 v[92:93], v[92:93], v[100:101] op_sel_hi:[1,0]
	v_pk_mul_f32 v[90:91], v[90:91], v[100:101] op_sel_hi:[1,0]
	v_pk_mul_f32 v[88:89], v[88:89], v[100:101] op_sel_hi:[1,0]
	v_pk_mul_f32 v[84:85], v[84:85], v[100:101] op_sel_hi:[1,0]
	v_pk_mul_f32 v[86:87], v[86:87], v[100:101] op_sel_hi:[1,0]
	v_pk_mul_f32 v[80:81], v[80:81], v[100:101] op_sel_hi:[1,0]
	v_pk_mul_f32 v[82:83], v[82:83], v[100:101] op_sel_hi:[1,0]
	v_mul_f32_e32 v97, 0xbfb8aa3b, v92
	v_mul_f32_e32 v100, 0xbfb8aa3b, v93
	v_pk_mul_f32 v[86:87], v[94:95], v[86:87]
	v_pk_mul_f32 v[84:85], v[92:93], v[84:85]
	v_mul_f32_e32 v92, 0xbfb8aa3b, v94
	v_mul_f32_e32 v93, 0xbfb8aa3b, v95
	v_mul_f32_e32 v94, 0xbfb8aa3b, v88
	v_mul_f32_e32 v95, 0xbfb8aa3b, v89
	v_pk_mul_f32 v[80:81], v[88:89], v[80:81]
	v_mul_f32_e32 v88, 0xbfb8aa3b, v90
	v_mul_f32_e32 v89, 0xbfb8aa3b, v91
	v_pk_mul_f32 v[82:83], v[90:91], v[82:83]
	v_exp_f32_e32 v90, v97
	v_exp_f32_e32 v91, v100
	v_exp_f32_e32 v92, v92
	v_exp_f32_e32 v93, v93
	v_exp_f32_e32 v94, v94
	v_exp_f32_e32 v95, v95
	v_exp_f32_e32 v88, v88
	v_exp_f32_e32 v89, v89
	v_add_f32_e32 v90, 1.0, v90
	v_add_f32_e32 v91, 1.0, v91
	v_add_f32_e32 v92, 1.0, v92
	v_add_f32_e32 v93, 1.0, v93
	v_add_f32_e32 v94, 1.0, v94
	v_add_f32_e32 v95, 1.0, v95
	v_add_f32_e32 v97, 1.0, v88
	v_add_f32_e32 v100, 1.0, v89
	v_rcp_f32_e32 v88, v90
	v_rcp_f32_e32 v89, v91
	v_rcp_f32_e32 v90, v92
	v_rcp_f32_e32 v91, v93
	v_rcp_f32_e32 v92, v94
	v_rcp_f32_e32 v93, v95
	v_rcp_f32_e32 v94, v97
	v_rcp_f32_e32 v95, v100
	v_pk_mul_f32 v[84:85], v[84:85], v[88:89]
	v_pk_mul_f32 v[86:87], v[86:87], v[90:91]
	v_pk_mul_f32 v[88:89], v[80:81], v[92:93]
	v_pk_mul_f32 v[90:91], v[82:83], v[94:95]
	v_cvt_pk_bf16_f32 v80, v84, v85
	v_cvt_pk_bf16_f32 v81, v86, v87
	v_cvt_pk_bf16_f32 v82, v88, v89
	v_cvt_pk_bf16_f32 v83, v90, v91
	global_store_dwordx4 v[98:99], v[80:83], off nt
	s_nop 1
	s_waitcnt vmcnt(7)
; __device__ __forceinline__ float rstd_from_slots(const float* slots, int row, int fq) {
;     const f32x4 s4 = *(const f32x4*)(slots + (size_t)row * 16 + 4 * fq);
;     float s = (s4[0] + s4[1]) + (s4[2] + s4[3]);
;     s += __shfl_xor(s, 16); s += __shfl_xor(s, 32);
;     return __builtin_amdgcn_rsqf(s * (1.0f / 1024.0f) + RMS_EPS_F);
; }
;     __device__ __forceinline__ void operator()(const f32x4 (&acc)[2][2][4][2], const Unit& u, int wr, int wc, int fr, int fq) const {
;         const int row0 = u.pm * BM + wr * 64 + fr; const int col0 = u.pn * BM + wc * 32 + 8 * fq;
; #pragma unroll
;         for (int ai = 0; ai < 2; ++ai)
; #pragma unroll
;             for (int m = 0; m < 4; ++m) { const int row = row0 + ai * HALF + m * 16; bf16_t* rowp = O + (size_t)row * ldc + col0;
;                 const float sc = slots ? rstd_from_slots(slots, row, fq) : 1.0f;
; #pragma unroll
;                 for (int bj = 0; bj < 2; ++bj) { const f32x4 v0 = acc[ai][bj][m][0] * sc, v1 = acc[ai][bj][m][1] * sc;
;                     u32x4 w; w.x = cvt_pk_bf16(v0[0], v0[1]); w.y = cvt_pk_bf16(v0[2], v0[3]); w.z = cvt_pk_bf16(v1[0], v1[1]); w.w = cvt_pk_bf16(v1[2], v1[3]);
;                     *(u32x4*)(rowp + bj * HALF) = w; } }
;     }
; __device__ __forceinline__ float silu_mul(float g, float u) { return g * u * __builtin_amdgcn_rcpf(1.0f + __builtin_amdgcn_exp2f(g * -1.4426950408889634f)); }
;     __device__ __forceinline__ void operator()(const f32x4 (&acc)[2][2][4][2], const Unit& u, int wr, int wc, int fr, int fq) const {
;         const int row0 = u.pm * BM + wr * 64 + fr; const int col0 = u.pn * HALF + wc * 32 + 8 * fq;
; #pragma unroll
;         for (int ai = 0; ai < 2; ++ai)
; #pragma unroll
;             for (int m = 0; m < 4; ++m) { const int row = row0 + ai * HALF + m * 16;
;                 const float sc = rstd_from_slots(slots, row, fq);
;                 const f32x4 g0 = acc[ai][0][m][0] * sc, g1 = acc[ai][0][m][1] * sc, u0 = acc[ai][1][m][0] * sc, u1 = acc[ai][1][m][1] * sc;
;                 u32x4 w; w.x = cvt_pk_bf16(silu_mul(g0[0], u0[0]), silu_mul(g0[1], u0[1])); w.y = cvt_pk_bf16(silu_mul(g0[2], u0[2]), silu_mul(g0[3], u0[3]));
;                 w.z = cvt_pk_bf16(silu_mul(g1[0], u1[0]), silu_mul(g1[1], u1[1])); w.w = cvt_pk_bf16(silu_mul(g1[2], u1[2]), silu_mul(g1[3], u1[3]));
	v_mov_b32_e32 v80, v184
	v_mov_b32_e32 v81, v185
	v_mov_b32_e32 v82, v186
	v_mov_b32_e32 v83, v187
	v_mov_b32_e32 v84, v81
	v_mov_b32_e32 v85, v82
	v_mov_b32_e32 v81, v83
	v_pk_add_f32 v[80:81], v[84:85], v[80:81]
	v_mad_i64_i32 v[82:83], s[0:1], v96, s56, v[146:147]
	v_add_f32_e32 v80, v80, v81
	ds_bpermute_b32 v81, v151, v80
	v_lshl_add_u64 v[82:83], v[82:83], 0, v[148:149]
	s_waitcnt lgkmcnt(0)
	v_add_f32_e32 v84, v80, v81
	ds_bpermute_b32 v85, v162, v84
	v_add_u32_e32 v80, 0x80, v150
	v_ashrrev_i32_e32 v81, 31, v80
	v_lshlrev_b64 v[86:87], 6, v[80:81]
	v_lshl_add_u64 v[86:87], v[136:137], 0, v[86:87]
	s_waitcnt lgkmcnt(0)
	v_add_f32_e32 v84, v84, v85
	v_fmamk_f32 v84, v84, 0x3a800000, v161
	v_rsq_f32_e32 v84, v84
	s_nop 0
	v_pk_mul_f32 v[78:79], v[78:79], v[84:85] op_sel_hi:[1,0]
	v_pk_mul_f32 v[76:77], v[76:77], v[84:85] op_sel_hi:[1,0]
	v_pk_mul_f32 v[74:75], v[74:75], v[84:85] op_sel_hi:[1,0]
	v_pk_mul_f32 v[72:73], v[72:73], v[84:85] op_sel_hi:[1,0]
	v_pk_mul_f32 v[68:69], v[68:69], v[84:85] op_sel_hi:[1,0]
	v_pk_mul_f32 v[70:71], v[70:71], v[84:85] op_sel_hi:[1,0]
	v_pk_mul_f32 v[64:65], v[64:65], v[84:85] op_sel_hi:[1,0]
	v_pk_mul_f32 v[66:67], v[66:67], v[84:85] op_sel_hi:[1,0]
	v_mul_f32_e32 v81, 0xbfb8aa3b, v76
	v_mul_f32_e32 v84, 0xbfb8aa3b, v77
	v_pk_mul_f32 v[70:71], v[78:79], v[70:71]
	v_pk_mul_f32 v[68:69], v[76:77], v[68:69]
	v_mul_f32_e32 v76, 0xbfb8aa3b, v78
	v_mul_f32_e32 v77, 0xbfb8aa3b, v79
	v_mul_f32_e32 v78, 0xbfb8aa3b, v72
	v_mul_f32_e32 v79, 0xbfb8aa3b, v73
	v_pk_mul_f32 v[64:65], v[72:73], v[64:65]
	v_mul_f32_e32 v72, 0xbfb8aa3b, v74
	v_mul_f32_e32 v73, 0xbfb8aa3b, v75
	v_pk_mul_f32 v[66:67], v[74:75], v[66:67]
	v_exp_f32_e32 v74, v81
	v_exp_f32_e32 v75, v84
	v_exp_f32_e32 v76, v76
	v_exp_f32_e32 v77, v77
	v_exp_f32_e32 v78, v78
	v_exp_f32_e32 v79, v79
	v_exp_f32_e32 v72, v72
	v_exp_f32_e32 v73, v73
	v_add_f32_e32 v74, 1.0, v74
	v_add_f32_e32 v75, 1.0, v75
	v_add_f32_e32 v76, 1.0, v76
	v_add_f32_e32 v77, 1.0, v77
	v_add_f32_e32 v78, 1.0, v78
	v_add_f32_e32 v79, 1.0, v79
	v_add_f32_e32 v81, 1.0, v72
	v_add_f32_e32 v84, 1.0, v73
	v_rcp_f32_e32 v72, v74
	v_rcp_f32_e32 v73, v75
	v_rcp_f32_e32 v74, v76
	v_rcp_f32_e32 v75, v77
	v_rcp_f32_e32 v76, v78
	v_rcp_f32_e32 v77, v79
	v_rcp_f32_e32 v78, v81
	v_rcp_f32_e32 v79, v84
	v_pk_mul_f32 v[68:69], v[68:69], v[72:73]
	v_pk_mul_f32 v[70:71], v[70:71], v[74:75]
	v_pk_mul_f32 v[72:73], v[64:65], v[76:77]
	v_pk_mul_f32 v[74:75], v[66:67], v[78:79]
	v_cvt_pk_bf16_f32 v64, v68, v69
	v_cvt_pk_bf16_f32 v65, v70, v71
	v_cvt_pk_bf16_f32 v66, v72, v73
	v_cvt_pk_bf16_f32 v67, v74, v75
	global_store_dwordx4 v[82:83], v[64:67], off nt
	s_nop 1
	s_waitcnt vmcnt(7)
	v_mov_b32_e32 v64, v188
	v_mov_b32_e32 v65, v189
	v_mov_b32_e32 v66, v190
	v_mov_b32_e32 v67, v191
	v_mov_b32_e32 v68, v65
	v_mov_b32_e32 v69, v66
	v_mov_b32_e32 v65, v67
	v_pk_add_f32 v[64:65], v[68:69], v[64:65]
	v_mad_i64_i32 v[66:67], s[0:1], v80, s56, v[146:147]
	v_add_f32_e32 v64, v64, v65
	ds_bpermute_b32 v65, v151, v64
	v_lshl_add_u64 v[66:67], v[66:67], 0, v[148:149]
	s_waitcnt lgkmcnt(0)
	v_add_f32_e32 v68, v64, v65
	ds_bpermute_b32 v69, v162, v68
	v_add_u32_e32 v64, 0x90, v150
	v_ashrrev_i32_e32 v65, 31, v64
	v_lshlrev_b64 v[70:71], 6, v[64:65]
	v_lshl_add_u64 v[70:71], v[136:137], 0, v[70:71]
	s_waitcnt lgkmcnt(0)
	v_add_f32_e32 v68, v68, v69
	v_fmamk_f32 v68, v68, 0x3a800000, v161
	v_rsq_f32_e32 v68, v68
	s_nop 0
	v_pk_mul_f32 v[62:63], v[62:63], v[68:69] op_sel_hi:[1,0]
	v_pk_mul_f32 v[60:61], v[60:61], v[68:69] op_sel_hi:[1,0]
	v_pk_mul_f32 v[58:59], v[58:59], v[68:69] op_sel_hi:[1,0]
	v_pk_mul_f32 v[56:57], v[56:57], v[68:69] op_sel_hi:[1,0]
	v_pk_mul_f32 v[52:53], v[52:53], v[68:69] op_sel_hi:[1,0]
	v_pk_mul_f32 v[54:55], v[54:55], v[68:69] op_sel_hi:[1,0]
	v_pk_mul_f32 v[48:49], v[48:49], v[68:69] op_sel_hi:[1,0]
	v_pk_mul_f32 v[50:51], v[50:51], v[68:69] op_sel_hi:[1,0]
	v_mul_f32_e32 v65, 0xbfb8aa3b, v60
	v_mul_f32_e32 v68, 0xbfb8aa3b, v61
	v_pk_mul_f32 v[54:55], v[62:63], v[54:55]
	v_pk_mul_f32 v[52:53], v[60:61], v[52:53]
	v_mul_f32_e32 v60, 0xbfb8aa3b, v62
	v_mul_f32_e32 v61, 0xbfb8aa3b, v63
	v_mul_f32_e32 v62, 0xbfb8aa3b, v56
	v_mul_f32_e32 v63, 0xbfb8aa3b, v57
	v_pk_mul_f32 v[48:49], v[56:57], v[48:49]
	v_mul_f32_e32 v56, 0xbfb8aa3b, v58
	v_mul_f32_e32 v57, 0xbfb8aa3b, v59
	v_pk_mul_f32 v[50:51], v[58:59], v[50:51]
	v_exp_f32_e32 v58, v65
	v_exp_f32_e32 v59, v68
	v_exp_f32_e32 v60, v60
	v_exp_f32_e32 v61, v61
	v_exp_f32_e32 v62, v62
	v_exp_f32_e32 v63, v63
	v_exp_f32_e32 v56, v56
	v_exp_f32_e32 v57, v57
	v_add_f32_e32 v58, 1.0, v58
	v_add_f32_e32 v59, 1.0, v59
	v_add_f32_e32 v60, 1.0, v60
	v_add_f32_e32 v61, 1.0, v61
	v_add_f32_e32 v62, 1.0, v62
	v_add_f32_e32 v63, 1.0, v63
	v_add_f32_e32 v65, 1.0, v56
	v_add_f32_e32 v68, 1.0, v57
	v_rcp_f32_e32 v56, v58
	v_rcp_f32_e32 v57, v59
	v_rcp_f32_e32 v58, v60
	v_rcp_f32_e32 v59, v61
	v_rcp_f32_e32 v60, v62
	v_rcp_f32_e32 v61, v63
	v_rcp_f32_e32 v62, v65
	v_rcp_f32_e32 v63, v68
	v_pk_mul_f32 v[52:53], v[52:53], v[56:57]
	v_pk_mul_f32 v[54:55], v[54:55], v[58:59]
	v_pk_mul_f32 v[56:57], v[48:49], v[60:61]
	v_pk_mul_f32 v[58:59], v[50:51], v[62:63]
	v_cvt_pk_bf16_f32 v48, v52, v53
	v_cvt_pk_bf16_f32 v49, v54, v55
	v_cvt_pk_bf16_f32 v50, v56, v57
	v_cvt_pk_bf16_f32 v51, v58, v59
	global_store_dwordx4 v[66:67], v[48:51], off nt
	s_nop 1
	s_waitcnt vmcnt(7)
	v_mov_b32_e32 v48, v192
	v_mov_b32_e32 v49, v193
	v_mov_b32_e32 v50, v194
	v_mov_b32_e32 v51, v195
	v_mov_b32_e32 v52, v49
	v_mov_b32_e32 v53, v50
	v_mov_b32_e32 v49, v51
	v_pk_add_f32 v[48:49], v[52:53], v[48:49]
	v_mad_i64_i32 v[50:51], s[0:1], v64, s56, v[146:147]
	v_add_f32_e32 v48, v48, v49
	ds_bpermute_b32 v49, v151, v48
	v_lshl_add_u64 v[50:51], v[50:51], 0, v[148:149]
	s_waitcnt lgkmcnt(0)
; __device__ __forceinline__ float rstd_from_slots(const float* slots, int row, int fq) {
;     const f32x4 s4 = *(const f32x4*)(slots + (size_t)row * 16 + 4 * fq);
;     float s = (s4[0] + s4[1]) + (s4[2] + s4[3]);
;     s += __shfl_xor(s, 16); s += __shfl_xor(s, 32);
;     return __builtin_amdgcn_rsqf(s * (1.0f / 1024.0f) + RMS_EPS_F);
; }
;     __device__ __forceinline__ void operator()(const f32x4 (&acc)[2][2][4][2], const Unit& u, int wr, int wc, int fr, int fq) const {
;         const int row0 = u.pm * BM + wr * 64 + fr; const int col0 = u.pn * BM + wc * 32 + 8 * fq;
; #pragma unroll
;         for (int ai = 0; ai < 2; ++ai)
; #pragma unroll
;             for (int m = 0; m < 4; ++m) { const int row = row0 + ai * HALF + m * 16; bf16_t* rowp = O + (size_t)row * ldc + col0;
;                 const float sc = slots ? rstd_from_slots(slots, row, fq) : 1.0f;
; #pragma unroll
;                 for (int bj = 0; bj < 2; ++bj) { const f32x4 v0 = acc[ai][bj][m][0] * sc, v1 = acc[ai][bj][m][1] * sc;
;                     u32x4 w; w.x = cvt_pk_bf16(v0[0], v0[1]); w.y = cvt_pk_bf16(v0[2], v0[3]); w.z = cvt_pk_bf16(v1[0], v1[1]); w.w = cvt_pk_bf16(v1[2], v1[3]);
;                     *(u32x4*)(rowp + bj * HALF) = w; } }
;     }
; __device__ __forceinline__ float silu_mul(float g, float u) { return g * u * __builtin_amdgcn_rcpf(1.0f + __builtin_amdgcn_exp2f(g * -1.4426950408889634f)); }
;     __device__ __forceinline__ void operator()(const f32x4 (&acc)[2][2][4][2], const Unit& u, int wr, int wc, int fr, int fq) const {
;         const int row0 = u.pm * BM + wr * 64 + fr; const int col0 = u.pn * HALF + wc * 32 + 8 * fq;
; #pragma unroll
;         for (int ai = 0; ai < 2; ++ai)
; #pragma unroll
;             for (int m = 0; m < 4; ++m) { const int row = row0 + ai * HALF + m * 16;
;                 const float sc = rstd_from_slots(slots, row, fq);
;                 const f32x4 g0 = acc[ai][0][m][0] * sc, g1 = acc[ai][0][m][1] * sc, u0 = acc[ai][1][m][0] * sc, u1 = acc[ai][1][m][1] * sc;
;                 u32x4 w; w.x = cvt_pk_bf16(silu_mul(g0[0], u0[0]), silu_mul(g0[1], u0[1])); w.y = cvt_pk_bf16(silu_mul(g0[2], u0[2]), silu_mul(g0[3], u0[3]));
;                 w.z = cvt_pk_bf16(silu_mul(g1[0], u1[0]), silu_mul(g1[1], u1[1])); w.w = cvt_pk_bf16(silu_mul(g1[2], u1[2]), silu_mul(g1[3], u1[3]));
	v_add_f32_e32 v52, v48, v49
	ds_bpermute_b32 v53, v162, v52
	v_add_u32_e32 v48, 0xa0, v150
	v_ashrrev_i32_e32 v49, 31, v48
	v_lshlrev_b64 v[54:55], 6, v[48:49]
	v_lshl_add_u64 v[54:55], v[136:137], 0, v[54:55]
	s_waitcnt lgkmcnt(0)
	v_add_f32_e32 v52, v52, v53
	v_fmamk_f32 v52, v52, 0x3a800000, v161
	v_rsq_f32_e32 v52, v52
	s_nop 0
	v_pk_mul_f32 v[46:47], v[46:47], v[52:53] op_sel_hi:[1,0]
	v_pk_mul_f32 v[44:45], v[44:45], v[52:53] op_sel_hi:[1,0]
	v_pk_mul_f32 v[42:43], v[42:43], v[52:53] op_sel_hi:[1,0]
	v_pk_mul_f32 v[40:41], v[40:41], v[52:53] op_sel_hi:[1,0]
	v_pk_mul_f32 v[36:37], v[36:37], v[52:53] op_sel_hi:[1,0]
	v_pk_mul_f32 v[38:39], v[38:39], v[52:53] op_sel_hi:[1,0]
	v_pk_mul_f32 v[32:33], v[32:33], v[52:53] op_sel_hi:[1,0]
	v_pk_mul_f32 v[34:35], v[34:35], v[52:53] op_sel_hi:[1,0]
	v_mul_f32_e32 v49, 0xbfb8aa3b, v44
	v_mul_f32_e32 v52, 0xbfb8aa3b, v45
	v_pk_mul_f32 v[38:39], v[46:47], v[38:39]
	v_pk_mul_f32 v[36:37], v[44:45], v[36:37]
	v_mul_f32_e32 v44, 0xbfb8aa3b, v46
	v_mul_f32_e32 v45, 0xbfb8aa3b, v47
	v_mul_f32_e32 v46, 0xbfb8aa3b, v40
	v_mul_f32_e32 v47, 0xbfb8aa3b, v41
	v_pk_mul_f32 v[32:33], v[40:41], v[32:33]
	v_mul_f32_e32 v40, 0xbfb8aa3b, v42
	v_mul_f32_e32 v41, 0xbfb8aa3b, v43
	v_pk_mul_f32 v[34:35], v[42:43], v[34:35]
	v_exp_f32_e32 v42, v49
	v_exp_f32_e32 v43, v52
	v_exp_f32_e32 v44, v44
	v_exp_f32_e32 v45, v45
	v_exp_f32_e32 v46, v46
	v_exp_f32_e32 v47, v47
	v_exp_f32_e32 v40, v40
	v_exp_f32_e32 v41, v41
	v_add_f32_e32 v42, 1.0, v42
	v_add_f32_e32 v43, 1.0, v43
	v_add_f32_e32 v44, 1.0, v44
	v_add_f32_e32 v45, 1.0, v45
	v_add_f32_e32 v46, 1.0, v46
	v_add_f32_e32 v47, 1.0, v47
	v_add_f32_e32 v49, 1.0, v40
	v_add_f32_e32 v52, 1.0, v41
	v_rcp_f32_e32 v40, v42
	v_rcp_f32_e32 v41, v43
	v_rcp_f32_e32 v42, v44
	v_rcp_f32_e32 v43, v45
	v_rcp_f32_e32 v44, v46
	v_rcp_f32_e32 v45, v47
	v_rcp_f32_e32 v46, v49
	v_rcp_f32_e32 v47, v52
	v_pk_mul_f32 v[36:37], v[36:37], v[40:41]
	v_pk_mul_f32 v[38:39], v[38:39], v[42:43]
	v_pk_mul_f32 v[40:41], v[32:33], v[44:45]
	v_pk_mul_f32 v[42:43], v[34:35], v[46:47]
	v_cvt_pk_bf16_f32 v32, v36, v37
	v_cvt_pk_bf16_f32 v33, v38, v39
	v_cvt_pk_bf16_f32 v34, v40, v41
	v_cvt_pk_bf16_f32 v35, v42, v43
	global_store_dwordx4 v[50:51], v[32:35], off nt
	s_nop 1
	s_waitcnt vmcnt(7)
	v_mov_b32_e32 v32, v196
	v_mov_b32_e32 v33, v197
	v_mov_b32_e32 v34, v198
	v_mov_b32_e32 v35, v199
	v_mov_b32_e32 v36, v33
	v_mov_b32_e32 v37, v34
	v_mov_b32_e32 v33, v35
	v_pk_add_f32 v[32:33], v[36:37], v[32:33]
	v_mad_i64_i32 v[34:35], s[0:1], v48, s56, v[146:147]
	v_add_f32_e32 v32, v32, v33
	ds_bpermute_b32 v33, v151, v32
	v_lshl_add_u64 v[34:35], v[34:35], 0, v[148:149]
	s_waitcnt lgkmcnt(0)
	v_add_f32_e32 v36, v32, v33
	ds_bpermute_b32 v37, v162, v36
	v_add_u32_e32 v32, 0xb0, v150
	v_ashrrev_i32_e32 v33, 31, v32
	v_lshlrev_b64 v[38:39], 6, v[32:33]
	v_lshl_add_u64 v[38:39], v[136:137], 0, v[38:39]
	s_waitcnt lgkmcnt(0)
; __device__ __forceinline__ float rstd_from_slots(const float* slots, int row, int fq) {
;     const f32x4 s4 = *(const f32x4*)(slots + (size_t)row * 16 + 4 * fq);
;     float s = (s4[0] + s4[1]) + (s4[2] + s4[3]);
;     s += __shfl_xor(s, 16); s += __shfl_xor(s, 32);
;     return __builtin_amdgcn_rsqf(s * (1.0f / 1024.0f) + RMS_EPS_F);
; }
;     __device__ __forceinline__ void operator()(const f32x4 (&acc)[2][2][4][2], const Unit& u, int wr, int wc, int fr, int fq) const {
;         const int row0 = u.pm * BM + wr * 64 + fr; const int col0 = u.pn * BM + wc * 32 + 8 * fq;
; #pragma unroll
;         for (int ai = 0; ai < 2; ++ai)
; #pragma unroll
;             for (int m = 0; m < 4; ++m) { const int row = row0 + ai * HALF + m * 16; bf16_t* rowp = O + (size_t)row * ldc + col0;
;                 const float sc = slots ? rstd_from_slots(slots, row, fq) : 1.0f;
; #pragma unroll
;                 for (int bj = 0; bj < 2; ++bj) { const f32x4 v0 = acc[ai][bj][m][0] * sc, v1 = acc[ai][bj][m][1] * sc;
;                     u32x4 w; w.x = cvt_pk_bf16(v0[0], v0[1]); w.y = cvt_pk_bf16(v0[2], v0[3]); w.z = cvt_pk_bf16(v1[0], v1[1]); w.w = cvt_pk_bf16(v1[2], v1[3]);
;                     *(u32x4*)(rowp + bj * HALF) = w; } }
;     }
; __device__ __forceinline__ float silu_mul(float g, float u) { return g * u * __builtin_amdgcn_rcpf(1.0f + __builtin_amdgcn_exp2f(g * -1.4426950408889634f)); }
;     __device__ __forceinline__ void operator()(const f32x4 (&acc)[2][2][4][2], const Unit& u, int wr, int wc, int fr, int fq) const {
;         const int row0 = u.pm * BM + wr * 64 + fr; const int col0 = u.pn * HALF + wc * 32 + 8 * fq;
; #pragma unroll
;         for (int ai = 0; ai < 2; ++ai)
; #pragma unroll
;             for (int m = 0; m < 4; ++m) { const int row = row0 + ai * HALF + m * 16;
;                 const float sc = rstd_from_slots(slots, row, fq);
;                 const f32x4 g0 = acc[ai][0][m][0] * sc, g1 = acc[ai][0][m][1] * sc, u0 = acc[ai][1][m][0] * sc, u1 = acc[ai][1][m][1] * sc;
;                 u32x4 w; w.x = cvt_pk_bf16(silu_mul(g0[0], u0[0]), silu_mul(g0[1], u0[1])); w.y = cvt_pk_bf16(silu_mul(g0[2], u0[2]), silu_mul(g0[3], u0[3]));
;                 w.z = cvt_pk_bf16(silu_mul(g1[0], u1[0]), silu_mul(g1[1], u1[1])); w.w = cvt_pk_bf16(silu_mul(g1[2], u1[2]), silu_mul(g1[3], u1[3]));
	v_add_f32_e32 v36, v36, v37
	v_fmamk_f32 v36, v36, 0x3a800000, v161
	v_rsq_f32_e32 v36, v36
	s_nop 0
	v_pk_mul_f32 v[30:31], v[30:31], v[36:37] op_sel_hi:[1,0]
	v_pk_mul_f32 v[28:29], v[28:29], v[36:37] op_sel_hi:[1,0]
	v_pk_mul_f32 v[26:27], v[26:27], v[36:37] op_sel_hi:[1,0]
	v_pk_mul_f32 v[24:25], v[24:25], v[36:37] op_sel_hi:[1,0]
	v_pk_mul_f32 v[20:21], v[20:21], v[36:37] op_sel_hi:[1,0]
	v_pk_mul_f32 v[22:23], v[22:23], v[36:37] op_sel_hi:[1,0]
	v_pk_mul_f32 v[16:17], v[16:17], v[36:37] op_sel_hi:[1,0]
	v_pk_mul_f32 v[18:19], v[18:19], v[36:37] op_sel_hi:[1,0]
	v_mul_f32_e32 v33, 0xbfb8aa3b, v28
	v_mul_f32_e32 v36, 0xbfb8aa3b, v29
	v_pk_mul_f32 v[22:23], v[30:31], v[22:23]
	v_pk_mul_f32 v[20:21], v[28:29], v[20:21]
	v_mul_f32_e32 v28, 0xbfb8aa3b, v30
	v_mul_f32_e32 v29, 0xbfb8aa3b, v31
	v_mul_f32_e32 v30, 0xbfb8aa3b, v24
	v_mul_f32_e32 v31, 0xbfb8aa3b, v25
	v_pk_mul_f32 v[16:17], v[24:25], v[16:17]
	v_mul_f32_e32 v24, 0xbfb8aa3b, v26
	v_mul_f32_e32 v25, 0xbfb8aa3b, v27
	v_pk_mul_f32 v[18:19], v[26:27], v[18:19]
	v_exp_f32_e32 v26, v33
	v_exp_f32_e32 v27, v36
	v_exp_f32_e32 v28, v28
	v_exp_f32_e32 v29, v29
	v_exp_f32_e32 v30, v30
	v_exp_f32_e32 v31, v31
	v_exp_f32_e32 v24, v24
	v_exp_f32_e32 v25, v25
	v_add_f32_e32 v26, 1.0, v26
	v_add_f32_e32 v27, 1.0, v27
	v_add_f32_e32 v28, 1.0, v28
	v_add_f32_e32 v29, 1.0, v29
	v_add_f32_e32 v30, 1.0, v30
	v_add_f32_e32 v31, 1.0, v31
	v_add_f32_e32 v33, 1.0, v24
	v_add_f32_e32 v36, 1.0, v25
	v_rcp_f32_e32 v24, v26
	v_rcp_f32_e32 v25, v27
	v_rcp_f32_e32 v26, v28
	v_rcp_f32_e32 v27, v29
	v_rcp_f32_e32 v28, v30
	v_rcp_f32_e32 v29, v31
	v_rcp_f32_e32 v30, v33
	v_rcp_f32_e32 v31, v36
	v_pk_mul_f32 v[20:21], v[20:21], v[24:25]
	v_pk_mul_f32 v[22:23], v[22:23], v[26:27]
	v_pk_mul_f32 v[24:25], v[16:17], v[28:29]
	v_pk_mul_f32 v[26:27], v[18:19], v[30:31]
	v_cvt_pk_bf16_f32 v16, v20, v21
	v_cvt_pk_bf16_f32 v17, v22, v23
	v_cvt_pk_bf16_f32 v18, v24, v25
	v_cvt_pk_bf16_f32 v19, v26, v27
	global_store_dwordx4 v[34:35], v[16:19], off nt
	s_nop 1
	s_waitcnt vmcnt(7)
	v_mov_b32_e32 v16, v200
	v_mov_b32_e32 v17, v201
	v_mov_b32_e32 v18, v202
	v_mov_b32_e32 v19, v203
	v_mov_b32_e32 v20, v17
	v_mov_b32_e32 v21, v18
	v_mov_b32_e32 v17, v19
	v_pk_add_f32 v[16:17], v[20:21], v[16:17]
	v_mad_i64_i32 v[18:19], s[0:1], v32, s56, v[146:147]
	v_add_f32_e32 v16, v16, v17
	ds_bpermute_b32 v17, v151, v16
	v_lshl_add_u64 v[18:19], v[18:19], 0, v[148:149]
	s_mov_b64 s[0:1], -1
	s_waitcnt lgkmcnt(0)
	v_add_f32_e32 v16, v16, v17
	ds_bpermute_b32 v17, v162, v16
	s_waitcnt lgkmcnt(0)
	v_add_f32_e32 v16, v16, v17
	v_fmamk_f32 v16, v16, 0x3a800000, v161
	v_rsq_f32_e32 v16, v16
	s_nop 0
	v_pk_mul_f32 v[14:15], v[14:15], v[16:17] op_sel_hi:[1,0]
	v_pk_mul_f32 v[12:13], v[12:13], v[16:17] op_sel_hi:[1,0]
	v_pk_mul_f32 v[10:11], v[10:11], v[16:17] op_sel_hi:[1,0]
	v_pk_mul_f32 v[8:9], v[8:9], v[16:17] op_sel_hi:[1,0]
	v_pk_mul_f32 v[4:5], v[4:5], v[16:17] op_sel_hi:[1,0]
	v_pk_mul_f32 v[6:7], v[6:7], v[16:17] op_sel_hi:[1,0]
	v_pk_mul_f32 v[0:1], v[0:1], v[16:17] op_sel_hi:[1,0]
	v_pk_mul_f32 v[2:3], v[2:3], v[16:17] op_sel_hi:[1,0]
	v_mul_f32_e32 v16, 0xbfb8aa3b, v12
	v_mul_f32_e32 v17, 0xbfb8aa3b, v13
	v_pk_mul_f32 v[6:7], v[14:15], v[6:7]
	v_pk_mul_f32 v[4:5], v[12:13], v[4:5]
	v_mul_f32_e32 v12, 0xbfb8aa3b, v14
	v_mul_f32_e32 v13, 0xbfb8aa3b, v15
	v_mul_f32_e32 v14, 0xbfb8aa3b, v8
	v_mul_f32_e32 v15, 0xbfb8aa3b, v9
	v_pk_mul_f32 v[0:1], v[8:9], v[0:1]
	v_mul_f32_e32 v8, 0xbfb8aa3b, v10
	v_mul_f32_e32 v9, 0xbfb8aa3b, v11
	v_pk_mul_f32 v[2:3], v[10:11], v[2:3]
	v_exp_f32_e32 v10, v16
	v_exp_f32_e32 v11, v17
	v_exp_f32_e32 v12, v12
	v_exp_f32_e32 v13, v13
	v_exp_f32_e32 v14, v14
	v_exp_f32_e32 v15, v15
	v_exp_f32_e32 v8, v8
	v_exp_f32_e32 v9, v9
	v_add_f32_e32 v10, 1.0, v10
	v_add_f32_e32 v11, 1.0, v11
	v_add_f32_e32 v12, 1.0, v12
	v_add_f32_e32 v13, 1.0, v13
	v_add_f32_e32 v14, 1.0, v14
	v_add_f32_e32 v15, 1.0, v15
	v_add_f32_e32 v16, 1.0, v8
	v_add_f32_e32 v17, 1.0, v9
	v_rcp_f32_e32 v8, v10
	v_rcp_f32_e32 v9, v11
	v_rcp_f32_e32 v10, v12
	v_rcp_f32_e32 v11, v13
	v_rcp_f32_e32 v12, v14
	v_rcp_f32_e32 v13, v15
	v_rcp_f32_e32 v14, v16
	v_rcp_f32_e32 v15, v17
	v_pk_mul_f32 v[4:5], v[4:5], v[8:9]
	v_pk_mul_f32 v[6:7], v[6:7], v[10:11]
	v_pk_mul_f32 v[8:9], v[0:1], v[12:13]
	v_pk_mul_f32 v[10:11], v[2:3], v[14:15]
	v_cvt_pk_bf16_f32 v0, v4, v5
	v_cvt_pk_bf16_f32 v1, v6, v7
	v_cvt_pk_bf16_f32 v2, v8, v9
	v_cvt_pk_bf16_f32 v3, v10, v11
	global_store_dwordx4 v[18:19], v[0:3], off nt
	s_cbranch_vccnz .LBB0_1107
	s_andn2_b64 vcc, exec, s[6:7]
	s_cbranch_vccnz .LBB0_1106
	s_barrier
	s_branch .LBB0_1106

; #define PG8_STAGE(bufoff, gbase, voff) do { _Pragma("unroll") for (int _i = 0; _i < 2; ++_i) \
;         __builtin_amdgcn_global_load_lds((const unsigned*)((const char*)(gbase) + (voff)[_i]), (PG8_LAS unsigned*)(lds + (bufoff) + ldsw + _i * 8192), 16, 0, PG8_LOAD_AUX); } while (0)
; #define PG8_LDA(dst, b, h) do { _Pragma("unroll") for (int m = 0; m < 4; ++m) _Pragma("unroll") for (int k = 0; k < 2; ++k) dst[m][k] = *(const PG8_LAS bf16x8*)(lds + PG8_SA(b, h) + aoff + m * 2048 + k * 1024); } while (0)
; #define PG8_LDB(dst, b, h) do { _Pragma("unroll") for (int n = 0; n < 2; ++n) _Pragma("unroll") for (int k = 0; k < 2; ++k) dst[n][k] = *(const PG8_LAS bf16x8*)(lds + PG8_SB(b, h) + boff + n * 2048 + k * 1024); } while (0)
; #define PG8_MMA(ai, bj, At, Bt) do { __builtin_amdgcn_s_setprio(1); _Pragma("unroll") for (int m = 0; m < 4; ++m) _Pragma("unroll") for (int n = 0; n < 2; ++n) _Pragma("unroll") for (int k = 0; k < 2; ++k) \
;         acc[ai][bj][m][n] = __builtin_amdgcn_mfma_f32_16x16x32_bf16(Bt[n][k], At[m][k], acc[ai][bj][m][n], 0, 0, 0); __builtin_amdgcn_s_setprio(0); } while (0)
; #define PG8_WAIT_V(n) asm volatile("s_waitcnt vmcnt(" #n ")" ::: "memory")
; #define PG8_WAIT_L(n) asm volatile("s_waitcnt lgkmcnt(" #n ")" ::: "memory")
; #define PG8_BAR __builtin_amdgcn_s_barrier()
; #define PG8_SCHED __builtin_amdgcn_sched_barrier(0)
; template <class Epi, class Sched, bool ALIGN_EPI = false, bool SP2 = false>
; __device__ __forceinline__ void gemm_phase(PG8_LAS unsigned char* lds, const Gemm g, const Sched& S, const Epi& E) {
;     ...
;             PG8_LDB(B0, 1, 0); PG8_LDB(B1, 1, 1); PG8_SCHED; PG8_LDA(At, 1, 0); PG8_STAGE(PG8_SA(0, 1), a2 + hstepA, voffA);
;             PG8_WAIT_V(8); PG8_WAIT_L(0); PG8_BAR; PG8_MMA(0, 0, At, B0); PG8_MMA(0, 1, At, B1); PG8_BAR; PG8_SCHED;
;             PG8_LDA(At, 1, 1); PG8_STAGE(PG8_SB(1, 0), b3, voffB); PG8_STAGE(PG8_SB(1, 1), b3 + hstepB, voffB); PG8_STAGE(PG8_SA(1, 0), a3, voffA);
.Lkmid_P13:
	s_add_i32 s28, 0, 0x18000
	v_add_u32_e32 v159, s28, v151
	s_add_i32 s29, 0, 0x1c000
	ds_read_b128 v[146:149], v159
	ds_read_b128 v[160:163], v159 offset:1024
	ds_read_b128 v[164:167], v159 offset:2048
	ds_read_b128 v[168:171], v159 offset:3072
	v_add_u32_e32 v159, s29, v151
	ds_read_b128 v[172:175], v159
	ds_read_b128 v[176:179], v159 offset:1024
	ds_read_b128 v[180:183], v159 offset:2048
	ds_read_b128 v[184:187], v159 offset:3072
	s_add_u32 s22, s22, 0xb0000
	s_addc_u32 s23, s23, 0
	s_mov_b32 m0, s45
	v_lshl_add_u64 v[228:229], s[22:23], 0, v[128:129]
	ds_read_b128 v[188:191], v157 offset:32768
	ds_read_b128 v[192:195], v157 offset:33792
	ds_read_b128 v[196:199], v157 offset:34816
	ds_read_b128 v[200:203], v157 offset:35840
	ds_read_b128 v[204:207], v157 offset:36864
	ds_read_b128 v[208:211], v157 offset:37888
	ds_read_b128 v[212:215], v157 offset:38912
	ds_read_b128 v[216:219], v157 offset:39936
	global_load_lds_dwordx4 v[228:229], off
	v_lshl_add_u64 v[228:229], s[22:23], 0, v[132:133]
	s_mov_b32 m0, s46
	s_nop 0
	global_load_lds_dwordx4 v[228:229], off
	s_waitcnt vmcnt(8)
	s_waitcnt lgkmcnt(0)
	s_barrier
	s_setprio 1
	s_waitcnt lgkmcnt(0)
	v_mfma_f32_16x16x32_bf16 v[124:127], v[146:149], v[188:191], v[124:127]
	v_mfma_f32_16x16x32_bf16 v[120:123], v[164:167], v[188:191], v[120:123]
	v_mfma_f32_16x16x32_bf16 v[108:111], v[146:149], v[196:199], v[108:111]
	v_mfma_f32_16x16x32_bf16 v[104:107], v[164:167], v[196:199], v[104:107]
	v_mfma_f32_16x16x32_bf16 v[92:95], v[146:149], v[204:207], v[92:95]
	v_mfma_f32_16x16x32_bf16 v[88:91], v[164:167], v[204:207], v[88:91]
	v_mfma_f32_16x16x32_bf16 v[76:79], v[146:149], v[212:215], v[76:79]
	v_mfma_f32_16x16x32_bf16 v[72:75], v[164:167], v[212:215], v[72:75]
	v_mfma_f32_16x16x32_bf16 v[124:127], v[160:163], v[192:195], v[124:127]
	v_mfma_f32_16x16x32_bf16 v[120:123], v[168:171], v[192:195], v[120:123]
	v_mfma_f32_16x16x32_bf16 v[108:111], v[160:163], v[200:203], v[108:111]
	v_mfma_f32_16x16x32_bf16 v[104:107], v[168:171], v[200:203], v[104:107]
	v_mfma_f32_16x16x32_bf16 v[92:95], v[160:163], v[208:211], v[92:95]
	v_mfma_f32_16x16x32_bf16 v[88:91], v[168:171], v[208:211], v[88:91]
	v_mfma_f32_16x16x32_bf16 v[76:79], v[160:163], v[216:219], v[76:79]
	v_mfma_f32_16x16x32_bf16 v[72:75], v[168:171], v[216:219], v[72:75]
	s_setprio 0
	s_setprio 1
	v_mfma_f32_16x16x32_bf16 v[116:119], v[172:175], v[188:191], v[116:119]
	v_mfma_f32_16x16x32_bf16 v[112:115], v[180:183], v[188:191], v[112:115]
	v_mfma_f32_16x16x32_bf16 v[100:103], v[172:175], v[196:199], v[100:103]
	v_mfma_f32_16x16x32_bf16 v[96:99], v[180:183], v[196:199], v[96:99]
	v_mfma_f32_16x16x32_bf16 v[84:87], v[172:175], v[204:207], v[84:87]
	v_mfma_f32_16x16x32_bf16 v[80:83], v[180:183], v[204:207], v[80:83]
	v_mfma_f32_16x16x32_bf16 v[68:71], v[172:175], v[212:215], v[68:71]
	v_mfma_f32_16x16x32_bf16 v[64:67], v[180:183], v[212:215], v[64:67]
	v_mfma_f32_16x16x32_bf16 v[116:119], v[176:179], v[192:195], v[116:119]
	v_mfma_f32_16x16x32_bf16 v[112:115], v[184:187], v[192:195], v[112:115]
	v_mfma_f32_16x16x32_bf16 v[100:103], v[176:179], v[200:203], v[100:103]
	v_mfma_f32_16x16x32_bf16 v[96:99], v[184:187], v[200:203], v[96:99]
	v_mfma_f32_16x16x32_bf16 v[84:87], v[176:179], v[208:211], v[84:87]
	v_mfma_f32_16x16x32_bf16 v[80:83], v[184:187], v[208:211], v[80:83]
	v_mfma_f32_16x16x32_bf16 v[68:71], v[176:179], v[216:219], v[68:71]
	v_mfma_f32_16x16x32_bf16 v[64:67], v[184:187], v[216:219], v[64:67]
	s_setprio 0
	s_barrier
	s_add_i32 s22, s28, s42
	v_lshl_add_u64 v[220:221], v[220:221], 0, s[18:19]
	s_mov_b32 m0, s22
	ds_read_b128 v[188:191], v157 offset:49152
	ds_read_b128 v[192:195], v157 offset:50176
	ds_read_b128 v[196:199], v157 offset:51200
	ds_read_b128 v[200:203], v157 offset:52224
	ds_read_b128 v[204:207], v157 offset:53248
	ds_read_b128 v[208:211], v157 offset:54272
	ds_read_b128 v[212:215], v157 offset:55296
	ds_read_b128 v[216:219], v157 offset:56320
	global_load_lds_dwordx4 v[220:221], off
	s_add_i32 m0, s22, 0x2000
	s_add_u32 s20, s20, 0x2c080
	v_lshl_add_u64 v[220:221], v[222:223], 0, s[18:19]
	s_addc_u32 s21, s21, 0
	s_add_i32 s22, s29, s42
	global_load_lds_dwordx4 v[220:221], off
	v_lshl_add_u64 v[220:221], s[20:21], 0, v[130:131]
	s_mov_b32 m0, s22
	s_nop 0
	global_load_lds_dwordx4 v[220:221], off
	v_lshl_add_u64 v[220:221], s[20:21], 0, v[134:135]
	s_add_i32 m0, s22, 0x2000
	s_nop 0
	global_load_lds_dwordx4 v[220:221], off
	v_lshl_add_u64 v[220:221], v[224:225], 0, s[18:19]
	s_mov_b32 m0, s50
	s_nop 0
	global_load_lds_dwordx4 v[220:221], off
	v_lshl_add_u64 v[220:221], v[226:227], 0, s[18:19]
	s_mov_b32 m0, s51
	s_nop 0
	global_load_lds_dwordx4 v[220:221], off
	s_waitcnt vmcnt(8)
	s_waitcnt lgkmcnt(0)
	s_barrier
; __device__ __forceinline__ unsigned cvt_pk_bf16(float lo, float hi) { const cvt_f32x2_t v = {lo, hi}; const cvt_bf16x2_t b = __builtin_convertvector(v, cvt_bf16x2_t); return __builtin_bit_cast(unsigned, b); }
; #define PG8_WAIT_V(n) asm volatile("s_waitcnt vmcnt(" #n ")" ::: "memory")
; #define PG8_WAIT_L(n) asm volatile("s_waitcnt lgkmcnt(" #n ")" ::: "memory")
; #define PG8_BAR __builtin_amdgcn_s_barrier()
; #define PG8_SCHED __builtin_amdgcn_sched_barrier(0)
;     __device__ __forceinline__ void operator()(const f32x4 (&acc)[2][2][4][2], const Unit& u, int wr, int wc, int fr, int fq) const {
;     ...
;             for (int m = 0; m < 4; ++m) { const int rowg = u.pm * BM + ai * HALF + wr * 64 + m * 16, row = rowg + fr; const size_t off = (size_t)row * 1024 + col0;
;                 u32x4 w[2]; float ss = 0.f;
; #pragma unroll
;                 for (int bj = 0; bj < 2; ++bj) { f32x4 b0, b1;
;                     if (BASE_F32) { const float* bp = (const float*)base + off + 32 * bj; b0 = *(const f32x4*)bp; b1 = *(const f32x4*)(bp + 4); }
;                     else { const u32x4 bb = *(const u32x4*)((const bf16_t*)base + off + 32 * bj);
;                         b0 = (f32x4){__uint_as_float(bb.x << 16), __uint_as_float(bb.x & 0xffff0000u), __uint_as_float(bb.y << 16), __uint_as_float(bb.y & 0xffff0000u)};
;                         b1 = (f32x4){__uint_as_float(bb.z << 16), __uint_as_float(bb.z & 0xffff0000u), __uint_as_float(bb.w << 16), __uint_as_float(bb.w & 0xffff0000u)}; }
;                     const f32x4 o0 = b0 + acc[ai][bj][m][0], o1 = b1 + acc[ai][bj][m][1];
;                     ss += ((o0[0] * o0[0] + o0[1] * o0[1]) + (o0[2] * o0[2] + o0[3] * o0[3])) + ((o1[0] * o1[0] + o1[1] * o1[1]) + (o1[2] * o1[2] + o1[3] * o1[3]));
;                     w[bj].x = cvt_pk_bf16(o0[0], o0[1]); w[bj].y = cvt_pk_bf16(o0[2], o0[3]); w[bj].z = cvt_pk_bf16(o1[0], o1[1]); w[bj].w = cvt_pk_bf16(o1[2], o1[3]); }
;                 ss += __shfl_xor(ss, 16); ss += __shfl_xor(ss, 32); if (fq == 0) slots[(size_t)row * 16 + u.pn * 4 + wc] = ss;
; template <class Epi, class Sched, bool ALIGN_EPI = false, bool SP2 = false>
; __device__ __forceinline__ void gemm_phase(PG8_LAS unsigned char* lds, const Gemm g, const Sched& S, const Epi& E) {
;     ...
;             PG8_WAIT_V(8); PG8_WAIT_L(0); PG8_BAR; PG8_MMA(1, 0, At, B0); PG8_MMA(1, 1, At, B1); PG8_BAR; PG8_SCHED;
	s_setprio 1
	s_waitcnt lgkmcnt(0)
	v_mfma_f32_16x16x32_bf16 v[60:63], v[146:149], v[188:191], v[60:63]
	v_mfma_f32_16x16x32_bf16 v[56:59], v[164:167], v[188:191], v[56:59]
	v_mfma_f32_16x16x32_bf16 v[44:47], v[146:149], v[196:199], v[44:47]
	v_mfma_f32_16x16x32_bf16 v[40:43], v[164:167], v[196:199], v[40:43]
	v_mfma_f32_16x16x32_bf16 v[28:31], v[146:149], v[204:207], v[28:31]
	v_mfma_f32_16x16x32_bf16 v[24:27], v[164:167], v[204:207], v[24:27]
	v_mfma_f32_16x16x32_bf16 v[12:15], v[146:149], v[212:215], v[12:15]
	v_mfma_f32_16x16x32_bf16 v[8:11], v[164:167], v[212:215], v[8:11]
	v_mfma_f32_16x16x32_bf16 v[60:63], v[160:163], v[192:195], v[60:63]
	v_mfma_f32_16x16x32_bf16 v[56:59], v[168:171], v[192:195], v[56:59]
	v_mfma_f32_16x16x32_bf16 v[44:47], v[160:163], v[200:203], v[44:47]
	v_mfma_f32_16x16x32_bf16 v[40:43], v[168:171], v[200:203], v[40:43]
	v_mfma_f32_16x16x32_bf16 v[28:31], v[160:163], v[208:211], v[28:31]
	v_mfma_f32_16x16x32_bf16 v[24:27], v[168:171], v[208:211], v[24:27]
	v_mfma_f32_16x16x32_bf16 v[12:15], v[160:163], v[216:219], v[12:15]
	v_mfma_f32_16x16x32_bf16 v[8:11], v[168:171], v[216:219], v[8:11]
	s_setprio 0
	s_setprio 1
	v_mfma_f32_16x16x32_bf16 v[52:55], v[172:175], v[188:191], v[52:55]
	v_mfma_f32_16x16x32_bf16 v[48:51], v[180:183], v[188:191], v[48:51]
	v_mfma_f32_16x16x32_bf16 v[36:39], v[172:175], v[196:199], v[36:39]
	v_mfma_f32_16x16x32_bf16 v[32:35], v[180:183], v[196:199], v[32:35]
	v_mfma_f32_16x16x32_bf16 v[20:23], v[172:175], v[204:207], v[20:23]
	v_mfma_f32_16x16x32_bf16 v[16:19], v[180:183], v[204:207], v[16:19]
	v_mfma_f32_16x16x32_bf16 v[4:7], v[172:175], v[212:215], v[4:7]
	v_mfma_f32_16x16x32_bf16 v[0:3], v[180:183], v[212:215], v[0:3]
	v_mfma_f32_16x16x32_bf16 v[52:55], v[176:179], v[192:195], v[52:55]
	v_mfma_f32_16x16x32_bf16 v[48:51], v[184:187], v[192:195], v[48:51]
	v_mfma_f32_16x16x32_bf16 v[36:39], v[176:179], v[200:203], v[36:39]
	v_mfma_f32_16x16x32_bf16 v[32:35], v[184:187], v[200:203], v[32:35]
	v_mfma_f32_16x16x32_bf16 v[20:23], v[176:179], v[208:211], v[20:23]
	v_mfma_f32_16x16x32_bf16 v[16:19], v[184:187], v[208:211], v[16:19]
	v_mfma_f32_16x16x32_bf16 v[4:7], v[176:179], v[216:219], v[4:7]
	v_mfma_f32_16x16x32_bf16 v[0:3], v[184:187], v[216:219], v[0:3]
	s_setprio 0
	s_barrier
	s_add_i32 s27, s27, 2
	s_add_u32 s0, s0, 0x100
	s_addc_u32 s1, s1, 0
	s_add_u32 s25, s25, 0x100
	s_addc_u32 s26, s26, 0
	s_cmp_gt_u32 s27, 41
	s_cbranch_scc0 .LBB0_1196
	s_lshl_b32 s22, s24, 8
	s_add_i32 s22, s22, s49
	v_or_b32_e32 v148, s22, v150
	v_ashrrev_i32_e32 v149, 31, v148
	v_readlane_b32 s26, v239, 49
	v_lshl_or_b32 v146, s14, 8, v152
	v_lshlrev_b64 v[160:161], 11, v[148:149]
	v_readlane_b32 s27, v239, 50
	v_ashrrev_i32_e32 v147, 31, v146
	v_and_b32_e32 v168, 64, v158
	v_lshl_add_u64 v[160:161], s[26:27], 0, v[160:161]
	v_lshl_add_u64 v[164:165], v[146:147], 1, v[160:161]
	global_load_dwordx4 v[160:163], v[164:165], off
	s_nop 0
	global_load_dwordx4 v[164:167], v[164:165], off offset:64
	v_add_u32_e32 v176, 64, v168
	v_xor_b32_e32 v159, 16, v158
	v_cmp_lt_i32_e32 vcc, v159, v176
	s_lshl_b32 s0, s14, 2
	s_ashr_i32 s1, s0, 31
	v_cndmask_b32_e32 v159, v158, v159, vcc
	v_lshlrev_b32_e32 v159, 2, v159
	s_waitcnt vmcnt(0)
	v_lshlrev_b32_e32 v168, 16, v160
	v_and_b32_e32 v169, 0xffff0000, v160
	v_lshlrev_b32_e32 v160, 16, v161
	v_and_b32_e32 v161, 0xffff0000, v161
	v_lshlrev_b32_e32 v170, 16, v162
	v_and_b32_e32 v171, 0xffff0000, v162
	v_lshlrev_b32_e32 v162, 16, v163
	v_and_b32_e32 v163, 0xffff0000, v163
	v_lshlrev_b32_e32 v172, 16, v164
	v_and_b32_e32 v173, 0xffff0000, v164
	v_lshlrev_b32_e32 v164, 16, v165
	v_and_b32_e32 v165, 0xffff0000, v165
	v_lshlrev_b32_e32 v174, 16, v166
	v_and_b32_e32 v175, 0xffff0000, v166
	v_lshlrev_b32_e32 v166, 16, v167
	v_and_b32_e32 v167, 0xffff0000, v167
	v_pk_add_f32 v[126:127], v[126:127], v[160:161]
	v_pk_add_f32 v[124:125], v[124:125], v[168:169]
	v_pk_add_f32 v[122:123], v[122:123], v[162:163]
	v_pk_add_f32 v[120:121], v[120:121], v[170:171]
	v_pk_add_f32 v[118:119], v[118:119], v[164:165]
	v_pk_add_f32 v[116:117], v[116:117], v[172:173]
	v_pk_add_f32 v[114:115], v[114:115], v[166:167]
	v_pk_add_f32 v[112:113], v[112:113], v[174:175]
	v_mul_f32_e32 v160, v125, v125
	v_mul_f32_e32 v161, v127, v127
	v_mul_f32_e32 v162, v121, v121
	v_mul_f32_e32 v163, v123, v123
	v_mul_f32_e32 v164, v117, v117
	v_mul_f32_e32 v165, v119, v119
	v_mul_f32_e32 v166, v113, v113
	v_mul_f32_e32 v167, v115, v115
	v_fmac_f32_e32 v160, v124, v124
	v_fmac_f32_e32 v161, v126, v126
	v_fmac_f32_e32 v162, v120, v120
	v_fmac_f32_e32 v163, v122, v122
	v_fmac_f32_e32 v164, v116, v116
	v_fmac_f32_e32 v165, v118, v118
	v_fmac_f32_e32 v166, v112, v112
	v_fmac_f32_e32 v167, v114, v114
	v_add_f32_e32 v160, v160, v161
	v_add_f32_e32 v161, v162, v163
	v_add_f32_e32 v162, v164, v165
	v_add_f32_e32 v163, v166, v167
	v_add_f32_e32 v160, v160, v161
	v_add_f32_e32 v161, v162, v163
	v_add_f32_e32 v161, v160, v161
	ds_bpermute_b32 v162, v159, v161
	v_xor_b32_e32 v160, 32, v158
	v_cmp_lt_i32_e32 vcc, v160, v176
	s_waitcnt lgkmcnt(0)
	v_add_f32_e32 v161, v161, v162
	v_cndmask_b32_e32 v160, v158, v160, vcc
	v_lshlrev_b32_e32 v160, 2, v160
	ds_bpermute_b32 v162, v160, v161
	s_and_saveexec_b64 s[20:21], s[2:3]
	s_cbranch_execz .LBB0_1201
	v_lshlrev_b64 v[148:149], 6, v[148:149]
	v_lshl_add_u64 v[148:149], s[82:83], 0, v[148:149]
	v_lshl_add_u64 v[148:149], s[0:1], 2, v[148:149]
	s_lshl_b32 s14, s48, 2
	v_lshl_add_u64 v[148:149], v[148:149], 0, s[14:15]
	s_waitcnt lgkmcnt(0)
	v_add_f32_e32 v161, v161, v162
	global_store_dword v[148:149], v161, off
; __device__ __forceinline__ unsigned swap8(unsigned v) { return (unsigned)__builtin_amdgcn_update_dpp(0, (int)v, 0x128  , 0xF, 0xF, false); }
; __device__ __forceinline__ void wide_store(bf16_t* O, int ldc, int rowg  , int col0  , int fr, u32x4 w0, u32x4 w1) {
;     const bool lo = fr < 8;
;     u32x4 snd = lo ? w1 : w0, rcv;
;     rcv.x = swap8(snd.x); rcv.y = swap8(snd.y); rcv.z = swap8(snd.z); rcv.w = swap8(snd.w);
;     const u32x4 first = lo ? w0 : rcv, second = lo ? rcv : w1;
;     bf16_t* p = O + (size_t)(rowg + (fr & 7)) * ldc + col0 + (lo ? 0 : 32);
;     __builtin_nontemporal_store(first, (u32x4*)p); __builtin_nontemporal_store(second, (u32x4*)(p + (size_t)8 * ldc));
; }
;     __device__ __forceinline__ void operator()(const f32x4 (&acc)[2][2][4][2], const Unit& u, int wr, int wc, int fr, int fq) const {
;     ...
;             for (int m = 0; m < 4; ++m) { const int rowg = u.pm * BM + ai * HALF + wr * 64 + m * 16, row = rowg + fr; const size_t off = (size_t)row * 1024 + col0;
;                 u32x4 w[2]; float ss = 0.f;
; #pragma unroll
;                 for (int bj = 0; bj < 2; ++bj) { f32x4 b0, b1;
;                     if (BASE_F32) { const float* bp = (const float*)base + off + 32 * bj; b0 = *(const f32x4*)bp; b1 = *(const f32x4*)(bp + 4); }
;                     else { const u32x4 bb = *(const u32x4*)((const bf16_t*)base + off + 32 * bj);
;                         b0 = (f32x4){__uint_as_float(bb.x << 16), __uint_as_float(bb.x & 0xffff0000u), __uint_as_float(bb.y << 16), __uint_as_float(bb.y & 0xffff0000u)};
;                         b1 = (f32x4){__uint_as_float(bb.z << 16), __uint_as_float(bb.z & 0xffff0000u), __uint_as_float(bb.w << 16), __uint_as_float(bb.w & 0xffff0000u)}; }
;                     const f32x4 o0 = b0 + acc[ai][bj][m][0], o1 = b1 + acc[ai][bj][m][1];
;                     ss += ((o0[0] * o0[0] + o0[1] * o0[1]) + (o0[2] * o0[2] + o0[3] * o0[3])) + ((o1[0] * o1[0] + o1[1] * o1[1]) + (o1[2] * o1[2] + o1[3] * o1[3]));
;                     w[bj].x = cvt_pk_bf16(o0[0], o0[1]); w[bj].y = cvt_pk_bf16(o0[2], o0[3]); w[bj].z = cvt_pk_bf16(o1[0], o1[1]); w[bj].w = cvt_pk_bf16(o1[2], o1[3]); }
;                 ss += __shfl_xor(ss, 16); ss += __shfl_xor(ss, 32); if (fq == 0) slots[(size_t)row * 16 + u.pn * 4 + wc] = ss;
;                 wide_store(xb, 1024, rowg, col0, fr, w[0], w[1]);
.LBB0_1201:
	s_or_b64 exec, exec, s[20:21]
	v_cvt_pk_bf16_f32 v120, v120, v121
	v_cvt_pk_bf16_f32 v112, v112, v113
	v_cvt_pk_bf16_f32 v124, v124, v125
	v_cvt_pk_bf16_f32 v125, v126, v127
	v_cvt_pk_bf16_f32 v121, v122, v123
	v_cvt_pk_bf16_f32 v118, v118, v119
	v_cvt_pk_bf16_f32 v113, v114, v115
	v_cndmask_b32_e64 v115, v120, v112, s[4:5]
	v_mov_b32_e32 v126, v137
	v_cvt_pk_bf16_f32 v122, v116, v117
	v_cndmask_b32_e64 v114, v121, v113, s[4:5]
	v_cndmask_b32_e64 v116, v125, v118, s[4:5]
	v_mov_b32_e32 v119, v137
	v_mov_b32_dpp v126, v115 row_ror:8 row_mask:0xf bank_mask:0xf
	v_mov_b32_e32 v127, v137
	v_cndmask_b32_e64 v117, v124, v122, s[4:5]
	v_mov_b32_e32 v123, v137
	v_mov_b32_dpp v119, v116 row_ror:8 row_mask:0xf bank_mask:0xf
	v_mov_b32_dpp v127, v114 row_ror:8 row_mask:0xf bank_mask:0xf
	v_cndmask_b32_e64 v116, v126, v120, s[4:5]
	v_cndmask_b32_e64 v120, v112, v126, s[4:5]
	v_or_b32_e32 v112, s22, v154
	v_mov_b32_dpp v123, v117 row_ror:8 row_mask:0xf bank_mask:0xf
	v_cndmask_b32_e64 v117, v127, v121, s[4:5]
	v_cndmask_b32_e64 v121, v113, v127, s[4:5]
	v_ashrrev_i32_e32 v113, 31, v112
	v_lshlrev_b64 v[112:113], 11, v[112:113]
	v_cndmask_b32_e64 v115, v119, v125, s[4:5]
	v_cndmask_b32_e64 v114, v123, v124, s[4:5]
	v_cndmask_b32_e64 v119, v118, v119, s[4:5]
	v_cndmask_b32_e64 v118, v122, v123, s[4:5]
	v_lshl_add_u64 v[122:123], s[26:27], 0, v[112:113]
	v_lshlrev_b64 v[112:113], 1, v[146:147]
	v_lshl_add_u64 v[122:123], v[122:123], 0, v[112:113]
	v_lshl_add_u64 v[122:123], v[122:123], 0, v[136:137]
	s_cmp_lg_u64 s[36:37], 0
	s_cbranch_scc0 .LBB0_1199
	s_barrier
.LBB0_1199:
	global_store_dwordx4 v[122:123], v[114:117], off nt
	s_or_b32 s23, s22, 16
	s_nop 0
	v_add_co_u32_e32 v114, vcc, s47, v122
	s_nop 1
	v_addc_co_u32_e32 v115, vcc, 0, v123, vcc
	global_store_dwordx4 v[114:115], v[118:121], off nt
	v_or_b32_e32 v114, s23, v150
	v_ashrrev_i32_e32 v115, 31, v114
	v_lshlrev_b64 v[116:117], 11, v[114:115]
	v_lshl_add_u64 v[116:117], s[26:27], 0, v[116:117]
	v_lshl_add_u64 v[120:121], v[116:117], 0, v[112:113]
	global_load_dwordx4 v[116:119], v[120:121], off
	s_nop 0
	global_load_dwordx4 v[120:123], v[120:121], off offset:64
	s_waitcnt vmcnt(1)
	v_lshlrev_b32_e32 v124, 16, v116
	v_and_b32_e32 v125, 0xffff0000, v116
	v_lshlrev_b32_e32 v116, 16, v117
	v_and_b32_e32 v117, 0xffff0000, v117
	v_lshlrev_b32_e32 v126, 16, v118
	v_and_b32_e32 v127, 0xffff0000, v118
	v_lshlrev_b32_e32 v118, 16, v119
	v_and_b32_e32 v119, 0xffff0000, v119
	s_waitcnt vmcnt(0)
	v_lshlrev_b32_e32 v148, 16, v120
	v_and_b32_e32 v149, 0xffff0000, v120
	v_lshlrev_b32_e32 v120, 16, v121
	v_and_b32_e32 v121, 0xffff0000, v121
	s_waitcnt lgkmcnt(0)
	v_lshlrev_b32_e32 v162, 16, v122
	v_and_b32_e32 v163, 0xffff0000, v122
	v_lshlrev_b32_e32 v122, 16, v123
	v_and_b32_e32 v123, 0xffff0000, v123
	v_pk_add_f32 v[110:111], v[110:111], v[116:117]
	v_pk_add_f32 v[108:109], v[108:109], v[124:125]
	v_pk_add_f32 v[106:107], v[106:107], v[118:119]
	v_pk_add_f32 v[104:105], v[104:105], v[126:127]
	v_pk_add_f32 v[102:103], v[102:103], v[120:121]
	v_pk_add_f32 v[100:101], v[100:101], v[148:149]
	v_pk_add_f32 v[98:99], v[98:99], v[122:123]
	v_pk_add_f32 v[96:97], v[96:97], v[162:163]
	v_mul_f32_e32 v116, v109, v109
	v_mul_f32_e32 v117, v111, v111
	v_mul_f32_e32 v118, v105, v105
	v_mul_f32_e32 v119, v107, v107
	v_mul_f32_e32 v120, v101, v101
	v_mul_f32_e32 v121, v103, v103
	v_mul_f32_e32 v122, v97, v97
	v_mul_f32_e32 v123, v99, v99
	v_fmac_f32_e32 v116, v108, v108
	v_fmac_f32_e32 v117, v110, v110
	v_fmac_f32_e32 v118, v104, v104
	v_fmac_f32_e32 v119, v106, v106
	v_fmac_f32_e32 v120, v100, v100
	v_fmac_f32_e32 v121, v102, v102
	v_fmac_f32_e32 v122, v96, v96
	v_fmac_f32_e32 v123, v98, v98
	v_add_f32_e32 v116, v116, v117
	v_add_f32_e32 v117, v118, v119
	v_add_f32_e32 v118, v120, v121
	v_add_f32_e32 v119, v122, v123
	v_add_f32_e32 v116, v116, v117
	v_add_f32_e32 v117, v118, v119
	v_add_f32_e32 v116, v116, v117
	ds_bpermute_b32 v117, v159, v116
	s_waitcnt lgkmcnt(0)
	v_add_f32_e32 v116, v116, v117
	ds_bpermute_b32 v117, v160, v116
	s_and_saveexec_b64 s[20:21], s[2:3]
	s_cbranch_execz .LBB0_1203
	v_lshlrev_b64 v[114:115], 6, v[114:115]
	v_lshl_add_u64 v[114:115], s[82:83], 0, v[114:115]
	v_lshl_add_u64 v[114:115], s[0:1], 2, v[114:115]
	s_lshl_b32 s14, s48, 2
	v_lshl_add_u64 v[114:115], v[114:115], 0, s[14:15]
	s_waitcnt lgkmcnt(0)
	v_add_f32_e32 v116, v116, v117
	global_store_dword v[114:115], v116, off
